# K-loop LDS read bases precomputed per tile in spare VGPRs v241/v242: the load segments now issue no VALU at all; otherwise the lean-compute version
# speedup vs baseline: 1.0195x; 1.0041x over previous
; #define PG8_STAGE(bufoff, gbase, voff) do { _Pragma("unroll") for (int _i = 0; _i < 2; ++_i) \
;         __builtin_amdgcn_global_load_lds((const unsigned*)((const char*)(gbase) + (voff)[_i]), (PG8_LAS unsigned*)(lds + (bufoff) + ldsw + _i * 8192), 16, 0, 0); } while (0)
; #define PG8_LDA(dst, b, h) do { _Pragma("unroll") for (int m = 0; m < 4; ++m) _Pragma("unroll") for (int k = 0; k < 2; ++k) dst[m][k] = *(const PG8_LAS bf16x8*)(lds + PG8_SA(b, h) + aoff + m * 2048 + k * 1024); } while (0)
; #define PG8_LDB(dst, b, h) do { _Pragma("unroll") for (int n = 0; n < 2; ++n) _Pragma("unroll") for (int k = 0; k < 2; ++k) dst[n][k] = *(const PG8_LAS bf16x8*)(lds + PG8_SB(b, h) + boff + n * 2048 + k * 1024); } while (0)
; #define PG8_MMA(ai, bj, At, Bt) do { __builtin_amdgcn_s_setprio(1); _Pragma("unroll") for (int m = 0; m < 4; ++m) _Pragma("unroll") for (int n = 0; n < 2; ++n) _Pragma("unroll") for (int k = 0; k < 2; ++k) \
;         acc[ai][bj][m][n] = __builtin_amdgcn_mfma_f32_16x16x32_bf16(Bt[n][k], At[m][k], acc[ai][bj][m][n], 0, 0, 0); __builtin_amdgcn_s_setprio(0); } while (0)
; #define PG8_WAIT_V(n) asm volatile("s_waitcnt vmcnt(" #n ")" ::: "memory")
; #define PG8_WAIT_L(n) asm volatile("s_waitcnt lgkmcnt(" #n ")" ::: "memory")
; #define PG8_BAR __builtin_amdgcn_s_barrier()
; #define PG8_SCHED __builtin_amdgcn_sched_barrier(0)
; template <class Epi, class Sched, bool ALIGN_EPI = false, bool SP2 = false>
; __device__ __forceinline__ void gemm_phase(PG8_LAS unsigned char* lds, const Gemm g, const Sched& S, const Epi& E) {
;     ...
;             PG8_LDB(B0, 0, 0); PG8_LDB(B1, 0, 1); PG8_SCHED; PG8_LDA(At, 0, 0); PG8_STAGE(PG8_SA(1, 1), a1 + hstepA, voffA);
;             PG8_WAIT_V(8); PG8_WAIT_L(0); PG8_BAR; PG8_MMA(0, 0, At, B0); PG8_MMA(0, 1, At, B1); PG8_BAR; PG8_SCHED;
;     ...
; #pragma unroll
;         for (int a = 0; a < 2; ++a)
; #pragma unroll
;             for (int b = 0; b < 2; ++b)
; #pragma unroll
;                 for (int m = 0; m < 4; ++m)
; #pragma unroll
;                     for (int n = 0; n < 2; ++n) acc[a][b][m][n] = (f32x4){0.f, 0.f, 0.f, 0.f};
;         cur = nxt; cA = nA; cB = nB; ++ui;
.LBB0_310:
	s_ashr_i32 s61, s60, 31
	s_lshl_b64 s[62:63], s[60:61], 20
	v_readlane_b32 s64, v240, 26
	v_readlane_b32 s65, v240, 27
	s_add_u32 s62, s64, s62
	s_addc_u32 s63, s65, s63
	s_and_b64 s[64:65], s[4:5], exec
	s_cselect_b32 s20, s63, s7
	s_cselect_b32 s33, s62, s6
	s_ashr_i32 s55, s54, 31
	s_lshl_b64 s[64:65], s[54:55], 20
	v_readlane_b32 s76, v240, 3
	v_readlane_b32 s77, v240, 4
	s_add_u32 s64, s76, s64
	s_addc_u32 s65, s77, s65
	s_and_b64 s[70:71], s[4:5], exec
	s_cselect_b32 s55, s65, s69
	s_cselect_b32 s61, s64, s68
	s_add_u32 s6, s6, 0x80080
	s_addc_u32 s7, s7, 0
	v_readlane_b32 s78, v240, 5
	s_add_u32 s76, s68, 0x100
	v_mov_b64_e32 v[0:1], 0
	s_addc_u32 s77, s69, 0
	s_mov_b32 s78, -2
	v_mov_b64_e32 v[2:3], 0
	v_mov_b64_e32 v[4:5], 0
	v_mov_b64_e32 v[6:7], 0
	v_mov_b64_e32 v[16:17], 0
	v_mov_b64_e32 v[18:19], 0
	v_mov_b64_e32 v[20:21], 0
	v_mov_b64_e32 v[22:23], 0
	v_mov_b64_e32 v[32:33], 0
	v_mov_b64_e32 v[34:35], 0
	v_mov_b64_e32 v[36:37], 0
	v_mov_b64_e32 v[38:39], 0
	v_mov_b64_e32 v[48:49], 0
	v_mov_b64_e32 v[50:51], 0
	v_mov_b64_e32 v[52:53], 0
	v_mov_b64_e32 v[54:55], 0
	v_mov_b64_e32 v[8:9], 0
	v_mov_b64_e32 v[10:11], 0
	v_mov_b64_e32 v[12:13], 0
	v_mov_b64_e32 v[14:15], 0
	v_mov_b64_e32 v[24:25], 0
	v_mov_b64_e32 v[26:27], 0
	v_mov_b64_e32 v[28:29], 0
	v_mov_b64_e32 v[30:31], 0
	v_mov_b64_e32 v[40:41], 0
	v_mov_b64_e32 v[42:43], 0
	v_mov_b64_e32 v[44:45], 0
	v_mov_b64_e32 v[46:47], 0
	v_mov_b64_e32 v[56:57], 0
	v_mov_b64_e32 v[58:59], 0
	v_mov_b64_e32 v[60:61], 0
	v_mov_b64_e32 v[62:63], 0
	v_mov_b64_e32 v[64:65], 0
	v_mov_b64_e32 v[66:67], 0
	v_mov_b64_e32 v[68:69], 0
	v_mov_b64_e32 v[70:71], 0
	v_mov_b64_e32 v[80:81], 0
	v_mov_b64_e32 v[82:83], 0
	v_mov_b64_e32 v[84:85], 0
	v_mov_b64_e32 v[86:87], 0
	v_mov_b64_e32 v[96:97], 0
	v_mov_b64_e32 v[98:99], 0
	v_mov_b64_e32 v[100:101], 0
	v_mov_b64_e32 v[102:103], 0
	v_mov_b64_e32 v[112:113], 0
	v_mov_b64_e32 v[114:115], 0
	v_mov_b64_e32 v[116:117], 0
	v_mov_b64_e32 v[118:119], 0
	v_mov_b64_e32 v[72:73], 0
	v_mov_b64_e32 v[74:75], 0
	v_mov_b64_e32 v[76:77], 0
	v_mov_b64_e32 v[78:79], 0
	v_mov_b64_e32 v[88:89], 0
	v_mov_b64_e32 v[90:91], 0
	v_mov_b64_e32 v[92:93], 0
	v_mov_b64_e32 v[94:95], 0
	v_mov_b64_e32 v[104:105], 0
	v_mov_b64_e32 v[106:107], 0
	v_mov_b64_e32 v[108:109], 0
	v_mov_b64_e32 v[110:111], 0
	v_mov_b64_e32 v[120:121], 0
	v_mov_b64_e32 v[122:123], 0
	v_mov_b64_e32 v[124:125], 0
	v_mov_b64_e32 v[126:127], 0
	v_readlane_b32 s79, v240, 6
	v_add_u32_e32 v241, 0x18000, v174
	v_add_u32_e32 v242, 0x1c000, v174
.LBB0_311:
	ds_read_b128 v[148:151], v176
	ds_read_b128 v[152:155], v176 offset:1024
	ds_read_b128 v[156:159], v176 offset:2048
	ds_read_b128 v[180:183], v176 offset:3072
	ds_read_b128 v[184:187], v177
	ds_read_b128 v[188:191], v177 offset:1024
	ds_read_b128 v[192:195], v177 offset:2048
	ds_read_b128 v[196:199], v177 offset:3072
	s_add_u32 s68, s6, 0xfff80080
	s_addc_u32 s69, s7, -1
	s_cmp_eq_u32 s78, 28
	s_cselect_b32 s71, s20, s69
	s_cselect_b32 s70, s33, s68
	s_cselect_b32 s69, s55, s77
	s_cselect_b32 s68, s61, s76
	s_add_i32 m0, s9, 0xc000
	ds_read_b128 v[200:203], v178
	ds_read_b128 v[204:207], v178 offset:1024
	ds_read_b128 v[208:211], v178 offset:2048
	ds_read_b128 v[212:215], v178 offset:3072
	ds_read_b128 v[216:219], v178 offset:4096
	ds_read_b128 v[220:223], v178 offset:5120
	ds_read_b128 v[224:227], v178 offset:6144
	ds_read_b128 v[228:231], v178 offset:7168
	global_load_lds_dwordx4 v140, s[6:7]
	s_add_i32 m0, s9, 0xe000
	s_nop 0
	global_load_lds_dwordx4 v142, s[6:7]
	s_waitcnt vmcnt(8)
	s_waitcnt lgkmcnt(0)
	s_setprio 0
	s_barrier
	v_mfma_f32_16x16x32_bf16 v[124:127], v[148:151], v[200:203], v[124:127]
	v_mfma_f32_16x16x32_bf16 v[120:123], v[156:159], v[200:203], v[120:123]
	v_mfma_f32_16x16x32_bf16 v[108:111], v[148:151], v[208:211], v[108:111]
	v_mfma_f32_16x16x32_bf16 v[104:107], v[156:159], v[208:211], v[104:107]
	v_mfma_f32_16x16x32_bf16 v[92:95], v[148:151], v[216:219], v[92:95]
	v_mfma_f32_16x16x32_bf16 v[88:91], v[156:159], v[216:219], v[88:91]
	v_mfma_f32_16x16x32_bf16 v[76:79], v[148:151], v[224:227], v[76:79]
	v_mfma_f32_16x16x32_bf16 v[72:75], v[156:159], v[224:227], v[72:75]
	v_mfma_f32_16x16x32_bf16 v[124:127], v[152:155], v[204:207], v[124:127]
	v_mfma_f32_16x16x32_bf16 v[120:123], v[180:183], v[204:207], v[120:123]
	v_mfma_f32_16x16x32_bf16 v[108:111], v[152:155], v[212:215], v[108:111]
	v_mfma_f32_16x16x32_bf16 v[104:107], v[180:183], v[212:215], v[104:107]
	v_mfma_f32_16x16x32_bf16 v[92:95], v[152:155], v[220:223], v[92:95]
	v_mfma_f32_16x16x32_bf16 v[88:91], v[180:183], v[220:223], v[88:91]
	v_mfma_f32_16x16x32_bf16 v[76:79], v[152:155], v[228:231], v[76:79]
	v_mfma_f32_16x16x32_bf16 v[72:75], v[180:183], v[228:231], v[72:75]
	v_mfma_f32_16x16x32_bf16 v[116:119], v[184:187], v[200:203], v[116:119]
	v_mfma_f32_16x16x32_bf16 v[112:115], v[192:195], v[200:203], v[112:115]
	v_mfma_f32_16x16x32_bf16 v[100:103], v[184:187], v[208:211], v[100:103]
	v_mfma_f32_16x16x32_bf16 v[96:99], v[192:195], v[208:211], v[96:99]
	v_mfma_f32_16x16x32_bf16 v[84:87], v[184:187], v[216:219], v[84:87]
	v_mfma_f32_16x16x32_bf16 v[80:83], v[192:195], v[216:219], v[80:83]
	v_mfma_f32_16x16x32_bf16 v[68:71], v[184:187], v[224:227], v[68:71]
	v_mfma_f32_16x16x32_bf16 v[64:67], v[192:195], v[224:227], v[64:67]
	v_mfma_f32_16x16x32_bf16 v[116:119], v[188:191], v[204:207], v[116:119]
	v_mfma_f32_16x16x32_bf16 v[112:115], v[196:199], v[204:207], v[112:115]
	v_mfma_f32_16x16x32_bf16 v[100:103], v[188:191], v[212:215], v[100:103]
	v_mfma_f32_16x16x32_bf16 v[96:99], v[196:199], v[212:215], v[96:99]
	v_mfma_f32_16x16x32_bf16 v[84:87], v[188:191], v[220:223], v[84:87]
	v_mfma_f32_16x16x32_bf16 v[80:83], v[196:199], v[220:223], v[80:83]
	v_mfma_f32_16x16x32_bf16 v[68:71], v[188:191], v[228:231], v[68:71]
	v_mfma_f32_16x16x32_bf16 v[64:67], v[196:199], v[228:231], v[64:67]
	s_barrier
; #define PG8_STAGE(bufoff, gbase, voff) do { _Pragma("unroll") for (int _i = 0; _i < 2; ++_i) \
;         __builtin_amdgcn_global_load_lds((const unsigned*)((const char*)(gbase) + (voff)[_i]), (PG8_LAS unsigned*)(lds + (bufoff) + ldsw + _i * 8192), 16, 0, 0); } while (0)
; #define PG8_LDA(dst, b, h) do { _Pragma("unroll") for (int m = 0; m < 4; ++m) _Pragma("unroll") for (int k = 0; k < 2; ++k) dst[m][k] = *(const PG8_LAS bf16x8*)(lds + PG8_SA(b, h) + aoff + m * 2048 + k * 1024); } while (0)
; #define PG8_LDB(dst, b, h) do { _Pragma("unroll") for (int n = 0; n < 2; ++n) _Pragma("unroll") for (int k = 0; k < 2; ++k) dst[n][k] = *(const PG8_LAS bf16x8*)(lds + PG8_SB(b, h) + boff + n * 2048 + k * 1024); } while (0)
; #define PG8_MMA(ai, bj, At, Bt) do { __builtin_amdgcn_s_setprio(1); _Pragma("unroll") for (int m = 0; m < 4; ++m) _Pragma("unroll") for (int n = 0; n < 2; ++n) _Pragma("unroll") for (int k = 0; k < 2; ++k) \
;         acc[ai][bj][m][n] = __builtin_amdgcn_mfma_f32_16x16x32_bf16(Bt[n][k], At[m][k], acc[ai][bj][m][n], 0, 0, 0); __builtin_amdgcn_s_setprio(0); } while (0)
; #define PG8_WAIT_V(n) asm volatile("s_waitcnt vmcnt(" #n ")" ::: "memory")
; #define PG8_WAIT_L(n) asm volatile("s_waitcnt lgkmcnt(" #n ")" ::: "memory")
; #define PG8_BAR __builtin_amdgcn_s_barrier()
; #define PG8_SCHED __builtin_amdgcn_sched_barrier(0)
; template <class Epi, class Sched, bool ALIGN_EPI = false, bool SP2 = false>
; __device__ __forceinline__ void gemm_phase(PG8_LAS unsigned char* lds, const Gemm g, const Sched& S, const Epi& E) {
;     ...
;             PG8_LDA(At, 0, 1); PG8_STAGE(PG8_SB(0, 0), b2, voffB); PG8_STAGE(PG8_SB(0, 1), b2 + hstepB, voffB); PG8_STAGE(PG8_SA(0, 0), a2, voffA);
;             PG8_WAIT_V(8); PG8_WAIT_L(0); PG8_BAR; PG8_MMA(1, 0, At, B0); PG8_MMA(1, 1, At, B1); PG8_BAR; PG8_SCHED;
;             PG8_LDB(B0, 1, 0); PG8_LDB(B1, 1, 1); PG8_SCHED; PG8_LDA(At, 1, 0); PG8_STAGE(PG8_SA(0, 1), a2 + hstepA, voffA);
	s_setprio 1
	s_add_u32 s98, s68, s46
	s_addc_u32 s99, s69, s47
	s_add_u32 s100, s70, s46
	s_addc_u32 s101, s71, s47
	s_add_i32 s79, s72, s28
	s_mov_b32 m0, s79
	ds_read_b128 v[200:203], v178 offset:16384
	ds_read_b128 v[204:207], v178 offset:17408
	ds_read_b128 v[208:211], v178 offset:18432
	ds_read_b128 v[212:215], v178 offset:19456
	ds_read_b128 v[216:219], v178 offset:20480
	ds_read_b128 v[220:223], v178 offset:21504
	ds_read_b128 v[224:227], v178 offset:22528
	ds_read_b128 v[228:231], v178 offset:23552
	global_load_lds_dwordx4 v130, s[68:69]
	s_add_i32 m0, s79, 0x2000
	s_add_u32 s80, s68, 0x80000
	s_addc_u32 s81, s69, 0
	s_add_i32 s79, s73, s28
	global_load_lds_dwordx4 v134, s[68:69]
	s_mov_b32 m0, s79
	s_nop 0
	global_load_lds_dwordx4 v130, s[80:81]
	s_add_i32 m0, s79, 0x2000
	s_nop 0
	global_load_lds_dwordx4 v134, s[80:81]
	s_mov_b32 m0, s9
	s_nop 0
	global_load_lds_dwordx4 v128, s[70:71]
	s_mov_b32 m0, s19
	s_nop 0
	global_load_lds_dwordx4 v132, s[70:71]
	s_waitcnt vmcnt(8)
	s_waitcnt lgkmcnt(0)
	s_setprio 0
	s_barrier
	v_mfma_f32_16x16x32_bf16 v[60:63], v[148:151], v[200:203], v[60:63]
	v_mfma_f32_16x16x32_bf16 v[56:59], v[156:159], v[200:203], v[56:59]
	v_mfma_f32_16x16x32_bf16 v[44:47], v[148:151], v[208:211], v[44:47]
	v_mfma_f32_16x16x32_bf16 v[40:43], v[156:159], v[208:211], v[40:43]
	v_mfma_f32_16x16x32_bf16 v[28:31], v[148:151], v[216:219], v[28:31]
	v_mfma_f32_16x16x32_bf16 v[24:27], v[156:159], v[216:219], v[24:27]
	v_mfma_f32_16x16x32_bf16 v[12:15], v[148:151], v[224:227], v[12:15]
	v_mfma_f32_16x16x32_bf16 v[8:11], v[156:159], v[224:227], v[8:11]
	v_mfma_f32_16x16x32_bf16 v[60:63], v[152:155], v[204:207], v[60:63]
	v_mfma_f32_16x16x32_bf16 v[56:59], v[180:183], v[204:207], v[56:59]
	v_mfma_f32_16x16x32_bf16 v[44:47], v[152:155], v[212:215], v[44:47]
	v_mfma_f32_16x16x32_bf16 v[40:43], v[180:183], v[212:215], v[40:43]
	v_mfma_f32_16x16x32_bf16 v[28:31], v[152:155], v[220:223], v[28:31]
	v_mfma_f32_16x16x32_bf16 v[24:27], v[180:183], v[220:223], v[24:27]
	v_mfma_f32_16x16x32_bf16 v[12:15], v[152:155], v[228:231], v[12:15]
	v_mfma_f32_16x16x32_bf16 v[8:11], v[180:183], v[228:231], v[8:11]
	v_mfma_f32_16x16x32_bf16 v[52:55], v[184:187], v[200:203], v[52:55]
	v_mfma_f32_16x16x32_bf16 v[48:51], v[192:195], v[200:203], v[48:51]
	v_mfma_f32_16x16x32_bf16 v[36:39], v[184:187], v[208:211], v[36:39]
	v_mfma_f32_16x16x32_bf16 v[32:35], v[192:195], v[208:211], v[32:35]
	v_mfma_f32_16x16x32_bf16 v[20:23], v[184:187], v[216:219], v[20:23]
	v_mfma_f32_16x16x32_bf16 v[16:19], v[192:195], v[216:219], v[16:19]
	v_mfma_f32_16x16x32_bf16 v[4:7], v[184:187], v[224:227], v[4:7]
	v_mfma_f32_16x16x32_bf16 v[0:3], v[192:195], v[224:227], v[0:3]
	v_mfma_f32_16x16x32_bf16 v[52:55], v[188:191], v[204:207], v[52:55]
	v_mfma_f32_16x16x32_bf16 v[48:51], v[196:199], v[204:207], v[48:51]
	v_mfma_f32_16x16x32_bf16 v[36:39], v[188:191], v[212:215], v[36:39]
	v_mfma_f32_16x16x32_bf16 v[32:35], v[196:199], v[212:215], v[32:35]
	v_mfma_f32_16x16x32_bf16 v[20:23], v[188:191], v[220:223], v[20:23]
	v_mfma_f32_16x16x32_bf16 v[16:19], v[196:199], v[220:223], v[16:19]
	v_mfma_f32_16x16x32_bf16 v[4:7], v[188:191], v[228:231], v[4:7]
	v_mfma_f32_16x16x32_bf16 v[0:3], v[196:199], v[228:231], v[0:3]
	s_barrier
	s_setprio 1
	s_add_i32 s79, 0, 0x18000
	s_add_i32 s80, 0, 0x1c000
	ds_read_b128 v[148:151], v241
	ds_read_b128 v[152:155], v241 offset:1024
	ds_read_b128 v[156:159], v241 offset:2048
	ds_read_b128 v[180:183], v241 offset:3072
	ds_read_b128 v[184:187], v242
	ds_read_b128 v[188:191], v242 offset:1024
	ds_read_b128 v[192:195], v242 offset:2048
	ds_read_b128 v[196:199], v242 offset:3072
	s_add_u32 s70, s70, 0x80000
	s_addc_u32 s71, s71, 0
	s_mov_b32 m0, s29
	ds_read_b128 v[200:203], v178 offset:32768
	ds_read_b128 v[204:207], v178 offset:33792
	ds_read_b128 v[208:211], v178 offset:34816
	ds_read_b128 v[212:215], v178 offset:35840
	ds_read_b128 v[216:219], v178 offset:36864
	ds_read_b128 v[220:223], v178 offset:37888
	ds_read_b128 v[224:227], v178 offset:38912
	ds_read_b128 v[228:231], v178 offset:39936
	global_load_lds_dwordx4 v128, s[70:71]
	s_mov_b32 m0, s30
	s_nop 0
	global_load_lds_dwordx4 v132, s[70:71]
	s_waitcnt vmcnt(8)
	s_waitcnt lgkmcnt(0)
	s_setprio 0
	s_barrier
; #define PG8_STAGE(bufoff, gbase, voff) do { _Pragma("unroll") for (int _i = 0; _i < 2; ++_i) \
;         __builtin_amdgcn_global_load_lds((const unsigned*)((const char*)(gbase) + (voff)[_i]), (PG8_LAS unsigned*)(lds + (bufoff) + ldsw + _i * 8192), 16, 0, 0); } while (0)
; #define PG8_LDA(dst, b, h) do { _Pragma("unroll") for (int m = 0; m < 4; ++m) _Pragma("unroll") for (int k = 0; k < 2; ++k) dst[m][k] = *(const PG8_LAS bf16x8*)(lds + PG8_SA(b, h) + aoff + m * 2048 + k * 1024); } while (0)
; #define PG8_MMA(ai, bj, At, Bt) do { __builtin_amdgcn_s_setprio(1); _Pragma("unroll") for (int m = 0; m < 4; ++m) _Pragma("unroll") for (int n = 0; n < 2; ++n) _Pragma("unroll") for (int k = 0; k < 2; ++k) \
;         acc[ai][bj][m][n] = __builtin_amdgcn_mfma_f32_16x16x32_bf16(Bt[n][k], At[m][k], acc[ai][bj][m][n], 0, 0, 0); __builtin_amdgcn_s_setprio(0); } while (0)
; #define PG8_WAIT_V(n) asm volatile("s_waitcnt vmcnt(" #n ")" ::: "memory")
; #define PG8_WAIT_L(n) asm volatile("s_waitcnt lgkmcnt(" #n ")" ::: "memory")
; #define PG8_BAR __builtin_amdgcn_s_barrier()
; #define PG8_SCHED __builtin_amdgcn_sched_barrier(0)
; template <class Epi, class Sched, bool ALIGN_EPI = false, bool SP2 = false>
; __device__ __forceinline__ void gemm_phase(PG8_LAS unsigned char* lds, const Gemm g, const Sched& S, const Epi& E) {
;     ...
;             PG8_WAIT_V(8); PG8_WAIT_L(0); PG8_BAR; PG8_MMA(0, 0, At, B0); PG8_MMA(0, 1, At, B1); PG8_BAR; PG8_SCHED;
;             PG8_LDA(At, 1, 1); PG8_STAGE(PG8_SB(1, 0), b3, voffB); PG8_STAGE(PG8_SB(1, 1), b3 + hstepB, voffB); PG8_STAGE(PG8_SA(1, 0), a3, voffA);
;             PG8_WAIT_V(8); PG8_WAIT_L(0); PG8_BAR; PG8_MMA(1, 0, At, B0); PG8_MMA(1, 1, At, B1); PG8_BAR; PG8_SCHED;
	v_mfma_f32_16x16x32_bf16 v[124:127], v[148:151], v[200:203], v[124:127]
	v_mfma_f32_16x16x32_bf16 v[120:123], v[156:159], v[200:203], v[120:123]
	v_mfma_f32_16x16x32_bf16 v[108:111], v[148:151], v[208:211], v[108:111]
	v_mfma_f32_16x16x32_bf16 v[104:107], v[156:159], v[208:211], v[104:107]
	v_mfma_f32_16x16x32_bf16 v[92:95], v[148:151], v[216:219], v[92:95]
	v_mfma_f32_16x16x32_bf16 v[88:91], v[156:159], v[216:219], v[88:91]
	v_mfma_f32_16x16x32_bf16 v[76:79], v[148:151], v[224:227], v[76:79]
	v_mfma_f32_16x16x32_bf16 v[72:75], v[156:159], v[224:227], v[72:75]
	v_mfma_f32_16x16x32_bf16 v[124:127], v[152:155], v[204:207], v[124:127]
	v_mfma_f32_16x16x32_bf16 v[120:123], v[180:183], v[204:207], v[120:123]
	v_mfma_f32_16x16x32_bf16 v[108:111], v[152:155], v[212:215], v[108:111]
	v_mfma_f32_16x16x32_bf16 v[104:107], v[180:183], v[212:215], v[104:107]
	v_mfma_f32_16x16x32_bf16 v[92:95], v[152:155], v[220:223], v[92:95]
	v_mfma_f32_16x16x32_bf16 v[88:91], v[180:183], v[220:223], v[88:91]
	v_mfma_f32_16x16x32_bf16 v[76:79], v[152:155], v[228:231], v[76:79]
	v_mfma_f32_16x16x32_bf16 v[72:75], v[180:183], v[228:231], v[72:75]
	v_mfma_f32_16x16x32_bf16 v[116:119], v[184:187], v[200:203], v[116:119]
	v_mfma_f32_16x16x32_bf16 v[112:115], v[192:195], v[200:203], v[112:115]
	v_mfma_f32_16x16x32_bf16 v[100:103], v[184:187], v[208:211], v[100:103]
	v_mfma_f32_16x16x32_bf16 v[96:99], v[192:195], v[208:211], v[96:99]
	v_mfma_f32_16x16x32_bf16 v[84:87], v[184:187], v[216:219], v[84:87]
	v_mfma_f32_16x16x32_bf16 v[80:83], v[192:195], v[216:219], v[80:83]
	v_mfma_f32_16x16x32_bf16 v[68:71], v[184:187], v[224:227], v[68:71]
	v_mfma_f32_16x16x32_bf16 v[64:67], v[192:195], v[224:227], v[64:67]
	v_mfma_f32_16x16x32_bf16 v[116:119], v[188:191], v[204:207], v[116:119]
	v_mfma_f32_16x16x32_bf16 v[112:115], v[196:199], v[204:207], v[112:115]
	v_mfma_f32_16x16x32_bf16 v[100:103], v[188:191], v[212:215], v[100:103]
	v_mfma_f32_16x16x32_bf16 v[96:99], v[196:199], v[212:215], v[96:99]
	v_mfma_f32_16x16x32_bf16 v[84:87], v[188:191], v[220:223], v[84:87]
	v_mfma_f32_16x16x32_bf16 v[80:83], v[196:199], v[220:223], v[80:83]
	v_mfma_f32_16x16x32_bf16 v[68:71], v[188:191], v[228:231], v[68:71]
	v_mfma_f32_16x16x32_bf16 v[64:67], v[196:199], v[228:231], v[64:67]
	s_barrier
	s_setprio 1
	s_add_i32 s70, s79, s28
	s_mov_b32 m0, s70
	ds_read_b128 v[200:203], v178 offset:49152
	ds_read_b128 v[204:207], v178 offset:50176
	ds_read_b128 v[208:211], v178 offset:51200
	ds_read_b128 v[212:215], v178 offset:52224
	ds_read_b128 v[216:219], v178 offset:53248
	ds_read_b128 v[220:223], v178 offset:54272
	ds_read_b128 v[224:227], v178 offset:55296
	ds_read_b128 v[228:231], v178 offset:56320
	global_load_lds_dwordx4 v130, s[98:99]
	s_add_i32 m0, s70, 0x2000
	s_add_u32 s68, s68, 0x80080
	s_addc_u32 s69, s69, 0
	s_add_i32 s70, s80, s28
	global_load_lds_dwordx4 v134, s[98:99]
	s_mov_b32 m0, s70
	s_nop 0
	global_load_lds_dwordx4 v130, s[68:69]
	s_add_i32 m0, s70, 0x2000
	s_nop 0
	global_load_lds_dwordx4 v134, s[68:69]
	s_mov_b32 m0, s34
	s_nop 0
	global_load_lds_dwordx4 v128, s[100:101]
	s_mov_b32 m0, s35
	s_nop 0
	global_load_lds_dwordx4 v132, s[100:101]
	s_waitcnt vmcnt(8)
	s_waitcnt lgkmcnt(0)
	s_setprio 0
	s_barrier
	v_mfma_f32_16x16x32_bf16 v[60:63], v[148:151], v[200:203], v[60:63]
	v_mfma_f32_16x16x32_bf16 v[56:59], v[156:159], v[200:203], v[56:59]
	v_mfma_f32_16x16x32_bf16 v[44:47], v[148:151], v[208:211], v[44:47]
	v_mfma_f32_16x16x32_bf16 v[40:43], v[156:159], v[208:211], v[40:43]
	v_mfma_f32_16x16x32_bf16 v[28:31], v[148:151], v[216:219], v[28:31]
	v_mfma_f32_16x16x32_bf16 v[24:27], v[156:159], v[216:219], v[24:27]
	v_mfma_f32_16x16x32_bf16 v[12:15], v[148:151], v[224:227], v[12:15]
	v_mfma_f32_16x16x32_bf16 v[8:11], v[156:159], v[224:227], v[8:11]
	v_mfma_f32_16x16x32_bf16 v[60:63], v[152:155], v[204:207], v[60:63]
	v_mfma_f32_16x16x32_bf16 v[56:59], v[180:183], v[204:207], v[56:59]
	v_mfma_f32_16x16x32_bf16 v[44:47], v[152:155], v[212:215], v[44:47]
	v_mfma_f32_16x16x32_bf16 v[40:43], v[180:183], v[212:215], v[40:43]
	v_mfma_f32_16x16x32_bf16 v[28:31], v[152:155], v[220:223], v[28:31]
	v_mfma_f32_16x16x32_bf16 v[24:27], v[180:183], v[220:223], v[24:27]
	v_mfma_f32_16x16x32_bf16 v[12:15], v[152:155], v[228:231], v[12:15]
	v_mfma_f32_16x16x32_bf16 v[8:11], v[180:183], v[228:231], v[8:11]
	v_mfma_f32_16x16x32_bf16 v[52:55], v[184:187], v[200:203], v[52:55]
	v_mfma_f32_16x16x32_bf16 v[48:51], v[192:195], v[200:203], v[48:51]
	v_mfma_f32_16x16x32_bf16 v[36:39], v[184:187], v[208:211], v[36:39]
	v_mfma_f32_16x16x32_bf16 v[32:35], v[192:195], v[208:211], v[32:35]
	v_mfma_f32_16x16x32_bf16 v[20:23], v[184:187], v[216:219], v[20:23]
	v_mfma_f32_16x16x32_bf16 v[16:19], v[192:195], v[216:219], v[16:19]
	v_mfma_f32_16x16x32_bf16 v[4:7], v[184:187], v[224:227], v[4:7]
	v_mfma_f32_16x16x32_bf16 v[0:3], v[192:195], v[224:227], v[0:3]
	v_mfma_f32_16x16x32_bf16 v[52:55], v[188:191], v[204:207], v[52:55]
	v_mfma_f32_16x16x32_bf16 v[48:51], v[196:199], v[204:207], v[48:51]
	v_mfma_f32_16x16x32_bf16 v[36:39], v[188:191], v[212:215], v[36:39]
	v_mfma_f32_16x16x32_bf16 v[32:35], v[196:199], v[212:215], v[32:35]
	v_mfma_f32_16x16x32_bf16 v[20:23], v[188:191], v[220:223], v[20:23]
	v_mfma_f32_16x16x32_bf16 v[16:19], v[196:199], v[220:223], v[16:19]
	v_mfma_f32_16x16x32_bf16 v[4:7], v[188:191], v[228:231], v[4:7]
	v_mfma_f32_16x16x32_bf16 v[0:3], v[196:199], v[228:231], v[0:3]
	s_barrier
	s_setprio 1
	s_add_i32 s78, s78, 2
	s_add_u32 s6, s6, 0x100
	s_addc_u32 s7, s7, 0
	s_add_u32 s76, s76, 0x100
	s_addc_u32 s77, s77, 0
	s_cmp_gt_u32 s78, 29
	s_cbranch_scc0 .LBB0_311
	s_and_b64 vcc, exec, s[48:49]
	s_cbranch_vccz .LBB0_314
	s_barrier

; #define PG8_STAGE(bufoff, gbase, voff) do { _Pragma("unroll") for (int _i = 0; _i < 2; ++_i) \
;         __builtin_amdgcn_global_load_lds((const unsigned*)((const char*)(gbase) + (voff)[_i]), (PG8_LAS unsigned*)(lds + (bufoff) + ldsw + _i * 8192), 16, 0, 0); } while (0)
; #define PG8_LDA(dst, b, h) do { _Pragma("unroll") for (int m = 0; m < 4; ++m) _Pragma("unroll") for (int k = 0; k < 2; ++k) dst[m][k] = *(const PG8_LAS bf16x8*)(lds + PG8_SA(b, h) + aoff + m * 2048 + k * 1024); } while (0)
; #define PG8_LDB(dst, b, h) do { _Pragma("unroll") for (int n = 0; n < 2; ++n) _Pragma("unroll") for (int k = 0; k < 2; ++k) dst[n][k] = *(const PG8_LAS bf16x8*)(lds + PG8_SB(b, h) + boff + n * 2048 + k * 1024); } while (0)
; #define PG8_MMA(ai, bj, At, Bt) do { __builtin_amdgcn_s_setprio(1); _Pragma("unroll") for (int m = 0; m < 4; ++m) _Pragma("unroll") for (int n = 0; n < 2; ++n) _Pragma("unroll") for (int k = 0; k < 2; ++k) \
;         acc[ai][bj][m][n] = __builtin_amdgcn_mfma_f32_16x16x32_bf16(Bt[n][k], At[m][k], acc[ai][bj][m][n], 0, 0, 0); __builtin_amdgcn_s_setprio(0); } while (0)
; #define PG8_WAIT_V(n) asm volatile("s_waitcnt vmcnt(" #n ")" ::: "memory")
; #define PG8_WAIT_L(n) asm volatile("s_waitcnt lgkmcnt(" #n ")" ::: "memory")
; #define PG8_BAR __builtin_amdgcn_s_barrier()
; #define PG8_SCHED __builtin_amdgcn_sched_barrier(0)
; template <class Epi, class Sched, bool ALIGN_EPI = false, bool SP2 = false>
; __device__ __forceinline__ void gemm_phase(PG8_LAS unsigned char* lds, const Gemm g, const Sched& S, const Epi& E) {
;     ...
;             PG8_LDB(B0, 0, 0); PG8_LDB(B1, 0, 1); PG8_SCHED; PG8_LDA(At, 0, 0); PG8_STAGE(PG8_SA(1, 1), a1 + hstepA, voffA);
;             PG8_WAIT_V(8); PG8_WAIT_L(0); PG8_BAR; PG8_MMA(0, 0, At, B0); PG8_MMA(0, 1, At, B1); PG8_BAR; PG8_SCHED;
;     ...
; #pragma unroll
;         for (int a = 0; a < 2; ++a)
; #pragma unroll
;             for (int b = 0; b < 2; ++b)
; #pragma unroll
;                 for (int m = 0; m < 4; ++m)
; #pragma unroll
;                     for (int n = 0; n < 2; ++n) acc[a][b][m][n] = (f32x4){0.f, 0.f, 0.f, 0.f};
;         cur = nxt; cA = nA; cB = nB; ++ui;
.LBB0_496:
	s_ashr_i32 s43, s42, 31
	s_lshl_b64 s[28:29], s[42:43], 20
	s_add_u32 s46, s64, s28
	s_addc_u32 s47, s65, s29
	s_and_b64 s[28:29], s[4:5], exec
	s_cselect_b32 s7, s47, s55
	s_cselect_b32 s28, s46, s54
	s_ashr_i32 s41, s40, 31
	s_lshl_b64 s[30:31], s[40:41], 20
	v_readlane_b32 s48, v240, 26
	v_readlane_b32 s49, v240, 27
	s_add_u32 s48, s48, s30
	s_addc_u32 s49, s49, s31
	s_and_b64 s[30:31], s[4:5], exec
	s_cselect_b32 s29, s49, s61
	s_cselect_b32 s30, s48, s60
	s_add_u32 s54, s54, 0x80080
	s_addc_u32 s55, s55, 0
	s_add_u32 s31, s60, 0x100
	v_mov_b64_e32 v[0:1], 0
	s_addc_u32 s33, s61, 0
	s_mov_b32 s34, -2
	v_mov_b64_e32 v[2:3], 0
	v_mov_b64_e32 v[4:5], 0
	v_mov_b64_e32 v[6:7], 0
	v_mov_b64_e32 v[16:17], 0
	v_mov_b64_e32 v[18:19], 0
	v_mov_b64_e32 v[20:21], 0
	v_mov_b64_e32 v[22:23], 0
	v_mov_b64_e32 v[32:33], 0
	v_mov_b64_e32 v[34:35], 0
	v_mov_b64_e32 v[36:37], 0
	v_mov_b64_e32 v[38:39], 0
	v_mov_b64_e32 v[48:49], 0
	v_mov_b64_e32 v[50:51], 0
	v_mov_b64_e32 v[52:53], 0
	v_mov_b64_e32 v[54:55], 0
	v_mov_b64_e32 v[8:9], 0
	v_mov_b64_e32 v[10:11], 0
	v_mov_b64_e32 v[12:13], 0
	v_mov_b64_e32 v[14:15], 0
	v_mov_b64_e32 v[24:25], 0
	v_mov_b64_e32 v[26:27], 0
	v_mov_b64_e32 v[28:29], 0
	v_mov_b64_e32 v[30:31], 0
	v_mov_b64_e32 v[40:41], 0
	v_mov_b64_e32 v[42:43], 0
	v_mov_b64_e32 v[44:45], 0
	v_mov_b64_e32 v[46:47], 0
	v_mov_b64_e32 v[56:57], 0
	v_mov_b64_e32 v[58:59], 0
	v_mov_b64_e32 v[60:61], 0
	v_mov_b64_e32 v[62:63], 0
	v_mov_b64_e32 v[64:65], 0
	v_mov_b64_e32 v[66:67], 0
	v_mov_b64_e32 v[68:69], 0
	v_mov_b64_e32 v[70:71], 0
	v_mov_b64_e32 v[80:81], 0
	v_mov_b64_e32 v[82:83], 0
	v_mov_b64_e32 v[84:85], 0
	v_mov_b64_e32 v[86:87], 0
	v_mov_b64_e32 v[96:97], 0
	v_mov_b64_e32 v[98:99], 0
	v_mov_b64_e32 v[100:101], 0
	v_mov_b64_e32 v[102:103], 0
	v_mov_b64_e32 v[112:113], 0
	v_mov_b64_e32 v[114:115], 0
	v_mov_b64_e32 v[116:117], 0
	v_mov_b64_e32 v[118:119], 0
	v_mov_b64_e32 v[72:73], 0
	v_mov_b64_e32 v[74:75], 0
	v_mov_b64_e32 v[76:77], 0
	v_mov_b64_e32 v[78:79], 0
	v_mov_b64_e32 v[88:89], 0
	v_mov_b64_e32 v[90:91], 0
	v_mov_b64_e32 v[92:93], 0
	v_mov_b64_e32 v[94:95], 0
	v_mov_b64_e32 v[104:105], 0
	v_mov_b64_e32 v[106:107], 0
	v_mov_b64_e32 v[108:109], 0
	v_mov_b64_e32 v[110:111], 0
	v_mov_b64_e32 v[120:121], 0
	v_mov_b64_e32 v[122:123], 0
	v_mov_b64_e32 v[124:125], 0
	v_mov_b64_e32 v[126:127], 0
	v_add_u32_e32 v241, 0x18000, v153
	v_add_u32_e32 v242, 0x1c000, v153
.LBB0_497:
	ds_read_b128 v[146:149], v155
	ds_read_b128 v[158:161], v155 offset:1024
	ds_read_b128 v[168:171], v155 offset:2048
	ds_read_b128 v[172:175], v155 offset:3072
	ds_read_b128 v[176:179], v156
	ds_read_b128 v[180:183], v156 offset:1024
	ds_read_b128 v[184:187], v156 offset:2048
	ds_read_b128 v[188:191], v156 offset:3072
	s_add_u32 s41, s54, 0xfff80080
	s_addc_u32 s43, s55, -1
	s_cmp_eq_u32 s34, 28
	s_cselect_b32 s63, s7, s43
	s_cselect_b32 s62, s28, s41
	s_cselect_b32 s61, s29, s33
	s_cselect_b32 s60, s30, s31
	s_add_i32 m0, s69, 0xc000
	ds_read_b128 v[192:195], v157
	ds_read_b128 v[196:199], v157 offset:1024
	ds_read_b128 v[200:203], v157 offset:2048
	ds_read_b128 v[204:207], v157 offset:3072
	ds_read_b128 v[208:211], v157 offset:4096
	ds_read_b128 v[212:215], v157 offset:5120
	ds_read_b128 v[216:219], v157 offset:6144
	ds_read_b128 v[220:223], v157 offset:7168
	global_load_lds_dwordx4 v138, s[54:55]
	s_add_i32 m0, s69, 0xe000
	s_nop 0
	global_load_lds_dwordx4 v140, s[54:55]
	s_waitcnt vmcnt(8)
	s_waitcnt lgkmcnt(0)
	s_setprio 0
	s_barrier
	v_mfma_f32_16x16x32_bf16 v[124:127], v[146:149], v[192:195], v[124:127]
	v_mfma_f32_16x16x32_bf16 v[120:123], v[168:171], v[192:195], v[120:123]
	v_mfma_f32_16x16x32_bf16 v[108:111], v[146:149], v[200:203], v[108:111]
	v_mfma_f32_16x16x32_bf16 v[104:107], v[168:171], v[200:203], v[104:107]
	v_mfma_f32_16x16x32_bf16 v[92:95], v[146:149], v[208:211], v[92:95]
	v_mfma_f32_16x16x32_bf16 v[88:91], v[168:171], v[208:211], v[88:91]
	v_mfma_f32_16x16x32_bf16 v[76:79], v[146:149], v[216:219], v[76:79]
	v_mfma_f32_16x16x32_bf16 v[72:75], v[168:171], v[216:219], v[72:75]
	v_mfma_f32_16x16x32_bf16 v[124:127], v[158:161], v[196:199], v[124:127]
	v_mfma_f32_16x16x32_bf16 v[120:123], v[172:175], v[196:199], v[120:123]
	v_mfma_f32_16x16x32_bf16 v[108:111], v[158:161], v[204:207], v[108:111]
	v_mfma_f32_16x16x32_bf16 v[104:107], v[172:175], v[204:207], v[104:107]
	v_mfma_f32_16x16x32_bf16 v[92:95], v[158:161], v[212:215], v[92:95]
	v_mfma_f32_16x16x32_bf16 v[88:91], v[172:175], v[212:215], v[88:91]
	v_mfma_f32_16x16x32_bf16 v[76:79], v[158:161], v[220:223], v[76:79]
	v_mfma_f32_16x16x32_bf16 v[72:75], v[172:175], v[220:223], v[72:75]
	v_mfma_f32_16x16x32_bf16 v[116:119], v[176:179], v[192:195], v[116:119]
	v_mfma_f32_16x16x32_bf16 v[112:115], v[184:187], v[192:195], v[112:115]
	v_mfma_f32_16x16x32_bf16 v[100:103], v[176:179], v[200:203], v[100:103]
	v_mfma_f32_16x16x32_bf16 v[96:99], v[184:187], v[200:203], v[96:99]
	v_mfma_f32_16x16x32_bf16 v[84:87], v[176:179], v[208:211], v[84:87]
	v_mfma_f32_16x16x32_bf16 v[80:83], v[184:187], v[208:211], v[80:83]
	v_mfma_f32_16x16x32_bf16 v[68:71], v[176:179], v[216:219], v[68:71]
	v_mfma_f32_16x16x32_bf16 v[64:67], v[184:187], v[216:219], v[64:67]
	v_mfma_f32_16x16x32_bf16 v[116:119], v[180:183], v[196:199], v[116:119]
	v_mfma_f32_16x16x32_bf16 v[112:115], v[188:191], v[196:199], v[112:115]
	v_mfma_f32_16x16x32_bf16 v[100:103], v[180:183], v[204:207], v[100:103]
	v_mfma_f32_16x16x32_bf16 v[96:99], v[188:191], v[204:207], v[96:99]
	v_mfma_f32_16x16x32_bf16 v[84:87], v[180:183], v[212:215], v[84:87]
	v_mfma_f32_16x16x32_bf16 v[80:83], v[188:191], v[212:215], v[80:83]
	v_mfma_f32_16x16x32_bf16 v[68:71], v[180:183], v[220:223], v[68:71]
	v_mfma_f32_16x16x32_bf16 v[64:67], v[188:191], v[220:223], v[64:67]
	s_barrier
; #define PG8_STAGE(bufoff, gbase, voff) do { _Pragma("unroll") for (int _i = 0; _i < 2; ++_i) \
;         __builtin_amdgcn_global_load_lds((const unsigned*)((const char*)(gbase) + (voff)[_i]), (PG8_LAS unsigned*)(lds + (bufoff) + ldsw + _i * 8192), 16, 0, 0); } while (0)
; #define PG8_LDA(dst, b, h) do { _Pragma("unroll") for (int m = 0; m < 4; ++m) _Pragma("unroll") for (int k = 0; k < 2; ++k) dst[m][k] = *(const PG8_LAS bf16x8*)(lds + PG8_SA(b, h) + aoff + m * 2048 + k * 1024); } while (0)
; #define PG8_LDB(dst, b, h) do { _Pragma("unroll") for (int n = 0; n < 2; ++n) _Pragma("unroll") for (int k = 0; k < 2; ++k) dst[n][k] = *(const PG8_LAS bf16x8*)(lds + PG8_SB(b, h) + boff + n * 2048 + k * 1024); } while (0)
; #define PG8_MMA(ai, bj, At, Bt) do { __builtin_amdgcn_s_setprio(1); _Pragma("unroll") for (int m = 0; m < 4; ++m) _Pragma("unroll") for (int n = 0; n < 2; ++n) _Pragma("unroll") for (int k = 0; k < 2; ++k) \
;         acc[ai][bj][m][n] = __builtin_amdgcn_mfma_f32_16x16x32_bf16(Bt[n][k], At[m][k], acc[ai][bj][m][n], 0, 0, 0); __builtin_amdgcn_s_setprio(0); } while (0)
; #define PG8_WAIT_V(n) asm volatile("s_waitcnt vmcnt(" #n ")" ::: "memory")
; #define PG8_WAIT_L(n) asm volatile("s_waitcnt lgkmcnt(" #n ")" ::: "memory")
; #define PG8_BAR __builtin_amdgcn_s_barrier()
; #define PG8_SCHED __builtin_amdgcn_sched_barrier(0)
; template <class Epi, class Sched, bool ALIGN_EPI = false, bool SP2 = false>
; __device__ __forceinline__ void gemm_phase(PG8_LAS unsigned char* lds, const Gemm g, const Sched& S, const Epi& E) {
;     ...
;             PG8_LDA(At, 0, 1); PG8_STAGE(PG8_SB(0, 0), b2, voffB); PG8_STAGE(PG8_SB(0, 1), b2 + hstepB, voffB); PG8_STAGE(PG8_SA(0, 0), a2, voffA);
;             PG8_WAIT_V(8); PG8_WAIT_L(0); PG8_BAR; PG8_MMA(1, 0, At, B0); PG8_MMA(1, 1, At, B1); PG8_BAR; PG8_SCHED;
;             PG8_LDB(B0, 1, 0); PG8_LDB(B1, 1, 1); PG8_SCHED; PG8_LDA(At, 1, 0); PG8_STAGE(PG8_SA(0, 1), a2 + hstepA, voffA);
	s_setprio 1
	s_add_u32 s98, s60, s20
	s_addc_u32 s99, s61, s21
	s_add_u32 s100, s62, s20
	s_addc_u32 s101, s63, s21
	s_add_i32 s41, s81, s68
	s_mov_b32 m0, s41
	ds_read_b128 v[192:195], v157 offset:16384
	ds_read_b128 v[196:199], v157 offset:17408
	ds_read_b128 v[200:203], v157 offset:18432
	ds_read_b128 v[204:207], v157 offset:19456
	ds_read_b128 v[208:211], v157 offset:20480
	ds_read_b128 v[212:215], v157 offset:21504
	ds_read_b128 v[216:219], v157 offset:22528
	ds_read_b128 v[220:223], v157 offset:23552
	global_load_lds_dwordx4 v130, s[60:61]
	s_add_i32 m0, s41, 0x2000
	s_add_u32 s84, s60, 0x80000
	s_addc_u32 s85, s61, 0
	s_add_i32 s41, s82, s68
	global_load_lds_dwordx4 v134, s[60:61]
	s_mov_b32 m0, s41
	s_nop 0
	global_load_lds_dwordx4 v130, s[84:85]
	s_add_i32 m0, s41, 0x2000
	s_nop 0
	global_load_lds_dwordx4 v134, s[84:85]
	s_mov_b32 m0, s69
	s_nop 0
	global_load_lds_dwordx4 v128, s[62:63]
	s_mov_b32 m0, s70
	s_nop 0
	global_load_lds_dwordx4 v132, s[62:63]
	s_waitcnt vmcnt(8)
	s_waitcnt lgkmcnt(0)
	s_setprio 0
	s_barrier
	v_mfma_f32_16x16x32_bf16 v[60:63], v[146:149], v[192:195], v[60:63]
	v_mfma_f32_16x16x32_bf16 v[56:59], v[168:171], v[192:195], v[56:59]
	v_mfma_f32_16x16x32_bf16 v[44:47], v[146:149], v[200:203], v[44:47]
	v_mfma_f32_16x16x32_bf16 v[40:43], v[168:171], v[200:203], v[40:43]
	v_mfma_f32_16x16x32_bf16 v[28:31], v[146:149], v[208:211], v[28:31]
	v_mfma_f32_16x16x32_bf16 v[24:27], v[168:171], v[208:211], v[24:27]
	v_mfma_f32_16x16x32_bf16 v[12:15], v[146:149], v[216:219], v[12:15]
	v_mfma_f32_16x16x32_bf16 v[8:11], v[168:171], v[216:219], v[8:11]
	v_mfma_f32_16x16x32_bf16 v[60:63], v[158:161], v[196:199], v[60:63]
	v_mfma_f32_16x16x32_bf16 v[56:59], v[172:175], v[196:199], v[56:59]
	v_mfma_f32_16x16x32_bf16 v[44:47], v[158:161], v[204:207], v[44:47]
	v_mfma_f32_16x16x32_bf16 v[40:43], v[172:175], v[204:207], v[40:43]
	v_mfma_f32_16x16x32_bf16 v[28:31], v[158:161], v[212:215], v[28:31]
	v_mfma_f32_16x16x32_bf16 v[24:27], v[172:175], v[212:215], v[24:27]
	v_mfma_f32_16x16x32_bf16 v[12:15], v[158:161], v[220:223], v[12:15]
	v_mfma_f32_16x16x32_bf16 v[8:11], v[172:175], v[220:223], v[8:11]
	v_mfma_f32_16x16x32_bf16 v[52:55], v[176:179], v[192:195], v[52:55]
	v_mfma_f32_16x16x32_bf16 v[48:51], v[184:187], v[192:195], v[48:51]
	v_mfma_f32_16x16x32_bf16 v[36:39], v[176:179], v[200:203], v[36:39]
	v_mfma_f32_16x16x32_bf16 v[32:35], v[184:187], v[200:203], v[32:35]
	v_mfma_f32_16x16x32_bf16 v[20:23], v[176:179], v[208:211], v[20:23]
	v_mfma_f32_16x16x32_bf16 v[16:19], v[184:187], v[208:211], v[16:19]
	v_mfma_f32_16x16x32_bf16 v[4:7], v[176:179], v[216:219], v[4:7]
	v_mfma_f32_16x16x32_bf16 v[0:3], v[184:187], v[216:219], v[0:3]
	v_mfma_f32_16x16x32_bf16 v[52:55], v[180:183], v[196:199], v[52:55]
	v_mfma_f32_16x16x32_bf16 v[48:51], v[188:191], v[196:199], v[48:51]
	v_mfma_f32_16x16x32_bf16 v[36:39], v[180:183], v[204:207], v[36:39]
	v_mfma_f32_16x16x32_bf16 v[32:35], v[188:191], v[204:207], v[32:35]
	v_mfma_f32_16x16x32_bf16 v[20:23], v[180:183], v[212:215], v[20:23]
	v_mfma_f32_16x16x32_bf16 v[16:19], v[188:191], v[212:215], v[16:19]
	v_mfma_f32_16x16x32_bf16 v[4:7], v[180:183], v[220:223], v[4:7]
	v_mfma_f32_16x16x32_bf16 v[0:3], v[188:191], v[220:223], v[0:3]
	s_barrier
	s_setprio 1
	s_add_i32 s41, 0, 0x18000
	s_add_i32 s43, 0, 0x1c000
	ds_read_b128 v[146:149], v241
	ds_read_b128 v[158:161], v241 offset:1024
	ds_read_b128 v[168:171], v241 offset:2048
	ds_read_b128 v[172:175], v241 offset:3072
	ds_read_b128 v[176:179], v242
	ds_read_b128 v[180:183], v242 offset:1024
	ds_read_b128 v[184:187], v242 offset:2048
	ds_read_b128 v[188:191], v242 offset:3072
	s_add_u32 s62, s62, 0x80000
	s_addc_u32 s63, s63, 0
	s_mov_b32 m0, s71
	ds_read_b128 v[192:195], v157 offset:32768
	ds_read_b128 v[196:199], v157 offset:33792
	ds_read_b128 v[200:203], v157 offset:34816
	ds_read_b128 v[204:207], v157 offset:35840
	ds_read_b128 v[208:211], v157 offset:36864
	ds_read_b128 v[212:215], v157 offset:37888
	ds_read_b128 v[216:219], v157 offset:38912
	ds_read_b128 v[220:223], v157 offset:39936
	global_load_lds_dwordx4 v128, s[62:63]
	s_mov_b32 m0, s72
	s_nop 0
	global_load_lds_dwordx4 v132, s[62:63]
	s_waitcnt vmcnt(8)
	s_waitcnt lgkmcnt(0)
	s_setprio 0
	s_barrier
; #define PG8_STAGE(bufoff, gbase, voff) do { _Pragma("unroll") for (int _i = 0; _i < 2; ++_i) \
;         __builtin_amdgcn_global_load_lds((const unsigned*)((const char*)(gbase) + (voff)[_i]), (PG8_LAS unsigned*)(lds + (bufoff) + ldsw + _i * 8192), 16, 0, 0); } while (0)
; #define PG8_LDA(dst, b, h) do { _Pragma("unroll") for (int m = 0; m < 4; ++m) _Pragma("unroll") for (int k = 0; k < 2; ++k) dst[m][k] = *(const PG8_LAS bf16x8*)(lds + PG8_SA(b, h) + aoff + m * 2048 + k * 1024); } while (0)
; #define PG8_MMA(ai, bj, At, Bt) do { __builtin_amdgcn_s_setprio(1); _Pragma("unroll") for (int m = 0; m < 4; ++m) _Pragma("unroll") for (int n = 0; n < 2; ++n) _Pragma("unroll") for (int k = 0; k < 2; ++k) \
;         acc[ai][bj][m][n] = __builtin_amdgcn_mfma_f32_16x16x32_bf16(Bt[n][k], At[m][k], acc[ai][bj][m][n], 0, 0, 0); __builtin_amdgcn_s_setprio(0); } while (0)
; #define PG8_WAIT_V(n) asm volatile("s_waitcnt vmcnt(" #n ")" ::: "memory")
; #define PG8_WAIT_L(n) asm volatile("s_waitcnt lgkmcnt(" #n ")" ::: "memory")
; #define PG8_BAR __builtin_amdgcn_s_barrier()
; #define PG8_SCHED __builtin_amdgcn_sched_barrier(0)
; template <class Epi, class Sched, bool ALIGN_EPI = false, bool SP2 = false>
; __device__ __forceinline__ void gemm_phase(PG8_LAS unsigned char* lds, const Gemm g, const Sched& S, const Epi& E) {
;     ...
;             PG8_WAIT_V(8); PG8_WAIT_L(0); PG8_BAR; PG8_MMA(0, 0, At, B0); PG8_MMA(0, 1, At, B1); PG8_BAR; PG8_SCHED;
;             PG8_LDA(At, 1, 1); PG8_STAGE(PG8_SB(1, 0), b3, voffB); PG8_STAGE(PG8_SB(1, 1), b3 + hstepB, voffB); PG8_STAGE(PG8_SA(1, 0), a3, voffA);
;             PG8_WAIT_V(8); PG8_WAIT_L(0); PG8_BAR; PG8_MMA(1, 0, At, B0); PG8_MMA(1, 1, At, B1); PG8_BAR; PG8_SCHED;
	v_mfma_f32_16x16x32_bf16 v[124:127], v[146:149], v[192:195], v[124:127]
	v_mfma_f32_16x16x32_bf16 v[120:123], v[168:171], v[192:195], v[120:123]
	v_mfma_f32_16x16x32_bf16 v[108:111], v[146:149], v[200:203], v[108:111]
	v_mfma_f32_16x16x32_bf16 v[104:107], v[168:171], v[200:203], v[104:107]
	v_mfma_f32_16x16x32_bf16 v[92:95], v[146:149], v[208:211], v[92:95]
	v_mfma_f32_16x16x32_bf16 v[88:91], v[168:171], v[208:211], v[88:91]
	v_mfma_f32_16x16x32_bf16 v[76:79], v[146:149], v[216:219], v[76:79]
	v_mfma_f32_16x16x32_bf16 v[72:75], v[168:171], v[216:219], v[72:75]
	v_mfma_f32_16x16x32_bf16 v[124:127], v[158:161], v[196:199], v[124:127]
	v_mfma_f32_16x16x32_bf16 v[120:123], v[172:175], v[196:199], v[120:123]
	v_mfma_f32_16x16x32_bf16 v[108:111], v[158:161], v[204:207], v[108:111]
	v_mfma_f32_16x16x32_bf16 v[104:107], v[172:175], v[204:207], v[104:107]
	v_mfma_f32_16x16x32_bf16 v[92:95], v[158:161], v[212:215], v[92:95]
	v_mfma_f32_16x16x32_bf16 v[88:91], v[172:175], v[212:215], v[88:91]
	v_mfma_f32_16x16x32_bf16 v[76:79], v[158:161], v[220:223], v[76:79]
	v_mfma_f32_16x16x32_bf16 v[72:75], v[172:175], v[220:223], v[72:75]
	v_mfma_f32_16x16x32_bf16 v[116:119], v[176:179], v[192:195], v[116:119]
	v_mfma_f32_16x16x32_bf16 v[112:115], v[184:187], v[192:195], v[112:115]
	v_mfma_f32_16x16x32_bf16 v[100:103], v[176:179], v[200:203], v[100:103]
	v_mfma_f32_16x16x32_bf16 v[96:99], v[184:187], v[200:203], v[96:99]
	v_mfma_f32_16x16x32_bf16 v[84:87], v[176:179], v[208:211], v[84:87]
	v_mfma_f32_16x16x32_bf16 v[80:83], v[184:187], v[208:211], v[80:83]
	v_mfma_f32_16x16x32_bf16 v[68:71], v[176:179], v[216:219], v[68:71]
	v_mfma_f32_16x16x32_bf16 v[64:67], v[184:187], v[216:219], v[64:67]
	v_mfma_f32_16x16x32_bf16 v[116:119], v[180:183], v[196:199], v[116:119]
	v_mfma_f32_16x16x32_bf16 v[112:115], v[188:191], v[196:199], v[112:115]
	v_mfma_f32_16x16x32_bf16 v[100:103], v[180:183], v[204:207], v[100:103]
	v_mfma_f32_16x16x32_bf16 v[96:99], v[188:191], v[204:207], v[96:99]
	v_mfma_f32_16x16x32_bf16 v[84:87], v[180:183], v[212:215], v[84:87]
	v_mfma_f32_16x16x32_bf16 v[80:83], v[188:191], v[212:215], v[80:83]
	v_mfma_f32_16x16x32_bf16 v[68:71], v[180:183], v[220:223], v[68:71]
	v_mfma_f32_16x16x32_bf16 v[64:67], v[188:191], v[220:223], v[64:67]
	s_barrier
	s_setprio 1
	s_add_i32 s41, s41, s68
	s_mov_b32 m0, s41
	ds_read_b128 v[192:195], v157 offset:49152
	ds_read_b128 v[196:199], v157 offset:50176
	ds_read_b128 v[200:203], v157 offset:51200
	ds_read_b128 v[204:207], v157 offset:52224
	ds_read_b128 v[208:211], v157 offset:53248
	ds_read_b128 v[212:215], v157 offset:54272
	ds_read_b128 v[216:219], v157 offset:55296
	ds_read_b128 v[220:223], v157 offset:56320
	global_load_lds_dwordx4 v130, s[98:99]
	s_add_i32 m0, s41, 0x2000
	s_add_u32 s60, s60, 0x80080
	s_addc_u32 s61, s61, 0
	s_add_i32 s41, s43, s68
	global_load_lds_dwordx4 v134, s[98:99]
	s_mov_b32 m0, s41
	s_nop 0
	global_load_lds_dwordx4 v130, s[60:61]
	s_add_i32 m0, s41, 0x2000
	s_nop 0
	global_load_lds_dwordx4 v134, s[60:61]
	s_mov_b32 m0, s78
	s_nop 0
	global_load_lds_dwordx4 v128, s[100:101]
	s_mov_b32 m0, s79
	s_nop 0
	global_load_lds_dwordx4 v132, s[100:101]
	s_waitcnt vmcnt(8)
	s_waitcnt lgkmcnt(0)
	s_setprio 0
	s_barrier
	v_mfma_f32_16x16x32_bf16 v[60:63], v[146:149], v[192:195], v[60:63]
	v_mfma_f32_16x16x32_bf16 v[56:59], v[168:171], v[192:195], v[56:59]
	v_mfma_f32_16x16x32_bf16 v[44:47], v[146:149], v[200:203], v[44:47]
	v_mfma_f32_16x16x32_bf16 v[40:43], v[168:171], v[200:203], v[40:43]
	v_mfma_f32_16x16x32_bf16 v[28:31], v[146:149], v[208:211], v[28:31]
	v_mfma_f32_16x16x32_bf16 v[24:27], v[168:171], v[208:211], v[24:27]
	v_mfma_f32_16x16x32_bf16 v[12:15], v[146:149], v[216:219], v[12:15]
	v_mfma_f32_16x16x32_bf16 v[8:11], v[168:171], v[216:219], v[8:11]
	v_mfma_f32_16x16x32_bf16 v[60:63], v[158:161], v[196:199], v[60:63]
	v_mfma_f32_16x16x32_bf16 v[56:59], v[172:175], v[196:199], v[56:59]
	v_mfma_f32_16x16x32_bf16 v[44:47], v[158:161], v[204:207], v[44:47]
	v_mfma_f32_16x16x32_bf16 v[40:43], v[172:175], v[204:207], v[40:43]
	v_mfma_f32_16x16x32_bf16 v[28:31], v[158:161], v[212:215], v[28:31]
	v_mfma_f32_16x16x32_bf16 v[24:27], v[172:175], v[212:215], v[24:27]
	v_mfma_f32_16x16x32_bf16 v[12:15], v[158:161], v[220:223], v[12:15]
	v_mfma_f32_16x16x32_bf16 v[8:11], v[172:175], v[220:223], v[8:11]
	v_mfma_f32_16x16x32_bf16 v[52:55], v[176:179], v[192:195], v[52:55]
	v_mfma_f32_16x16x32_bf16 v[48:51], v[184:187], v[192:195], v[48:51]
	v_mfma_f32_16x16x32_bf16 v[36:39], v[176:179], v[200:203], v[36:39]
	v_mfma_f32_16x16x32_bf16 v[32:35], v[184:187], v[200:203], v[32:35]
	v_mfma_f32_16x16x32_bf16 v[20:23], v[176:179], v[208:211], v[20:23]
	v_mfma_f32_16x16x32_bf16 v[16:19], v[184:187], v[208:211], v[16:19]
	v_mfma_f32_16x16x32_bf16 v[4:7], v[176:179], v[216:219], v[4:7]
	v_mfma_f32_16x16x32_bf16 v[0:3], v[184:187], v[216:219], v[0:3]
	v_mfma_f32_16x16x32_bf16 v[52:55], v[180:183], v[196:199], v[52:55]
	v_mfma_f32_16x16x32_bf16 v[48:51], v[188:191], v[196:199], v[48:51]
	v_mfma_f32_16x16x32_bf16 v[36:39], v[180:183], v[204:207], v[36:39]
	v_mfma_f32_16x16x32_bf16 v[32:35], v[188:191], v[204:207], v[32:35]
	v_mfma_f32_16x16x32_bf16 v[20:23], v[180:183], v[212:215], v[20:23]
	v_mfma_f32_16x16x32_bf16 v[16:19], v[188:191], v[212:215], v[16:19]
	v_mfma_f32_16x16x32_bf16 v[4:7], v[180:183], v[220:223], v[4:7]
	v_mfma_f32_16x16x32_bf16 v[0:3], v[188:191], v[220:223], v[0:3]
	s_barrier
	s_setprio 1
	s_add_i32 s34, s34, 2
	s_add_u32 s54, s54, 0x100
	s_addc_u32 s55, s55, 0
	s_add_u32 s31, s31, 0x100
	s_addc_u32 s33, s33, 0
	s_cmp_gt_u32 s34, 29
	s_cbranch_scc0 .LBB0_497
	s_and_b64 vcc, exec, s[22:23]
	s_cbranch_vccz .LBB0_500
	s_barrier

; #define PG8_STAGE(bufoff, gbase, voff) do { _Pragma("unroll") for (int _i = 0; _i < 2; ++_i) \
;         __builtin_amdgcn_global_load_lds((const unsigned*)((const char*)(gbase) + (voff)[_i]), (PG8_LAS unsigned*)(lds + (bufoff) + ldsw + _i * 8192), 16, 0, 0); } while (0)
; #define PG8_LDA(dst, b, h) do { _Pragma("unroll") for (int m = 0; m < 4; ++m) _Pragma("unroll") for (int k = 0; k < 2; ++k) dst[m][k] = *(const PG8_LAS bf16x8*)(lds + PG8_SA(b, h) + aoff + m * 2048 + k * 1024); } while (0)
; #define PG8_LDB(dst, b, h) do { _Pragma("unroll") for (int n = 0; n < 2; ++n) _Pragma("unroll") for (int k = 0; k < 2; ++k) dst[n][k] = *(const PG8_LAS bf16x8*)(lds + PG8_SB(b, h) + boff + n * 2048 + k * 1024); } while (0)
; #define PG8_MMA(ai, bj, At, Bt) do { __builtin_amdgcn_s_setprio(1); _Pragma("unroll") for (int m = 0; m < 4; ++m) _Pragma("unroll") for (int n = 0; n < 2; ++n) _Pragma("unroll") for (int k = 0; k < 2; ++k) \
;         acc[ai][bj][m][n] = __builtin_amdgcn_mfma_f32_16x16x32_bf16(Bt[n][k], At[m][k], acc[ai][bj][m][n], 0, 0, 0); __builtin_amdgcn_s_setprio(0); } while (0)
; #define PG8_WAIT_V(n) asm volatile("s_waitcnt vmcnt(" #n ")" ::: "memory")
; #define PG8_WAIT_L(n) asm volatile("s_waitcnt lgkmcnt(" #n ")" ::: "memory")
; #define PG8_BAR __builtin_amdgcn_s_barrier()
; #define PG8_SCHED __builtin_amdgcn_sched_barrier(0)
; template <class Epi, class Sched, bool ALIGN_EPI = false, bool SP2 = false>
; __device__ __forceinline__ void gemm_phase(PG8_LAS unsigned char* lds, const Gemm g, const Sched& S, const Epi& E) {
;     ...
;             PG8_LDB(B0, 0, 0); PG8_LDB(B1, 0, 1); PG8_SCHED; PG8_LDA(At, 0, 0); PG8_STAGE(PG8_SA(1, 1), a1 + hstepA, voffA);
;             PG8_WAIT_V(8); PG8_WAIT_L(0); PG8_BAR; PG8_MMA(0, 0, At, B0); PG8_MMA(0, 1, At, B1); PG8_BAR; PG8_SCHED;
;     ...
; #pragma unroll
;         for (int a = 0; a < 2; ++a)
; #pragma unroll
;             for (int b = 0; b < 2; ++b)
; #pragma unroll
;                 for (int m = 0; m < 4; ++m)
; #pragma unroll
;                     for (int n = 0; n < 2; ++n) acc[a][b][m][n] = (f32x4){0.f, 0.f, 0.f, 0.f};
;         cur = nxt; cA = nA; cB = nB; ++ui;
.LBB0_828:
	s_ashr_i32 s19, s18, 31
	s_lshl_b64 s[22:23], s[18:19], 19
	v_readlane_b32 s56, v240, 14
	v_readlane_b32 s57, v240, 15
	s_add_u32 s22, s56, s22
	s_addc_u32 s23, s57, s23
	s_and_b64 s[0:1], s[0:1], exec
	s_cselect_b32 s19, s23, s41
	s_cselect_b32 s55, s22, s40
	s_add_u32 s0, s42, 0x240080
	s_addc_u32 s1, s43, 0
	s_add_u32 s56, s40, 0x100
	v_mov_b64_e32 v[0:1], 0
	s_addc_u32 s57, s41, 0
	s_mov_b32 s58, -2
	v_mov_b64_e32 v[2:3], 0
	v_mov_b64_e32 v[4:5], 0
	v_mov_b64_e32 v[6:7], 0
	v_mov_b64_e32 v[16:17], 0
	v_mov_b64_e32 v[18:19], 0
	v_mov_b64_e32 v[20:21], 0
	v_mov_b64_e32 v[22:23], 0
	v_mov_b64_e32 v[32:33], 0
	v_mov_b64_e32 v[34:35], 0
	v_mov_b64_e32 v[36:37], 0
	v_mov_b64_e32 v[38:39], 0
	v_mov_b64_e32 v[48:49], 0
	v_mov_b64_e32 v[50:51], 0
	v_mov_b64_e32 v[52:53], 0
	v_mov_b64_e32 v[54:55], 0
	v_mov_b64_e32 v[8:9], 0
	v_mov_b64_e32 v[10:11], 0
	v_mov_b64_e32 v[12:13], 0
	v_mov_b64_e32 v[14:15], 0
	v_mov_b64_e32 v[24:25], 0
	v_mov_b64_e32 v[26:27], 0
	v_mov_b64_e32 v[28:29], 0
	v_mov_b64_e32 v[30:31], 0
	v_mov_b64_e32 v[40:41], 0
	v_mov_b64_e32 v[42:43], 0
	v_mov_b64_e32 v[44:45], 0
	v_mov_b64_e32 v[46:47], 0
	v_mov_b64_e32 v[56:57], 0
	v_mov_b64_e32 v[58:59], 0
	v_mov_b64_e32 v[60:61], 0
	v_mov_b64_e32 v[62:63], 0
	v_mov_b64_e32 v[64:65], 0
	v_mov_b64_e32 v[66:67], 0
	v_mov_b64_e32 v[68:69], 0
	v_mov_b64_e32 v[70:71], 0
	v_mov_b64_e32 v[80:81], 0
	v_mov_b64_e32 v[82:83], 0
	v_mov_b64_e32 v[84:85], 0
	v_mov_b64_e32 v[86:87], 0
	v_mov_b64_e32 v[96:97], 0
	v_mov_b64_e32 v[98:99], 0
	v_mov_b64_e32 v[100:101], 0
	v_mov_b64_e32 v[102:103], 0
	v_mov_b64_e32 v[112:113], 0
	v_mov_b64_e32 v[114:115], 0
	v_mov_b64_e32 v[116:117], 0
	v_mov_b64_e32 v[118:119], 0
	v_mov_b64_e32 v[72:73], 0
	v_mov_b64_e32 v[74:75], 0
	v_mov_b64_e32 v[76:77], 0
	v_mov_b64_e32 v[78:79], 0
	v_mov_b64_e32 v[88:89], 0
	v_mov_b64_e32 v[90:91], 0
	v_mov_b64_e32 v[92:93], 0
	v_mov_b64_e32 v[94:95], 0
	v_mov_b64_e32 v[104:105], 0
	v_mov_b64_e32 v[106:107], 0
	v_mov_b64_e32 v[108:109], 0
	v_mov_b64_e32 v[110:111], 0
	v_mov_b64_e32 v[120:121], 0
	v_mov_b64_e32 v[122:123], 0
	v_mov_b64_e32 v[124:125], 0
	v_mov_b64_e32 v[126:127], 0
	v_add_u32_e32 v241, 0x18000, v151
	v_add_u32_e32 v242, 0x1c000, v151
.LBB0_829:
	ds_read_b128 v[144:147], v153
	ds_read_b128 v[158:161], v153 offset:1024
	ds_read_b128 v[166:169], v153 offset:2048
	ds_read_b128 v[170:173], v153 offset:3072
	ds_read_b128 v[174:177], v154
	ds_read_b128 v[178:181], v154 offset:1024
	ds_read_b128 v[182:185], v154 offset:2048
	ds_read_b128 v[186:189], v154 offset:3072
	s_add_u32 s40, s0, 0xffdc0080
	s_addc_u32 s41, s1, -1
	s_cmp_eq_u32 s58, 12
	s_cselect_b32 s43, s21, s41
	s_cselect_b32 s42, s20, s40
	s_cselect_b32 s41, s19, s57
	s_cselect_b32 s40, s55, s56
	s_add_i32 m0, s33, 0xc000
	ds_read_b128 v[190:193], v155
	ds_read_b128 v[194:197], v155 offset:1024
	ds_read_b128 v[198:201], v155 offset:2048
	ds_read_b128 v[202:205], v155 offset:3072
	ds_read_b128 v[206:209], v155 offset:4096
	ds_read_b128 v[210:213], v155 offset:5120
	ds_read_b128 v[214:217], v155 offset:6144
	ds_read_b128 v[218:221], v155 offset:7168
	global_load_lds_dwordx4 v136, s[0:1]
	s_add_i32 m0, s33, 0xe000
	s_nop 0
	global_load_lds_dwordx4 v138, s[0:1]
	s_waitcnt vmcnt(8)
	s_waitcnt lgkmcnt(0)
	s_setprio 0
	s_barrier
	v_mfma_f32_16x16x32_bf16 v[124:127], v[144:147], v[190:193], v[124:127]
	v_mfma_f32_16x16x32_bf16 v[120:123], v[166:169], v[190:193], v[120:123]
	v_mfma_f32_16x16x32_bf16 v[108:111], v[144:147], v[198:201], v[108:111]
	v_mfma_f32_16x16x32_bf16 v[104:107], v[166:169], v[198:201], v[104:107]
	v_mfma_f32_16x16x32_bf16 v[92:95], v[144:147], v[206:209], v[92:95]
	v_mfma_f32_16x16x32_bf16 v[88:91], v[166:169], v[206:209], v[88:91]
	v_mfma_f32_16x16x32_bf16 v[76:79], v[144:147], v[214:217], v[76:79]
	v_mfma_f32_16x16x32_bf16 v[72:75], v[166:169], v[214:217], v[72:75]
	v_mfma_f32_16x16x32_bf16 v[124:127], v[158:161], v[194:197], v[124:127]
	v_mfma_f32_16x16x32_bf16 v[120:123], v[170:173], v[194:197], v[120:123]
	v_mfma_f32_16x16x32_bf16 v[108:111], v[158:161], v[202:205], v[108:111]
	v_mfma_f32_16x16x32_bf16 v[104:107], v[170:173], v[202:205], v[104:107]
	v_mfma_f32_16x16x32_bf16 v[92:95], v[158:161], v[210:213], v[92:95]
	v_mfma_f32_16x16x32_bf16 v[88:91], v[170:173], v[210:213], v[88:91]
	v_mfma_f32_16x16x32_bf16 v[76:79], v[158:161], v[218:221], v[76:79]
	v_mfma_f32_16x16x32_bf16 v[72:75], v[170:173], v[218:221], v[72:75]
	v_mfma_f32_16x16x32_bf16 v[116:119], v[174:177], v[190:193], v[116:119]
	v_mfma_f32_16x16x32_bf16 v[112:115], v[182:185], v[190:193], v[112:115]
	v_mfma_f32_16x16x32_bf16 v[100:103], v[174:177], v[198:201], v[100:103]
	v_mfma_f32_16x16x32_bf16 v[96:99], v[182:185], v[198:201], v[96:99]
	v_mfma_f32_16x16x32_bf16 v[84:87], v[174:177], v[206:209], v[84:87]
	v_mfma_f32_16x16x32_bf16 v[80:83], v[182:185], v[206:209], v[80:83]
	v_mfma_f32_16x16x32_bf16 v[68:71], v[174:177], v[214:217], v[68:71]
	v_mfma_f32_16x16x32_bf16 v[64:67], v[182:185], v[214:217], v[64:67]
	v_mfma_f32_16x16x32_bf16 v[116:119], v[178:181], v[194:197], v[116:119]
	v_mfma_f32_16x16x32_bf16 v[112:115], v[186:189], v[194:197], v[112:115]
	v_mfma_f32_16x16x32_bf16 v[100:103], v[178:181], v[202:205], v[100:103]
	v_mfma_f32_16x16x32_bf16 v[96:99], v[186:189], v[202:205], v[96:99]
	v_mfma_f32_16x16x32_bf16 v[84:87], v[178:181], v[210:213], v[84:87]
	v_mfma_f32_16x16x32_bf16 v[80:83], v[186:189], v[210:213], v[80:83]
	v_mfma_f32_16x16x32_bf16 v[68:71], v[178:181], v[218:221], v[68:71]
	v_mfma_f32_16x16x32_bf16 v[64:67], v[186:189], v[218:221], v[64:67]
	s_barrier
; #define PG8_STAGE(bufoff, gbase, voff) do { _Pragma("unroll") for (int _i = 0; _i < 2; ++_i) \
;         __builtin_amdgcn_global_load_lds((const unsigned*)((const char*)(gbase) + (voff)[_i]), (PG8_LAS unsigned*)(lds + (bufoff) + ldsw + _i * 8192), 16, 0, 0); } while (0)
; #define PG8_LDA(dst, b, h) do { _Pragma("unroll") for (int m = 0; m < 4; ++m) _Pragma("unroll") for (int k = 0; k < 2; ++k) dst[m][k] = *(const PG8_LAS bf16x8*)(lds + PG8_SA(b, h) + aoff + m * 2048 + k * 1024); } while (0)
; #define PG8_LDB(dst, b, h) do { _Pragma("unroll") for (int n = 0; n < 2; ++n) _Pragma("unroll") for (int k = 0; k < 2; ++k) dst[n][k] = *(const PG8_LAS bf16x8*)(lds + PG8_SB(b, h) + boff + n * 2048 + k * 1024); } while (0)
; #define PG8_MMA(ai, bj, At, Bt) do { __builtin_amdgcn_s_setprio(1); _Pragma("unroll") for (int m = 0; m < 4; ++m) _Pragma("unroll") for (int n = 0; n < 2; ++n) _Pragma("unroll") for (int k = 0; k < 2; ++k) \
;         acc[ai][bj][m][n] = __builtin_amdgcn_mfma_f32_16x16x32_bf16(Bt[n][k], At[m][k], acc[ai][bj][m][n], 0, 0, 0); __builtin_amdgcn_s_setprio(0); } while (0)
; #define PG8_WAIT_V(n) asm volatile("s_waitcnt vmcnt(" #n ")" ::: "memory")
; #define PG8_WAIT_L(n) asm volatile("s_waitcnt lgkmcnt(" #n ")" ::: "memory")
; #define PG8_BAR __builtin_amdgcn_s_barrier()
; #define PG8_SCHED __builtin_amdgcn_sched_barrier(0)
; template <class Epi, class Sched, bool ALIGN_EPI = false, bool SP2 = false>
; __device__ __forceinline__ void gemm_phase(PG8_LAS unsigned char* lds, const Gemm g, const Sched& S, const Epi& E) {
;     ...
;             PG8_LDA(At, 0, 1); PG8_STAGE(PG8_SB(0, 0), b2, voffB); PG8_STAGE(PG8_SB(0, 1), b2 + hstepB, voffB); PG8_STAGE(PG8_SA(0, 0), a2, voffA);
;             PG8_WAIT_V(8); PG8_WAIT_L(0); PG8_BAR; PG8_MMA(1, 0, At, B0); PG8_MMA(1, 1, At, B1); PG8_BAR; PG8_SCHED;
;             PG8_LDB(B0, 1, 0); PG8_LDB(B1, 1, 1); PG8_SCHED; PG8_LDA(At, 1, 0); PG8_STAGE(PG8_SA(0, 1), a2 + hstepA, voffA);
	s_setprio 1
	s_add_u32 s98, s40, s10
	s_addc_u32 s99, s41, s11
	s_add_u32 s100, s42, s10
	s_addc_u32 s101, s43, s11
	s_add_i32 s59, s49, s30
	s_mov_b32 m0, s59
	ds_read_b128 v[190:193], v155 offset:16384
	ds_read_b128 v[194:197], v155 offset:17408
	ds_read_b128 v[198:201], v155 offset:18432
	ds_read_b128 v[202:205], v155 offset:19456
	ds_read_b128 v[206:209], v155 offset:20480
	ds_read_b128 v[210:213], v155 offset:21504
	ds_read_b128 v[214:217], v155 offset:22528
	ds_read_b128 v[218:221], v155 offset:23552
	global_load_lds_dwordx4 v132, s[40:41]
	s_add_i32 m0, s59, 0x2000
	s_add_u32 s60, s40, 0x40000
	s_addc_u32 s61, s41, 0
	s_add_i32 s59, s50, s30
	global_load_lds_dwordx4 v128, s[40:41]
	s_mov_b32 m0, s59
	s_nop 0
	global_load_lds_dwordx4 v132, s[60:61]
	s_add_i32 m0, s59, 0x2000
	s_nop 0
	global_load_lds_dwordx4 v128, s[60:61]
	s_mov_b32 m0, s33
	s_nop 0
	global_load_lds_dwordx4 v134, s[42:43]
	s_mov_b32 m0, s34
	s_nop 0
	global_load_lds_dwordx4 v130, s[42:43]
	s_waitcnt vmcnt(8)
	s_waitcnt lgkmcnt(0)
	s_setprio 0
	s_barrier
	v_mfma_f32_16x16x32_bf16 v[60:63], v[144:147], v[190:193], v[60:63]
	v_mfma_f32_16x16x32_bf16 v[56:59], v[166:169], v[190:193], v[56:59]
	v_mfma_f32_16x16x32_bf16 v[44:47], v[144:147], v[198:201], v[44:47]
	v_mfma_f32_16x16x32_bf16 v[40:43], v[166:169], v[198:201], v[40:43]
	v_mfma_f32_16x16x32_bf16 v[28:31], v[144:147], v[206:209], v[28:31]
	v_mfma_f32_16x16x32_bf16 v[24:27], v[166:169], v[206:209], v[24:27]
	v_mfma_f32_16x16x32_bf16 v[12:15], v[144:147], v[214:217], v[12:15]
	v_mfma_f32_16x16x32_bf16 v[8:11], v[166:169], v[214:217], v[8:11]
	v_mfma_f32_16x16x32_bf16 v[60:63], v[158:161], v[194:197], v[60:63]
	v_mfma_f32_16x16x32_bf16 v[56:59], v[170:173], v[194:197], v[56:59]
	v_mfma_f32_16x16x32_bf16 v[44:47], v[158:161], v[202:205], v[44:47]
	v_mfma_f32_16x16x32_bf16 v[40:43], v[170:173], v[202:205], v[40:43]
	v_mfma_f32_16x16x32_bf16 v[28:31], v[158:161], v[210:213], v[28:31]
	v_mfma_f32_16x16x32_bf16 v[24:27], v[170:173], v[210:213], v[24:27]
	v_mfma_f32_16x16x32_bf16 v[12:15], v[158:161], v[218:221], v[12:15]
	v_mfma_f32_16x16x32_bf16 v[8:11], v[170:173], v[218:221], v[8:11]
	v_mfma_f32_16x16x32_bf16 v[52:55], v[174:177], v[190:193], v[52:55]
	v_mfma_f32_16x16x32_bf16 v[48:51], v[182:185], v[190:193], v[48:51]
	v_mfma_f32_16x16x32_bf16 v[36:39], v[174:177], v[198:201], v[36:39]
	v_mfma_f32_16x16x32_bf16 v[32:35], v[182:185], v[198:201], v[32:35]
	v_mfma_f32_16x16x32_bf16 v[20:23], v[174:177], v[206:209], v[20:23]
	v_mfma_f32_16x16x32_bf16 v[16:19], v[182:185], v[206:209], v[16:19]
	v_mfma_f32_16x16x32_bf16 v[4:7], v[174:177], v[214:217], v[4:7]
	v_mfma_f32_16x16x32_bf16 v[0:3], v[182:185], v[214:217], v[0:3]
	v_mfma_f32_16x16x32_bf16 v[52:55], v[178:181], v[194:197], v[52:55]
	v_mfma_f32_16x16x32_bf16 v[48:51], v[186:189], v[194:197], v[48:51]
	v_mfma_f32_16x16x32_bf16 v[36:39], v[178:181], v[202:205], v[36:39]
	v_mfma_f32_16x16x32_bf16 v[32:35], v[186:189], v[202:205], v[32:35]
	v_mfma_f32_16x16x32_bf16 v[20:23], v[178:181], v[210:213], v[20:23]
	v_mfma_f32_16x16x32_bf16 v[16:19], v[186:189], v[210:213], v[16:19]
	v_mfma_f32_16x16x32_bf16 v[4:7], v[178:181], v[218:221], v[4:7]
	v_mfma_f32_16x16x32_bf16 v[0:3], v[186:189], v[218:221], v[0:3]
	s_barrier
	s_setprio 1
	s_add_i32 s59, 0, 0x18000
	s_add_i32 s60, 0, 0x1c000
	ds_read_b128 v[144:147], v241
	ds_read_b128 v[158:161], v241 offset:1024
	ds_read_b128 v[166:169], v241 offset:2048
	ds_read_b128 v[170:173], v241 offset:3072
	ds_read_b128 v[174:177], v242
	ds_read_b128 v[178:181], v242 offset:1024
	ds_read_b128 v[182:185], v242 offset:2048
	ds_read_b128 v[186:189], v242 offset:3072
	s_add_u32 s42, s42, 0x240000
	s_addc_u32 s43, s43, 0
	s_mov_b32 m0, s35
	ds_read_b128 v[190:193], v155 offset:32768
	ds_read_b128 v[194:197], v155 offset:33792
	ds_read_b128 v[198:201], v155 offset:34816
	ds_read_b128 v[202:205], v155 offset:35840
	ds_read_b128 v[206:209], v155 offset:36864
	ds_read_b128 v[210:213], v155 offset:37888
	ds_read_b128 v[214:217], v155 offset:38912
	ds_read_b128 v[218:221], v155 offset:39936
	global_load_lds_dwordx4 v134, s[42:43]
	s_mov_b32 m0, s44
	s_nop 0
	global_load_lds_dwordx4 v130, s[42:43]
	s_waitcnt vmcnt(8)
	s_waitcnt lgkmcnt(0)
	s_setprio 0
	s_barrier
; #define PG8_STAGE(bufoff, gbase, voff) do { _Pragma("unroll") for (int _i = 0; _i < 2; ++_i) \
;         __builtin_amdgcn_global_load_lds((const unsigned*)((const char*)(gbase) + (voff)[_i]), (PG8_LAS unsigned*)(lds + (bufoff) + ldsw + _i * 8192), 16, 0, 0); } while (0)
; #define PG8_LDA(dst, b, h) do { _Pragma("unroll") for (int m = 0; m < 4; ++m) _Pragma("unroll") for (int k = 0; k < 2; ++k) dst[m][k] = *(const PG8_LAS bf16x8*)(lds + PG8_SA(b, h) + aoff + m * 2048 + k * 1024); } while (0)
; #define PG8_MMA(ai, bj, At, Bt) do { __builtin_amdgcn_s_setprio(1); _Pragma("unroll") for (int m = 0; m < 4; ++m) _Pragma("unroll") for (int n = 0; n < 2; ++n) _Pragma("unroll") for (int k = 0; k < 2; ++k) \
;         acc[ai][bj][m][n] = __builtin_amdgcn_mfma_f32_16x16x32_bf16(Bt[n][k], At[m][k], acc[ai][bj][m][n], 0, 0, 0); __builtin_amdgcn_s_setprio(0); } while (0)
; #define PG8_WAIT_V(n) asm volatile("s_waitcnt vmcnt(" #n ")" ::: "memory")
; #define PG8_WAIT_L(n) asm volatile("s_waitcnt lgkmcnt(" #n ")" ::: "memory")
; #define PG8_BAR __builtin_amdgcn_s_barrier()
; #define PG8_SCHED __builtin_amdgcn_sched_barrier(0)
; template <class Epi, class Sched, bool ALIGN_EPI = false, bool SP2 = false>
; __device__ __forceinline__ void gemm_phase(PG8_LAS unsigned char* lds, const Gemm g, const Sched& S, const Epi& E) {
;     ...
;             PG8_WAIT_V(8); PG8_WAIT_L(0); PG8_BAR; PG8_MMA(0, 0, At, B0); PG8_MMA(0, 1, At, B1); PG8_BAR; PG8_SCHED;
;             PG8_LDA(At, 1, 1); PG8_STAGE(PG8_SB(1, 0), b3, voffB); PG8_STAGE(PG8_SB(1, 1), b3 + hstepB, voffB); PG8_STAGE(PG8_SA(1, 0), a3, voffA);
;             PG8_WAIT_V(8); PG8_WAIT_L(0); PG8_BAR; PG8_MMA(1, 0, At, B0); PG8_MMA(1, 1, At, B1); PG8_BAR; PG8_SCHED;
	v_mfma_f32_16x16x32_bf16 v[124:127], v[144:147], v[190:193], v[124:127]
	v_mfma_f32_16x16x32_bf16 v[120:123], v[166:169], v[190:193], v[120:123]
	v_mfma_f32_16x16x32_bf16 v[108:111], v[144:147], v[198:201], v[108:111]
	v_mfma_f32_16x16x32_bf16 v[104:107], v[166:169], v[198:201], v[104:107]
	v_mfma_f32_16x16x32_bf16 v[92:95], v[144:147], v[206:209], v[92:95]
	v_mfma_f32_16x16x32_bf16 v[88:91], v[166:169], v[206:209], v[88:91]
	v_mfma_f32_16x16x32_bf16 v[76:79], v[144:147], v[214:217], v[76:79]
	v_mfma_f32_16x16x32_bf16 v[72:75], v[166:169], v[214:217], v[72:75]
	v_mfma_f32_16x16x32_bf16 v[124:127], v[158:161], v[194:197], v[124:127]
	v_mfma_f32_16x16x32_bf16 v[120:123], v[170:173], v[194:197], v[120:123]
	v_mfma_f32_16x16x32_bf16 v[108:111], v[158:161], v[202:205], v[108:111]
	v_mfma_f32_16x16x32_bf16 v[104:107], v[170:173], v[202:205], v[104:107]
	v_mfma_f32_16x16x32_bf16 v[92:95], v[158:161], v[210:213], v[92:95]
	v_mfma_f32_16x16x32_bf16 v[88:91], v[170:173], v[210:213], v[88:91]
	v_mfma_f32_16x16x32_bf16 v[76:79], v[158:161], v[218:221], v[76:79]
	v_mfma_f32_16x16x32_bf16 v[72:75], v[170:173], v[218:221], v[72:75]
	v_mfma_f32_16x16x32_bf16 v[116:119], v[174:177], v[190:193], v[116:119]
	v_mfma_f32_16x16x32_bf16 v[112:115], v[182:185], v[190:193], v[112:115]
	v_mfma_f32_16x16x32_bf16 v[100:103], v[174:177], v[198:201], v[100:103]
	v_mfma_f32_16x16x32_bf16 v[96:99], v[182:185], v[198:201], v[96:99]
	v_mfma_f32_16x16x32_bf16 v[84:87], v[174:177], v[206:209], v[84:87]
	v_mfma_f32_16x16x32_bf16 v[80:83], v[182:185], v[206:209], v[80:83]
	v_mfma_f32_16x16x32_bf16 v[68:71], v[174:177], v[214:217], v[68:71]
	v_mfma_f32_16x16x32_bf16 v[64:67], v[182:185], v[214:217], v[64:67]
	v_mfma_f32_16x16x32_bf16 v[116:119], v[178:181], v[194:197], v[116:119]
	v_mfma_f32_16x16x32_bf16 v[112:115], v[186:189], v[194:197], v[112:115]
	v_mfma_f32_16x16x32_bf16 v[100:103], v[178:181], v[202:205], v[100:103]
	v_mfma_f32_16x16x32_bf16 v[96:99], v[186:189], v[202:205], v[96:99]
	v_mfma_f32_16x16x32_bf16 v[84:87], v[178:181], v[210:213], v[84:87]
	v_mfma_f32_16x16x32_bf16 v[80:83], v[186:189], v[210:213], v[80:83]
	v_mfma_f32_16x16x32_bf16 v[68:71], v[178:181], v[218:221], v[68:71]
	v_mfma_f32_16x16x32_bf16 v[64:67], v[186:189], v[218:221], v[64:67]
	s_barrier
	s_setprio 1
	s_add_i32 s42, s59, s30
	s_mov_b32 m0, s42
	ds_read_b128 v[190:193], v155 offset:49152
	ds_read_b128 v[194:197], v155 offset:50176
	ds_read_b128 v[198:201], v155 offset:51200
	ds_read_b128 v[202:205], v155 offset:52224
	ds_read_b128 v[206:209], v155 offset:53248
	ds_read_b128 v[210:213], v155 offset:54272
	ds_read_b128 v[214:217], v155 offset:55296
	ds_read_b128 v[218:221], v155 offset:56320
	global_load_lds_dwordx4 v132, s[98:99]
	s_add_i32 m0, s42, 0x2000
	s_add_u32 s40, s40, 0x40080
	s_addc_u32 s41, s41, 0
	s_add_i32 s42, s60, s30
	global_load_lds_dwordx4 v128, s[98:99]
	s_mov_b32 m0, s42
	s_nop 0
	global_load_lds_dwordx4 v132, s[40:41]
	s_add_i32 m0, s42, 0x2000
	s_nop 0
	global_load_lds_dwordx4 v128, s[40:41]
	s_mov_b32 m0, s47
	s_nop 0
	global_load_lds_dwordx4 v134, s[100:101]
	s_mov_b32 m0, s48
	s_nop 0
	global_load_lds_dwordx4 v130, s[100:101]
	s_waitcnt vmcnt(8)
	s_waitcnt lgkmcnt(0)
	s_setprio 0
	s_barrier
	v_mfma_f32_16x16x32_bf16 v[60:63], v[144:147], v[190:193], v[60:63]
	v_mfma_f32_16x16x32_bf16 v[56:59], v[166:169], v[190:193], v[56:59]
	v_mfma_f32_16x16x32_bf16 v[44:47], v[144:147], v[198:201], v[44:47]
	v_mfma_f32_16x16x32_bf16 v[40:43], v[166:169], v[198:201], v[40:43]
	v_mfma_f32_16x16x32_bf16 v[28:31], v[144:147], v[206:209], v[28:31]
	v_mfma_f32_16x16x32_bf16 v[24:27], v[166:169], v[206:209], v[24:27]
	v_mfma_f32_16x16x32_bf16 v[12:15], v[144:147], v[214:217], v[12:15]
	v_mfma_f32_16x16x32_bf16 v[8:11], v[166:169], v[214:217], v[8:11]
	v_mfma_f32_16x16x32_bf16 v[60:63], v[158:161], v[194:197], v[60:63]
	v_mfma_f32_16x16x32_bf16 v[56:59], v[170:173], v[194:197], v[56:59]
	v_mfma_f32_16x16x32_bf16 v[44:47], v[158:161], v[202:205], v[44:47]
	v_mfma_f32_16x16x32_bf16 v[40:43], v[170:173], v[202:205], v[40:43]
	v_mfma_f32_16x16x32_bf16 v[28:31], v[158:161], v[210:213], v[28:31]
	v_mfma_f32_16x16x32_bf16 v[24:27], v[170:173], v[210:213], v[24:27]
	v_mfma_f32_16x16x32_bf16 v[12:15], v[158:161], v[218:221], v[12:15]
	v_mfma_f32_16x16x32_bf16 v[8:11], v[170:173], v[218:221], v[8:11]
	v_mfma_f32_16x16x32_bf16 v[52:55], v[174:177], v[190:193], v[52:55]
	v_mfma_f32_16x16x32_bf16 v[48:51], v[182:185], v[190:193], v[48:51]
	v_mfma_f32_16x16x32_bf16 v[36:39], v[174:177], v[198:201], v[36:39]
	v_mfma_f32_16x16x32_bf16 v[32:35], v[182:185], v[198:201], v[32:35]
	v_mfma_f32_16x16x32_bf16 v[20:23], v[174:177], v[206:209], v[20:23]
	v_mfma_f32_16x16x32_bf16 v[16:19], v[182:185], v[206:209], v[16:19]
	v_mfma_f32_16x16x32_bf16 v[4:7], v[174:177], v[214:217], v[4:7]
	v_mfma_f32_16x16x32_bf16 v[0:3], v[182:185], v[214:217], v[0:3]
	v_mfma_f32_16x16x32_bf16 v[52:55], v[178:181], v[194:197], v[52:55]
	v_mfma_f32_16x16x32_bf16 v[48:51], v[186:189], v[194:197], v[48:51]
	v_mfma_f32_16x16x32_bf16 v[36:39], v[178:181], v[202:205], v[36:39]
	v_mfma_f32_16x16x32_bf16 v[32:35], v[186:189], v[202:205], v[32:35]
	v_mfma_f32_16x16x32_bf16 v[20:23], v[178:181], v[210:213], v[20:23]
	v_mfma_f32_16x16x32_bf16 v[16:19], v[186:189], v[210:213], v[16:19]
	v_mfma_f32_16x16x32_bf16 v[4:7], v[178:181], v[218:221], v[4:7]
	v_mfma_f32_16x16x32_bf16 v[0:3], v[186:189], v[218:221], v[0:3]
	s_barrier
	s_setprio 1
	s_add_i32 s58, s58, 2
	s_add_u32 s0, s0, 0x100
	s_addc_u32 s1, s1, 0
	s_add_u32 s56, s56, 0x100
	s_addc_u32 s57, s57, 0
	s_cmp_gt_u32 s58, 13
	s_cbranch_scc0 .LBB0_829
	s_and_b64 vcc, exec, s[16:17]
	s_cbranch_vccz .LBB0_832
	s_barrier

; #define PG8_STAGE(bufoff, gbase, voff) do { _Pragma("unroll") for (int _i = 0; _i < 2; ++_i) \
;         __builtin_amdgcn_global_load_lds((const unsigned*)((const char*)(gbase) + (voff)[_i]), (PG8_LAS unsigned*)(lds + (bufoff) + ldsw + _i * 8192), 16, 0, 0); } while (0)
; #define PG8_LDA(dst, b, h) do { _Pragma("unroll") for (int m = 0; m < 4; ++m) _Pragma("unroll") for (int k = 0; k < 2; ++k) dst[m][k] = *(const PG8_LAS bf16x8*)(lds + PG8_SA(b, h) + aoff + m * 2048 + k * 1024); } while (0)
; #define PG8_LDB(dst, b, h) do { _Pragma("unroll") for (int n = 0; n < 2; ++n) _Pragma("unroll") for (int k = 0; k < 2; ++k) dst[n][k] = *(const PG8_LAS bf16x8*)(lds + PG8_SB(b, h) + boff + n * 2048 + k * 1024); } while (0)
; #define PG8_MMA(ai, bj, At, Bt) do { __builtin_amdgcn_s_setprio(1); _Pragma("unroll") for (int m = 0; m < 4; ++m) _Pragma("unroll") for (int n = 0; n < 2; ++n) _Pragma("unroll") for (int k = 0; k < 2; ++k) \
;         acc[ai][bj][m][n] = __builtin_amdgcn_mfma_f32_16x16x32_bf16(Bt[n][k], At[m][k], acc[ai][bj][m][n], 0, 0, 0); __builtin_amdgcn_s_setprio(0); } while (0)
; #define PG8_WAIT_V(n) asm volatile("s_waitcnt vmcnt(" #n ")" ::: "memory")
; #define PG8_WAIT_L(n) asm volatile("s_waitcnt lgkmcnt(" #n ")" ::: "memory")
; #define PG8_BAR __builtin_amdgcn_s_barrier()
; #define PG8_SCHED __builtin_amdgcn_sched_barrier(0)
; template <class Epi, class Sched, bool ALIGN_EPI = false, bool SP2 = false>
; __device__ __forceinline__ void gemm_phase(PG8_LAS unsigned char* lds, const Gemm g, const Sched& S, const Epi& E) {
;     ...
;             PG8_LDB(B0, 0, 0); PG8_LDB(B1, 0, 1); PG8_SCHED; PG8_LDA(At, 0, 0); PG8_STAGE(PG8_SA(1, 1), a1 + hstepA, voffA);
;             PG8_WAIT_V(8); PG8_WAIT_L(0); PG8_BAR; PG8_MMA(0, 0, At, B0); PG8_MMA(0, 1, At, B1); PG8_BAR; PG8_SCHED;
;     ...
; #pragma unroll
;         for (int a = 0; a < 2; ++a)
; #pragma unroll
;             for (int b = 0; b < 2; ++b)
; #pragma unroll
;                 for (int m = 0; m < 4; ++m)
; #pragma unroll
;                     for (int n = 0; n < 2; ++n) acc[a][b][m][n] = (f32x4){0.f, 0.f, 0.f, 0.f};
;         cur = nxt; cA = nA; cB = nB; ++ui;
.LBB0_847:
	s_ashr_i32 s21, s20, 31
	s_lshl_b64 s[30:31], s[20:21], 19
	v_readlane_b32 s40, v240, 12
	v_readlane_b32 s41, v240, 13
	s_add_u32 s40, s40, s30
	s_addc_u32 s41, s41, s31
	s_and_b64 s[0:1], s[0:1], exec
	s_cselect_b32 s21, s41, s43
	s_cselect_b32 s30, s40, s42
	s_add_u32 s0, s44, 0x240080
	s_addc_u32 s1, s45, 0
	s_add_u32 s31, s42, 0x100
	v_mov_b64_e32 v[0:1], 0
	s_addc_u32 s34, s43, 0
	s_mov_b32 s58, -2
	v_mov_b64_e32 v[2:3], 0
	v_mov_b64_e32 v[4:5], 0
	v_mov_b64_e32 v[6:7], 0
	v_mov_b64_e32 v[16:17], 0
	v_mov_b64_e32 v[18:19], 0
	v_mov_b64_e32 v[20:21], 0
	v_mov_b64_e32 v[22:23], 0
	v_mov_b64_e32 v[32:33], 0
	v_mov_b64_e32 v[34:35], 0
	v_mov_b64_e32 v[36:37], 0
	v_mov_b64_e32 v[38:39], 0
	v_mov_b64_e32 v[48:49], 0
	v_mov_b64_e32 v[50:51], 0
	v_mov_b64_e32 v[52:53], 0
	v_mov_b64_e32 v[54:55], 0
	v_mov_b64_e32 v[8:9], 0
	v_mov_b64_e32 v[10:11], 0
	v_mov_b64_e32 v[12:13], 0
	v_mov_b64_e32 v[14:15], 0
	v_mov_b64_e32 v[24:25], 0
	v_mov_b64_e32 v[26:27], 0
	v_mov_b64_e32 v[28:29], 0
	v_mov_b64_e32 v[30:31], 0
	v_mov_b64_e32 v[40:41], 0
	v_mov_b64_e32 v[42:43], 0
	v_mov_b64_e32 v[44:45], 0
	v_mov_b64_e32 v[46:47], 0
	v_mov_b64_e32 v[56:57], 0
	v_mov_b64_e32 v[58:59], 0
	v_mov_b64_e32 v[60:61], 0
	v_mov_b64_e32 v[62:63], 0
	v_mov_b64_e32 v[64:65], 0
	v_mov_b64_e32 v[66:67], 0
	v_mov_b64_e32 v[68:69], 0
	v_mov_b64_e32 v[70:71], 0
	v_mov_b64_e32 v[80:81], 0
	v_mov_b64_e32 v[82:83], 0
	v_mov_b64_e32 v[84:85], 0
	v_mov_b64_e32 v[86:87], 0
	v_mov_b64_e32 v[96:97], 0
	v_mov_b64_e32 v[98:99], 0
	v_mov_b64_e32 v[100:101], 0
	v_mov_b64_e32 v[102:103], 0
	v_mov_b64_e32 v[112:113], 0
	v_mov_b64_e32 v[114:115], 0
	v_mov_b64_e32 v[116:117], 0
	v_mov_b64_e32 v[118:119], 0
	v_mov_b64_e32 v[72:73], 0
	v_mov_b64_e32 v[74:75], 0
	v_mov_b64_e32 v[76:77], 0
	v_mov_b64_e32 v[78:79], 0
	v_mov_b64_e32 v[88:89], 0
	v_mov_b64_e32 v[90:91], 0
	v_mov_b64_e32 v[92:93], 0
	v_mov_b64_e32 v[94:95], 0
	v_mov_b64_e32 v[104:105], 0
	v_mov_b64_e32 v[106:107], 0
	v_mov_b64_e32 v[108:109], 0
	v_mov_b64_e32 v[110:111], 0
	v_mov_b64_e32 v[120:121], 0
	v_mov_b64_e32 v[122:123], 0
	v_mov_b64_e32 v[124:125], 0
	v_mov_b64_e32 v[126:127], 0
	v_add_u32_e32 v241, 0x18000, v153
	v_add_u32_e32 v242, 0x1c000, v153
.LBB0_848:
	ds_read_b128 v[144:147], v155
	ds_read_b128 v[148:151], v155 offset:1024
	ds_read_b128 v[166:169], v155 offset:2048
	ds_read_b128 v[170:173], v155 offset:3072
	ds_read_b128 v[174:177], v156
	ds_read_b128 v[178:181], v156 offset:1024
	ds_read_b128 v[182:185], v156 offset:2048
	ds_read_b128 v[186:189], v156 offset:3072
	s_add_u32 s42, s0, 0xffdc0080
	s_addc_u32 s43, s1, -1
	s_cmp_eq_u32 s58, 12
	s_cselect_b32 s45, s23, s43
	s_cselect_b32 s44, s22, s42
	s_cselect_b32 s43, s21, s34
	s_cselect_b32 s42, s30, s31
	s_add_i32 m0, s46, 0xc000
	ds_read_b128 v[190:193], v157
	ds_read_b128 v[194:197], v157 offset:1024
	ds_read_b128 v[198:201], v157 offset:2048
	ds_read_b128 v[202:205], v157 offset:3072
	ds_read_b128 v[206:209], v157 offset:4096
	ds_read_b128 v[210:213], v157 offset:5120
	ds_read_b128 v[214:217], v157 offset:6144
	ds_read_b128 v[218:221], v157 offset:7168
	global_load_lds_dwordx4 v136, s[0:1]
	s_add_i32 m0, s46, 0xe000
	s_nop 0
	global_load_lds_dwordx4 v138, s[0:1]
	s_waitcnt vmcnt(8)
	s_waitcnt lgkmcnt(0)
	s_setprio 0
	s_barrier
	v_mfma_f32_16x16x32_bf16 v[124:127], v[144:147], v[190:193], v[124:127]
	v_mfma_f32_16x16x32_bf16 v[120:123], v[166:169], v[190:193], v[120:123]
	v_mfma_f32_16x16x32_bf16 v[108:111], v[144:147], v[198:201], v[108:111]
	v_mfma_f32_16x16x32_bf16 v[104:107], v[166:169], v[198:201], v[104:107]
	v_mfma_f32_16x16x32_bf16 v[92:95], v[144:147], v[206:209], v[92:95]
	v_mfma_f32_16x16x32_bf16 v[88:91], v[166:169], v[206:209], v[88:91]
	v_mfma_f32_16x16x32_bf16 v[76:79], v[144:147], v[214:217], v[76:79]
	v_mfma_f32_16x16x32_bf16 v[72:75], v[166:169], v[214:217], v[72:75]
	v_mfma_f32_16x16x32_bf16 v[124:127], v[148:151], v[194:197], v[124:127]
	v_mfma_f32_16x16x32_bf16 v[120:123], v[170:173], v[194:197], v[120:123]
	v_mfma_f32_16x16x32_bf16 v[108:111], v[148:151], v[202:205], v[108:111]
	v_mfma_f32_16x16x32_bf16 v[104:107], v[170:173], v[202:205], v[104:107]
	v_mfma_f32_16x16x32_bf16 v[92:95], v[148:151], v[210:213], v[92:95]
	v_mfma_f32_16x16x32_bf16 v[88:91], v[170:173], v[210:213], v[88:91]
	v_mfma_f32_16x16x32_bf16 v[76:79], v[148:151], v[218:221], v[76:79]
	v_mfma_f32_16x16x32_bf16 v[72:75], v[170:173], v[218:221], v[72:75]
	v_mfma_f32_16x16x32_bf16 v[116:119], v[174:177], v[190:193], v[116:119]
	v_mfma_f32_16x16x32_bf16 v[112:115], v[182:185], v[190:193], v[112:115]
	v_mfma_f32_16x16x32_bf16 v[100:103], v[174:177], v[198:201], v[100:103]
	v_mfma_f32_16x16x32_bf16 v[96:99], v[182:185], v[198:201], v[96:99]
	v_mfma_f32_16x16x32_bf16 v[84:87], v[174:177], v[206:209], v[84:87]
	v_mfma_f32_16x16x32_bf16 v[80:83], v[182:185], v[206:209], v[80:83]
	v_mfma_f32_16x16x32_bf16 v[68:71], v[174:177], v[214:217], v[68:71]
	v_mfma_f32_16x16x32_bf16 v[64:67], v[182:185], v[214:217], v[64:67]
	v_mfma_f32_16x16x32_bf16 v[116:119], v[178:181], v[194:197], v[116:119]
	v_mfma_f32_16x16x32_bf16 v[112:115], v[186:189], v[194:197], v[112:115]
	v_mfma_f32_16x16x32_bf16 v[100:103], v[178:181], v[202:205], v[100:103]
	v_mfma_f32_16x16x32_bf16 v[96:99], v[186:189], v[202:205], v[96:99]
	v_mfma_f32_16x16x32_bf16 v[84:87], v[178:181], v[210:213], v[84:87]
	v_mfma_f32_16x16x32_bf16 v[80:83], v[186:189], v[210:213], v[80:83]
	v_mfma_f32_16x16x32_bf16 v[68:71], v[178:181], v[218:221], v[68:71]
	v_mfma_f32_16x16x32_bf16 v[64:67], v[186:189], v[218:221], v[64:67]
	s_barrier
; #define PG8_STAGE(bufoff, gbase, voff) do { _Pragma("unroll") for (int _i = 0; _i < 2; ++_i) \
;         __builtin_amdgcn_global_load_lds((const unsigned*)((const char*)(gbase) + (voff)[_i]), (PG8_LAS unsigned*)(lds + (bufoff) + ldsw + _i * 8192), 16, 0, 0); } while (0)
; #define PG8_LDA(dst, b, h) do { _Pragma("unroll") for (int m = 0; m < 4; ++m) _Pragma("unroll") for (int k = 0; k < 2; ++k) dst[m][k] = *(const PG8_LAS bf16x8*)(lds + PG8_SA(b, h) + aoff + m * 2048 + k * 1024); } while (0)
; #define PG8_LDB(dst, b, h) do { _Pragma("unroll") for (int n = 0; n < 2; ++n) _Pragma("unroll") for (int k = 0; k < 2; ++k) dst[n][k] = *(const PG8_LAS bf16x8*)(lds + PG8_SB(b, h) + boff + n * 2048 + k * 1024); } while (0)
; #define PG8_MMA(ai, bj, At, Bt) do { __builtin_amdgcn_s_setprio(1); _Pragma("unroll") for (int m = 0; m < 4; ++m) _Pragma("unroll") for (int n = 0; n < 2; ++n) _Pragma("unroll") for (int k = 0; k < 2; ++k) \
;         acc[ai][bj][m][n] = __builtin_amdgcn_mfma_f32_16x16x32_bf16(Bt[n][k], At[m][k], acc[ai][bj][m][n], 0, 0, 0); __builtin_amdgcn_s_setprio(0); } while (0)
; #define PG8_WAIT_V(n) asm volatile("s_waitcnt vmcnt(" #n ")" ::: "memory")
; #define PG8_WAIT_L(n) asm volatile("s_waitcnt lgkmcnt(" #n ")" ::: "memory")
; #define PG8_BAR __builtin_amdgcn_s_barrier()
; #define PG8_SCHED __builtin_amdgcn_sched_barrier(0)
; template <class Epi, class Sched, bool ALIGN_EPI = false, bool SP2 = false>
; __device__ __forceinline__ void gemm_phase(PG8_LAS unsigned char* lds, const Gemm g, const Sched& S, const Epi& E) {
;     ...
;             PG8_LDA(At, 0, 1); PG8_STAGE(PG8_SB(0, 0), b2, voffB); PG8_STAGE(PG8_SB(0, 1), b2 + hstepB, voffB); PG8_STAGE(PG8_SA(0, 0), a2, voffA);
;             PG8_WAIT_V(8); PG8_WAIT_L(0); PG8_BAR; PG8_MMA(1, 0, At, B0); PG8_MMA(1, 1, At, B1); PG8_BAR; PG8_SCHED;
;             PG8_LDB(B0, 1, 0); PG8_LDB(B1, 1, 1); PG8_SCHED; PG8_LDA(At, 1, 0); PG8_STAGE(PG8_SA(0, 1), a2 + hstepA, voffA);
	s_setprio 1
	s_add_u32 s98, s42, s16
	s_addc_u32 s99, s43, s17
	s_add_u32 s100, s44, s16
	s_addc_u32 s101, s45, s17
	s_add_i32 s59, s54, s33
	s_mov_b32 m0, s59
	ds_read_b128 v[190:193], v157 offset:16384
	ds_read_b128 v[194:197], v157 offset:17408
	ds_read_b128 v[198:201], v157 offset:18432
	ds_read_b128 v[202:205], v157 offset:19456
	ds_read_b128 v[206:209], v157 offset:20480
	ds_read_b128 v[210:213], v157 offset:21504
	ds_read_b128 v[214:217], v157 offset:22528
	ds_read_b128 v[218:221], v157 offset:23552
	global_load_lds_dwordx4 v132, s[42:43]
	s_add_i32 m0, s59, 0x2000
	s_add_u32 s60, s42, 0x40000
	s_addc_u32 s61, s43, 0
	s_add_i32 s59, s55, s33
	global_load_lds_dwordx4 v128, s[42:43]
	s_mov_b32 m0, s59
	s_nop 0
	global_load_lds_dwordx4 v132, s[60:61]
	s_add_i32 m0, s59, 0x2000
	s_nop 0
	global_load_lds_dwordx4 v128, s[60:61]
	s_mov_b32 m0, s46
	s_nop 0
	global_load_lds_dwordx4 v134, s[44:45]
	s_mov_b32 m0, s47
	s_nop 0
	global_load_lds_dwordx4 v130, s[44:45]
	s_waitcnt vmcnt(8)
	s_waitcnt lgkmcnt(0)
	s_setprio 0
	s_barrier
	v_mfma_f32_16x16x32_bf16 v[60:63], v[144:147], v[190:193], v[60:63]
	v_mfma_f32_16x16x32_bf16 v[56:59], v[166:169], v[190:193], v[56:59]
	v_mfma_f32_16x16x32_bf16 v[44:47], v[144:147], v[198:201], v[44:47]
	v_mfma_f32_16x16x32_bf16 v[40:43], v[166:169], v[198:201], v[40:43]
	v_mfma_f32_16x16x32_bf16 v[28:31], v[144:147], v[206:209], v[28:31]
	v_mfma_f32_16x16x32_bf16 v[24:27], v[166:169], v[206:209], v[24:27]
	v_mfma_f32_16x16x32_bf16 v[12:15], v[144:147], v[214:217], v[12:15]
	v_mfma_f32_16x16x32_bf16 v[8:11], v[166:169], v[214:217], v[8:11]
	v_mfma_f32_16x16x32_bf16 v[60:63], v[148:151], v[194:197], v[60:63]
	v_mfma_f32_16x16x32_bf16 v[56:59], v[170:173], v[194:197], v[56:59]
	v_mfma_f32_16x16x32_bf16 v[44:47], v[148:151], v[202:205], v[44:47]
	v_mfma_f32_16x16x32_bf16 v[40:43], v[170:173], v[202:205], v[40:43]
	v_mfma_f32_16x16x32_bf16 v[28:31], v[148:151], v[210:213], v[28:31]
	v_mfma_f32_16x16x32_bf16 v[24:27], v[170:173], v[210:213], v[24:27]
	v_mfma_f32_16x16x32_bf16 v[12:15], v[148:151], v[218:221], v[12:15]
	v_mfma_f32_16x16x32_bf16 v[8:11], v[170:173], v[218:221], v[8:11]
	v_mfma_f32_16x16x32_bf16 v[52:55], v[174:177], v[190:193], v[52:55]
	v_mfma_f32_16x16x32_bf16 v[48:51], v[182:185], v[190:193], v[48:51]
	v_mfma_f32_16x16x32_bf16 v[36:39], v[174:177], v[198:201], v[36:39]
	v_mfma_f32_16x16x32_bf16 v[32:35], v[182:185], v[198:201], v[32:35]
	v_mfma_f32_16x16x32_bf16 v[20:23], v[174:177], v[206:209], v[20:23]
	v_mfma_f32_16x16x32_bf16 v[16:19], v[182:185], v[206:209], v[16:19]
	v_mfma_f32_16x16x32_bf16 v[4:7], v[174:177], v[214:217], v[4:7]
	v_mfma_f32_16x16x32_bf16 v[0:3], v[182:185], v[214:217], v[0:3]
	v_mfma_f32_16x16x32_bf16 v[52:55], v[178:181], v[194:197], v[52:55]
	v_mfma_f32_16x16x32_bf16 v[48:51], v[186:189], v[194:197], v[48:51]
	v_mfma_f32_16x16x32_bf16 v[36:39], v[178:181], v[202:205], v[36:39]
	v_mfma_f32_16x16x32_bf16 v[32:35], v[186:189], v[202:205], v[32:35]
	v_mfma_f32_16x16x32_bf16 v[20:23], v[178:181], v[210:213], v[20:23]
	v_mfma_f32_16x16x32_bf16 v[16:19], v[186:189], v[210:213], v[16:19]
	v_mfma_f32_16x16x32_bf16 v[4:7], v[178:181], v[218:221], v[4:7]
	v_mfma_f32_16x16x32_bf16 v[0:3], v[186:189], v[218:221], v[0:3]
	s_barrier
	s_setprio 1
	s_add_i32 s59, 0, 0x18000
	s_add_i32 s60, 0, 0x1c000
	ds_read_b128 v[144:147], v241
	ds_read_b128 v[148:151], v241 offset:1024
	ds_read_b128 v[166:169], v241 offset:2048
	ds_read_b128 v[170:173], v241 offset:3072
	ds_read_b128 v[174:177], v242
	ds_read_b128 v[178:181], v242 offset:1024
	ds_read_b128 v[182:185], v242 offset:2048
	ds_read_b128 v[186:189], v242 offset:3072
	s_add_u32 s44, s44, 0x240000
	s_addc_u32 s45, s45, 0
	s_mov_b32 m0, s48
	ds_read_b128 v[190:193], v157 offset:32768
	ds_read_b128 v[194:197], v157 offset:33792
	ds_read_b128 v[198:201], v157 offset:34816
	ds_read_b128 v[202:205], v157 offset:35840
	ds_read_b128 v[206:209], v157 offset:36864
	ds_read_b128 v[210:213], v157 offset:37888
	ds_read_b128 v[214:217], v157 offset:38912
	ds_read_b128 v[218:221], v157 offset:39936
	global_load_lds_dwordx4 v134, s[44:45]
	s_mov_b32 m0, s49
	s_nop 0
	global_load_lds_dwordx4 v130, s[44:45]
	s_waitcnt vmcnt(8)
	s_waitcnt lgkmcnt(0)
	s_setprio 0
	s_barrier
; #define PG8_STAGE(bufoff, gbase, voff) do { _Pragma("unroll") for (int _i = 0; _i < 2; ++_i) \
;         __builtin_amdgcn_global_load_lds((const unsigned*)((const char*)(gbase) + (voff)[_i]), (PG8_LAS unsigned*)(lds + (bufoff) + ldsw + _i * 8192), 16, 0, 0); } while (0)
; #define PG8_LDA(dst, b, h) do { _Pragma("unroll") for (int m = 0; m < 4; ++m) _Pragma("unroll") for (int k = 0; k < 2; ++k) dst[m][k] = *(const PG8_LAS bf16x8*)(lds + PG8_SA(b, h) + aoff + m * 2048 + k * 1024); } while (0)
; #define PG8_MMA(ai, bj, At, Bt) do { __builtin_amdgcn_s_setprio(1); _Pragma("unroll") for (int m = 0; m < 4; ++m) _Pragma("unroll") for (int n = 0; n < 2; ++n) _Pragma("unroll") for (int k = 0; k < 2; ++k) \
;         acc[ai][bj][m][n] = __builtin_amdgcn_mfma_f32_16x16x32_bf16(Bt[n][k], At[m][k], acc[ai][bj][m][n], 0, 0, 0); __builtin_amdgcn_s_setprio(0); } while (0)
; #define PG8_WAIT_V(n) asm volatile("s_waitcnt vmcnt(" #n ")" ::: "memory")
; #define PG8_WAIT_L(n) asm volatile("s_waitcnt lgkmcnt(" #n ")" ::: "memory")
; #define PG8_BAR __builtin_amdgcn_s_barrier()
; #define PG8_SCHED __builtin_amdgcn_sched_barrier(0)
; template <class Epi, class Sched, bool ALIGN_EPI = false, bool SP2 = false>
; __device__ __forceinline__ void gemm_phase(PG8_LAS unsigned char* lds, const Gemm g, const Sched& S, const Epi& E) {
;     ...
;             PG8_WAIT_V(8); PG8_WAIT_L(0); PG8_BAR; PG8_MMA(0, 0, At, B0); PG8_MMA(0, 1, At, B1); PG8_BAR; PG8_SCHED;
;             PG8_LDA(At, 1, 1); PG8_STAGE(PG8_SB(1, 0), b3, voffB); PG8_STAGE(PG8_SB(1, 1), b3 + hstepB, voffB); PG8_STAGE(PG8_SA(1, 0), a3, voffA);
;             PG8_WAIT_V(8); PG8_WAIT_L(0); PG8_BAR; PG8_MMA(1, 0, At, B0); PG8_MMA(1, 1, At, B1); PG8_BAR; PG8_SCHED;
	v_mfma_f32_16x16x32_bf16 v[124:127], v[144:147], v[190:193], v[124:127]
	v_mfma_f32_16x16x32_bf16 v[120:123], v[166:169], v[190:193], v[120:123]
	v_mfma_f32_16x16x32_bf16 v[108:111], v[144:147], v[198:201], v[108:111]
	v_mfma_f32_16x16x32_bf16 v[104:107], v[166:169], v[198:201], v[104:107]
	v_mfma_f32_16x16x32_bf16 v[92:95], v[144:147], v[206:209], v[92:95]
	v_mfma_f32_16x16x32_bf16 v[88:91], v[166:169], v[206:209], v[88:91]
	v_mfma_f32_16x16x32_bf16 v[76:79], v[144:147], v[214:217], v[76:79]
	v_mfma_f32_16x16x32_bf16 v[72:75], v[166:169], v[214:217], v[72:75]
	v_mfma_f32_16x16x32_bf16 v[124:127], v[148:151], v[194:197], v[124:127]
	v_mfma_f32_16x16x32_bf16 v[120:123], v[170:173], v[194:197], v[120:123]
	v_mfma_f32_16x16x32_bf16 v[108:111], v[148:151], v[202:205], v[108:111]
	v_mfma_f32_16x16x32_bf16 v[104:107], v[170:173], v[202:205], v[104:107]
	v_mfma_f32_16x16x32_bf16 v[92:95], v[148:151], v[210:213], v[92:95]
	v_mfma_f32_16x16x32_bf16 v[88:91], v[170:173], v[210:213], v[88:91]
	v_mfma_f32_16x16x32_bf16 v[76:79], v[148:151], v[218:221], v[76:79]
	v_mfma_f32_16x16x32_bf16 v[72:75], v[170:173], v[218:221], v[72:75]
	v_mfma_f32_16x16x32_bf16 v[116:119], v[174:177], v[190:193], v[116:119]
	v_mfma_f32_16x16x32_bf16 v[112:115], v[182:185], v[190:193], v[112:115]
	v_mfma_f32_16x16x32_bf16 v[100:103], v[174:177], v[198:201], v[100:103]
	v_mfma_f32_16x16x32_bf16 v[96:99], v[182:185], v[198:201], v[96:99]
	v_mfma_f32_16x16x32_bf16 v[84:87], v[174:177], v[206:209], v[84:87]
	v_mfma_f32_16x16x32_bf16 v[80:83], v[182:185], v[206:209], v[80:83]
	v_mfma_f32_16x16x32_bf16 v[68:71], v[174:177], v[214:217], v[68:71]
	v_mfma_f32_16x16x32_bf16 v[64:67], v[182:185], v[214:217], v[64:67]
	v_mfma_f32_16x16x32_bf16 v[116:119], v[178:181], v[194:197], v[116:119]
	v_mfma_f32_16x16x32_bf16 v[112:115], v[186:189], v[194:197], v[112:115]
	v_mfma_f32_16x16x32_bf16 v[100:103], v[178:181], v[202:205], v[100:103]
	v_mfma_f32_16x16x32_bf16 v[96:99], v[186:189], v[202:205], v[96:99]
	v_mfma_f32_16x16x32_bf16 v[84:87], v[178:181], v[210:213], v[84:87]
	v_mfma_f32_16x16x32_bf16 v[80:83], v[186:189], v[210:213], v[80:83]
	v_mfma_f32_16x16x32_bf16 v[68:71], v[178:181], v[218:221], v[68:71]
	v_mfma_f32_16x16x32_bf16 v[64:67], v[186:189], v[218:221], v[64:67]
	s_barrier
	s_setprio 1
	s_add_i32 s44, s59, s33
	s_mov_b32 m0, s44
	ds_read_b128 v[190:193], v157 offset:49152
	ds_read_b128 v[194:197], v157 offset:50176
	ds_read_b128 v[198:201], v157 offset:51200
	ds_read_b128 v[202:205], v157 offset:52224
	ds_read_b128 v[206:209], v157 offset:53248
	ds_read_b128 v[210:213], v157 offset:54272
	ds_read_b128 v[214:217], v157 offset:55296
	ds_read_b128 v[218:221], v157 offset:56320
	global_load_lds_dwordx4 v132, s[98:99]
	s_add_i32 m0, s44, 0x2000
	s_add_u32 s42, s42, 0x40080
	s_addc_u32 s43, s43, 0
	s_add_i32 s44, s60, s33
	global_load_lds_dwordx4 v128, s[98:99]
	s_mov_b32 m0, s44
	s_nop 0
	global_load_lds_dwordx4 v132, s[42:43]
	s_add_i32 m0, s44, 0x2000
	s_nop 0
	global_load_lds_dwordx4 v128, s[42:43]
	s_mov_b32 m0, s52
	s_nop 0
	global_load_lds_dwordx4 v134, s[100:101]
	s_mov_b32 m0, s53
	s_nop 0
	global_load_lds_dwordx4 v130, s[100:101]
	s_waitcnt vmcnt(8)
	s_waitcnt lgkmcnt(0)
	s_setprio 0
	s_barrier
	v_mfma_f32_16x16x32_bf16 v[60:63], v[144:147], v[190:193], v[60:63]
	v_mfma_f32_16x16x32_bf16 v[56:59], v[166:169], v[190:193], v[56:59]
	v_mfma_f32_16x16x32_bf16 v[44:47], v[144:147], v[198:201], v[44:47]
	v_mfma_f32_16x16x32_bf16 v[40:43], v[166:169], v[198:201], v[40:43]
	v_mfma_f32_16x16x32_bf16 v[28:31], v[144:147], v[206:209], v[28:31]
	v_mfma_f32_16x16x32_bf16 v[24:27], v[166:169], v[206:209], v[24:27]
	v_mfma_f32_16x16x32_bf16 v[12:15], v[144:147], v[214:217], v[12:15]
	v_mfma_f32_16x16x32_bf16 v[8:11], v[166:169], v[214:217], v[8:11]
	v_mfma_f32_16x16x32_bf16 v[60:63], v[148:151], v[194:197], v[60:63]
	v_mfma_f32_16x16x32_bf16 v[56:59], v[170:173], v[194:197], v[56:59]
	v_mfma_f32_16x16x32_bf16 v[44:47], v[148:151], v[202:205], v[44:47]
	v_mfma_f32_16x16x32_bf16 v[40:43], v[170:173], v[202:205], v[40:43]
	v_mfma_f32_16x16x32_bf16 v[28:31], v[148:151], v[210:213], v[28:31]
	v_mfma_f32_16x16x32_bf16 v[24:27], v[170:173], v[210:213], v[24:27]
	v_mfma_f32_16x16x32_bf16 v[12:15], v[148:151], v[218:221], v[12:15]
	v_mfma_f32_16x16x32_bf16 v[8:11], v[170:173], v[218:221], v[8:11]
	v_mfma_f32_16x16x32_bf16 v[52:55], v[174:177], v[190:193], v[52:55]
	v_mfma_f32_16x16x32_bf16 v[48:51], v[182:185], v[190:193], v[48:51]
	v_mfma_f32_16x16x32_bf16 v[36:39], v[174:177], v[198:201], v[36:39]
	v_mfma_f32_16x16x32_bf16 v[32:35], v[182:185], v[198:201], v[32:35]
	v_mfma_f32_16x16x32_bf16 v[20:23], v[174:177], v[206:209], v[20:23]
	v_mfma_f32_16x16x32_bf16 v[16:19], v[182:185], v[206:209], v[16:19]
	v_mfma_f32_16x16x32_bf16 v[4:7], v[174:177], v[214:217], v[4:7]
	v_mfma_f32_16x16x32_bf16 v[0:3], v[182:185], v[214:217], v[0:3]
	v_mfma_f32_16x16x32_bf16 v[52:55], v[178:181], v[194:197], v[52:55]
	v_mfma_f32_16x16x32_bf16 v[48:51], v[186:189], v[194:197], v[48:51]
	v_mfma_f32_16x16x32_bf16 v[36:39], v[178:181], v[202:205], v[36:39]
	v_mfma_f32_16x16x32_bf16 v[32:35], v[186:189], v[202:205], v[32:35]
	v_mfma_f32_16x16x32_bf16 v[20:23], v[178:181], v[210:213], v[20:23]
	v_mfma_f32_16x16x32_bf16 v[16:19], v[186:189], v[210:213], v[16:19]
	v_mfma_f32_16x16x32_bf16 v[4:7], v[178:181], v[218:221], v[4:7]
	v_mfma_f32_16x16x32_bf16 v[0:3], v[186:189], v[218:221], v[0:3]
	s_barrier
	s_setprio 1
	s_add_i32 s58, s58, 2
	s_add_u32 s0, s0, 0x100
	s_addc_u32 s1, s1, 0
	s_add_u32 s31, s31, 0x100
	s_addc_u32 s34, s34, 0
	s_cmp_gt_u32 s58, 13
	s_cbranch_scc0 .LBB0_848
	s_and_b64 vcc, exec, s[18:19]
	s_cbranch_vccz .LBB0_851
	s_barrier

; #define PG8_STAGE(bufoff, gbase, voff) do { _Pragma("unroll") for (int _i = 0; _i < 2; ++_i) \
;         __builtin_amdgcn_global_load_lds((const unsigned*)((const char*)(gbase) + (voff)[_i]), (PG8_LAS unsigned*)(lds + (bufoff) + ldsw + _i * 8192), 16, 0, 0); } while (0)
; #define PG8_LDA(dst, b, h) do { _Pragma("unroll") for (int m = 0; m < 4; ++m) _Pragma("unroll") for (int k = 0; k < 2; ++k) dst[m][k] = *(const PG8_LAS bf16x8*)(lds + PG8_SA(b, h) + aoff + m * 2048 + k * 1024); } while (0)
; #define PG8_LDB(dst, b, h) do { _Pragma("unroll") for (int n = 0; n < 2; ++n) _Pragma("unroll") for (int k = 0; k < 2; ++k) dst[n][k] = *(const PG8_LAS bf16x8*)(lds + PG8_SB(b, h) + boff + n * 2048 + k * 1024); } while (0)
; #define PG8_MMA(ai, bj, At, Bt) do { __builtin_amdgcn_s_setprio(1); _Pragma("unroll") for (int m = 0; m < 4; ++m) _Pragma("unroll") for (int n = 0; n < 2; ++n) _Pragma("unroll") for (int k = 0; k < 2; ++k) \
;         acc[ai][bj][m][n] = __builtin_amdgcn_mfma_f32_16x16x32_bf16(Bt[n][k], At[m][k], acc[ai][bj][m][n], 0, 0, 0); __builtin_amdgcn_s_setprio(0); } while (0)
; #define PG8_WAIT_V(n) asm volatile("s_waitcnt vmcnt(" #n ")" ::: "memory")
; #define PG8_WAIT_L(n) asm volatile("s_waitcnt lgkmcnt(" #n ")" ::: "memory")
; #define PG8_BAR __builtin_amdgcn_s_barrier()
; #define PG8_SCHED __builtin_amdgcn_sched_barrier(0)
; template <class Epi, class Sched, bool ALIGN_EPI = false, bool SP2 = false>
; __device__ __forceinline__ void gemm_phase(PG8_LAS unsigned char* lds, const Gemm g, const Sched& S, const Epi& E) {
;     ...
;             PG8_LDB(B0, 0, 0); PG8_LDB(B1, 0, 1); PG8_SCHED; PG8_LDA(At, 0, 0); PG8_STAGE(PG8_SA(1, 1), a1 + hstepA, voffA);
;             PG8_WAIT_V(8); PG8_WAIT_L(0); PG8_BAR; PG8_MMA(0, 0, At, B0); PG8_MMA(0, 1, At, B1); PG8_BAR; PG8_SCHED;
;     ...
; #pragma unroll
;         for (int a = 0; a < 2; ++a)
; #pragma unroll
;             for (int b = 0; b < 2; ++b)
; #pragma unroll
;                 for (int m = 0; m < 4; ++m)
; #pragma unroll
;                     for (int n = 0; n < 2; ++n) acc[a][b][m][n] = (f32x4){0.f, 0.f, 0.f, 0.f};
;         cur = nxt; cA = nA; cB = nB; ++ui;
.LBB0_926:
	s_ashr_i32 s45, s44, 31
	s_lshl_b64 s[46:47], s[44:45], 20
	v_readlane_b32 s48, v240, 26
	v_readlane_b32 s49, v240, 27
	s_add_u32 s46, s48, s46
	s_addc_u32 s47, s49, s47
	s_and_b64 s[48:49], s[4:5], exec
	s_cselect_b32 s45, s47, s53
	s_cselect_b32 s65, s46, s52
	s_ashr_i32 s43, s42, 31
	s_lshl_b64 s[48:49], s[42:43], 20
	v_readlane_b32 s56, v240, 16
	v_readlane_b32 s57, v240, 17
	s_add_u32 s48, s56, s48
	s_addc_u32 s49, s57, s49
	s_and_b64 s[56:57], s[4:5], exec
	s_cselect_b32 s43, s49, s55
	s_cselect_b32 s68, s48, s54
	s_add_u32 s52, s52, 0x80080
	s_addc_u32 s53, s53, 0
	s_add_u32 s69, s54, 0x100
	v_mov_b64_e32 v[0:1], 0
	s_addc_u32 s70, s55, 0
	s_mov_b32 s71, -2
	v_mov_b64_e32 v[2:3], 0
	v_mov_b64_e32 v[4:5], 0
	v_mov_b64_e32 v[6:7], 0
	v_mov_b64_e32 v[8:9], 0
	v_mov_b64_e32 v[10:11], 0
	v_mov_b64_e32 v[16:17], 0
	v_mov_b64_e32 v[18:19], 0
	v_mov_b64_e32 v[24:25], 0
	v_mov_b64_e32 v[26:27], 0
	v_mov_b64_e32 v[32:33], 0
	v_mov_b64_e32 v[34:35], 0
	v_mov_b64_e32 v[40:41], 0
	v_mov_b64_e32 v[42:43], 0
	v_mov_b64_e32 v[48:49], 0
	v_mov_b64_e32 v[50:51], 0
	v_mov_b64_e32 v[12:13], 0
	v_mov_b64_e32 v[14:15], 0
	v_mov_b64_e32 v[20:21], 0
	v_mov_b64_e32 v[22:23], 0
	v_mov_b64_e32 v[28:29], 0
	v_mov_b64_e32 v[30:31], 0
	v_mov_b64_e32 v[36:37], 0
	v_mov_b64_e32 v[38:39], 0
	v_mov_b64_e32 v[44:45], 0
	v_mov_b64_e32 v[46:47], 0
	v_mov_b64_e32 v[52:53], 0
	v_mov_b64_e32 v[54:55], 0
	v_mov_b64_e32 v[56:57], 0
	v_mov_b64_e32 v[58:59], 0
	v_mov_b64_e32 v[60:61], 0
	v_mov_b64_e32 v[62:63], 0
	v_mov_b64_e32 v[64:65], 0
	v_mov_b64_e32 v[66:67], 0
	v_mov_b64_e32 v[68:69], 0
	v_mov_b64_e32 v[70:71], 0
	v_mov_b64_e32 v[72:73], 0
	v_mov_b64_e32 v[74:75], 0
	v_mov_b64_e32 v[80:81], 0
	v_mov_b64_e32 v[82:83], 0
	v_mov_b64_e32 v[88:89], 0
	v_mov_b64_e32 v[90:91], 0
	v_mov_b64_e32 v[96:97], 0
	v_mov_b64_e32 v[98:99], 0
	v_mov_b64_e32 v[104:105], 0
	v_mov_b64_e32 v[106:107], 0
	v_mov_b64_e32 v[112:113], 0
	v_mov_b64_e32 v[114:115], 0
	v_mov_b64_e32 v[76:77], 0
	v_mov_b64_e32 v[78:79], 0
	v_mov_b64_e32 v[84:85], 0
	v_mov_b64_e32 v[86:87], 0
	v_mov_b64_e32 v[92:93], 0
	v_mov_b64_e32 v[94:95], 0
	v_mov_b64_e32 v[100:101], 0
	v_mov_b64_e32 v[102:103], 0
	v_mov_b64_e32 v[108:109], 0
	v_mov_b64_e32 v[110:111], 0
	v_mov_b64_e32 v[116:117], 0
	v_mov_b64_e32 v[118:119], 0
	v_mov_b64_e32 v[120:121], 0
	v_mov_b64_e32 v[122:123], 0
	v_mov_b64_e32 v[124:125], 0
	v_mov_b64_e32 v[126:127], 0
	v_add_u32_e32 v241, 0x18000, v151
	v_add_u32_e32 v242, 0x1c000, v151
.LBB0_927:
	ds_read_b128 v[156:159], v153
	ds_read_b128 v[166:169], v153 offset:1024
	ds_read_b128 v[170:173], v153 offset:2048
	ds_read_b128 v[174:177], v153 offset:3072
	ds_read_b128 v[178:181], v154
	ds_read_b128 v[182:185], v154 offset:1024
	ds_read_b128 v[186:189], v154 offset:2048
	ds_read_b128 v[190:193], v154 offset:3072
	s_add_u32 s54, s52, 0xfff80080
	s_addc_u32 s55, s53, -1
	s_cmp_eq_u32 s71, 28
	s_cselect_b32 s57, s45, s55
	s_cselect_b32 s56, s65, s54
	s_cselect_b32 s55, s43, s70
	s_cselect_b32 s54, s68, s69
	s_add_i32 m0, s29, 0xc000
	ds_read_b128 v[194:197], v155
	ds_read_b128 v[198:201], v155 offset:1024
	ds_read_b128 v[202:205], v155 offset:2048
	ds_read_b128 v[206:209], v155 offset:3072
	ds_read_b128 v[210:213], v155 offset:4096
	ds_read_b128 v[214:217], v155 offset:5120
	ds_read_b128 v[218:221], v155 offset:6144
	ds_read_b128 v[222:225], v155 offset:7168
	global_load_lds_dwordx4 v136, s[52:53]
	s_add_i32 m0, s29, 0xe000
	s_nop 0
	global_load_lds_dwordx4 v138, s[52:53]
	s_waitcnt vmcnt(8)
	s_waitcnt lgkmcnt(0)
	s_setprio 0
	s_barrier
	v_mfma_f32_16x16x32_bf16 v[124:127], v[156:159], v[194:197], v[124:127]
	v_mfma_f32_16x16x32_bf16 v[120:123], v[170:173], v[194:197], v[120:123]
	v_mfma_f32_16x16x32_bf16 v[116:119], v[156:159], v[202:205], v[116:119]
	v_mfma_f32_16x16x32_bf16 v[108:111], v[170:173], v[202:205], v[108:111]
	v_mfma_f32_16x16x32_bf16 v[100:103], v[156:159], v[210:213], v[100:103]
	v_mfma_f32_16x16x32_bf16 v[92:95], v[170:173], v[210:213], v[92:95]
	v_mfma_f32_16x16x32_bf16 v[84:87], v[156:159], v[218:221], v[84:87]
	v_mfma_f32_16x16x32_bf16 v[76:79], v[170:173], v[218:221], v[76:79]
	v_mfma_f32_16x16x32_bf16 v[124:127], v[166:169], v[198:201], v[124:127]
	v_mfma_f32_16x16x32_bf16 v[120:123], v[174:177], v[198:201], v[120:123]
	v_mfma_f32_16x16x32_bf16 v[116:119], v[166:169], v[206:209], v[116:119]
	v_mfma_f32_16x16x32_bf16 v[108:111], v[174:177], v[206:209], v[108:111]
	v_mfma_f32_16x16x32_bf16 v[100:103], v[166:169], v[214:217], v[100:103]
	v_mfma_f32_16x16x32_bf16 v[92:95], v[174:177], v[214:217], v[92:95]
	v_mfma_f32_16x16x32_bf16 v[84:87], v[166:169], v[222:225], v[84:87]
	v_mfma_f32_16x16x32_bf16 v[76:79], v[174:177], v[222:225], v[76:79]
	v_mfma_f32_16x16x32_bf16 v[112:115], v[178:181], v[194:197], v[112:115]
	v_mfma_f32_16x16x32_bf16 v[104:107], v[186:189], v[194:197], v[104:107]
	v_mfma_f32_16x16x32_bf16 v[96:99], v[178:181], v[202:205], v[96:99]
	v_mfma_f32_16x16x32_bf16 v[88:91], v[186:189], v[202:205], v[88:91]
	v_mfma_f32_16x16x32_bf16 v[80:83], v[178:181], v[210:213], v[80:83]
	v_mfma_f32_16x16x32_bf16 v[72:75], v[186:189], v[210:213], v[72:75]
	v_mfma_f32_16x16x32_bf16 v[68:71], v[178:181], v[218:221], v[68:71]
	v_mfma_f32_16x16x32_bf16 v[64:67], v[186:189], v[218:221], v[64:67]
	v_mfma_f32_16x16x32_bf16 v[112:115], v[182:185], v[198:201], v[112:115]
	v_mfma_f32_16x16x32_bf16 v[104:107], v[190:193], v[198:201], v[104:107]
	v_mfma_f32_16x16x32_bf16 v[96:99], v[182:185], v[206:209], v[96:99]
	v_mfma_f32_16x16x32_bf16 v[88:91], v[190:193], v[206:209], v[88:91]
	v_mfma_f32_16x16x32_bf16 v[80:83], v[182:185], v[214:217], v[80:83]
	v_mfma_f32_16x16x32_bf16 v[72:75], v[190:193], v[214:217], v[72:75]
	v_mfma_f32_16x16x32_bf16 v[68:71], v[182:185], v[222:225], v[68:71]
	v_mfma_f32_16x16x32_bf16 v[64:67], v[190:193], v[222:225], v[64:67]
	s_barrier
; #define PG8_STAGE(bufoff, gbase, voff) do { _Pragma("unroll") for (int _i = 0; _i < 2; ++_i) \
;         __builtin_amdgcn_global_load_lds((const unsigned*)((const char*)(gbase) + (voff)[_i]), (PG8_LAS unsigned*)(lds + (bufoff) + ldsw + _i * 8192), 16, 0, 0); } while (0)
; #define PG8_LDA(dst, b, h) do { _Pragma("unroll") for (int m = 0; m < 4; ++m) _Pragma("unroll") for (int k = 0; k < 2; ++k) dst[m][k] = *(const PG8_LAS bf16x8*)(lds + PG8_SA(b, h) + aoff + m * 2048 + k * 1024); } while (0)
; #define PG8_LDB(dst, b, h) do { _Pragma("unroll") for (int n = 0; n < 2; ++n) _Pragma("unroll") for (int k = 0; k < 2; ++k) dst[n][k] = *(const PG8_LAS bf16x8*)(lds + PG8_SB(b, h) + boff + n * 2048 + k * 1024); } while (0)
; #define PG8_MMA(ai, bj, At, Bt) do { __builtin_amdgcn_s_setprio(1); _Pragma("unroll") for (int m = 0; m < 4; ++m) _Pragma("unroll") for (int n = 0; n < 2; ++n) _Pragma("unroll") for (int k = 0; k < 2; ++k) \
;         acc[ai][bj][m][n] = __builtin_amdgcn_mfma_f32_16x16x32_bf16(Bt[n][k], At[m][k], acc[ai][bj][m][n], 0, 0, 0); __builtin_amdgcn_s_setprio(0); } while (0)
; #define PG8_WAIT_V(n) asm volatile("s_waitcnt vmcnt(" #n ")" ::: "memory")
; #define PG8_WAIT_L(n) asm volatile("s_waitcnt lgkmcnt(" #n ")" ::: "memory")
; #define PG8_BAR __builtin_amdgcn_s_barrier()
; #define PG8_SCHED __builtin_amdgcn_sched_barrier(0)
; template <class Epi, class Sched, bool ALIGN_EPI = false, bool SP2 = false>
; __device__ __forceinline__ void gemm_phase(PG8_LAS unsigned char* lds, const Gemm g, const Sched& S, const Epi& E) {
;     ...
;             PG8_LDA(At, 0, 1); PG8_STAGE(PG8_SB(0, 0), b2, voffB); PG8_STAGE(PG8_SB(0, 1), b2 + hstepB, voffB); PG8_STAGE(PG8_SA(0, 0), a2, voffA);
;             PG8_WAIT_V(8); PG8_WAIT_L(0); PG8_BAR; PG8_MMA(1, 0, At, B0); PG8_MMA(1, 1, At, B1); PG8_BAR; PG8_SCHED;
;             PG8_LDB(B0, 1, 0); PG8_LDB(B1, 1, 1); PG8_SCHED; PG8_LDA(At, 1, 0); PG8_STAGE(PG8_SA(0, 1), a2 + hstepA, voffA);
	s_setprio 1
	s_add_u32 s98, s54, s16
	s_addc_u32 s99, s55, s17
	s_add_u32 s100, s56, s16
	s_addc_u32 s101, s57, s17
	s_add_i32 s72, s58, s28
	s_mov_b32 m0, s72
	ds_read_b128 v[194:197], v155 offset:16384
	ds_read_b128 v[198:201], v155 offset:17408
	ds_read_b128 v[202:205], v155 offset:18432
	ds_read_b128 v[206:209], v155 offset:19456
	ds_read_b128 v[210:213], v155 offset:20480
	ds_read_b128 v[214:217], v155 offset:21504
	ds_read_b128 v[218:221], v155 offset:22528
	ds_read_b128 v[222:225], v155 offset:23552
	global_load_lds_dwordx4 v130, s[54:55]
	s_add_i32 m0, s72, 0x2000
	s_add_u32 s72, s54, 0x80000
	s_addc_u32 s73, s55, 0
	s_add_i32 s74, s59, s28
	global_load_lds_dwordx4 v134, s[54:55]
	s_mov_b32 m0, s74
	s_nop 0
	global_load_lds_dwordx4 v130, s[72:73]
	s_add_i32 m0, s74, 0x2000
	s_nop 0
	global_load_lds_dwordx4 v134, s[72:73]
	s_mov_b32 m0, s29
	s_nop 0
	global_load_lds_dwordx4 v128, s[56:57]
	s_mov_b32 m0, s30
	s_nop 0
	global_load_lds_dwordx4 v132, s[56:57]
	s_waitcnt vmcnt(8)
	s_waitcnt lgkmcnt(0)
	s_setprio 0
	s_barrier
	v_mfma_f32_16x16x32_bf16 v[60:63], v[156:159], v[194:197], v[60:63]
	v_mfma_f32_16x16x32_bf16 v[56:59], v[170:173], v[194:197], v[56:59]
	v_mfma_f32_16x16x32_bf16 v[52:55], v[156:159], v[202:205], v[52:55]
	v_mfma_f32_16x16x32_bf16 v[44:47], v[170:173], v[202:205], v[44:47]
	v_mfma_f32_16x16x32_bf16 v[36:39], v[156:159], v[210:213], v[36:39]
	v_mfma_f32_16x16x32_bf16 v[28:31], v[170:173], v[210:213], v[28:31]
	v_mfma_f32_16x16x32_bf16 v[20:23], v[156:159], v[218:221], v[20:23]
	v_mfma_f32_16x16x32_bf16 v[12:15], v[170:173], v[218:221], v[12:15]
	v_mfma_f32_16x16x32_bf16 v[60:63], v[166:169], v[198:201], v[60:63]
	v_mfma_f32_16x16x32_bf16 v[56:59], v[174:177], v[198:201], v[56:59]
	v_mfma_f32_16x16x32_bf16 v[52:55], v[166:169], v[206:209], v[52:55]
	v_mfma_f32_16x16x32_bf16 v[44:47], v[174:177], v[206:209], v[44:47]
	v_mfma_f32_16x16x32_bf16 v[36:39], v[166:169], v[214:217], v[36:39]
	v_mfma_f32_16x16x32_bf16 v[28:31], v[174:177], v[214:217], v[28:31]
	v_mfma_f32_16x16x32_bf16 v[20:23], v[166:169], v[222:225], v[20:23]
	v_mfma_f32_16x16x32_bf16 v[12:15], v[174:177], v[222:225], v[12:15]
	v_mfma_f32_16x16x32_bf16 v[48:51], v[178:181], v[194:197], v[48:51]
	v_mfma_f32_16x16x32_bf16 v[40:43], v[186:189], v[194:197], v[40:43]
	v_mfma_f32_16x16x32_bf16 v[32:35], v[178:181], v[202:205], v[32:35]
	v_mfma_f32_16x16x32_bf16 v[24:27], v[186:189], v[202:205], v[24:27]
	v_mfma_f32_16x16x32_bf16 v[16:19], v[178:181], v[210:213], v[16:19]
	v_mfma_f32_16x16x32_bf16 v[8:11], v[186:189], v[210:213], v[8:11]
	v_mfma_f32_16x16x32_bf16 v[4:7], v[178:181], v[218:221], v[4:7]
	v_mfma_f32_16x16x32_bf16 v[0:3], v[186:189], v[218:221], v[0:3]
	v_mfma_f32_16x16x32_bf16 v[48:51], v[182:185], v[198:201], v[48:51]
	v_mfma_f32_16x16x32_bf16 v[40:43], v[190:193], v[198:201], v[40:43]
	v_mfma_f32_16x16x32_bf16 v[32:35], v[182:185], v[206:209], v[32:35]
	v_mfma_f32_16x16x32_bf16 v[24:27], v[190:193], v[206:209], v[24:27]
	v_mfma_f32_16x16x32_bf16 v[16:19], v[182:185], v[214:217], v[16:19]
	v_mfma_f32_16x16x32_bf16 v[8:11], v[190:193], v[214:217], v[8:11]
	v_mfma_f32_16x16x32_bf16 v[4:7], v[182:185], v[222:225], v[4:7]
	v_mfma_f32_16x16x32_bf16 v[0:3], v[190:193], v[222:225], v[0:3]
	s_barrier
	s_setprio 1
	s_add_i32 s72, 0, 0x18000
	s_add_i32 s73, 0, 0x1c000
	ds_read_b128 v[156:159], v241
	ds_read_b128 v[166:169], v241 offset:1024
	ds_read_b128 v[170:173], v241 offset:2048
	ds_read_b128 v[174:177], v241 offset:3072
	ds_read_b128 v[178:181], v242
	ds_read_b128 v[182:185], v242 offset:1024
	ds_read_b128 v[186:189], v242 offset:2048
	ds_read_b128 v[190:193], v242 offset:3072
	s_add_u32 s56, s56, 0x80000
	s_addc_u32 s57, s57, 0
	s_mov_b32 m0, s31
	ds_read_b128 v[194:197], v155 offset:32768
	ds_read_b128 v[198:201], v155 offset:33792
	ds_read_b128 v[202:205], v155 offset:34816
	ds_read_b128 v[206:209], v155 offset:35840
	ds_read_b128 v[210:213], v155 offset:36864
	ds_read_b128 v[214:217], v155 offset:37888
	ds_read_b128 v[218:221], v155 offset:38912
	ds_read_b128 v[222:225], v155 offset:39936
	global_load_lds_dwordx4 v128, s[56:57]
	s_mov_b32 m0, s33
	s_nop 0
	global_load_lds_dwordx4 v132, s[56:57]
	s_waitcnt vmcnt(8)
	s_waitcnt lgkmcnt(0)
	s_setprio 0
	s_barrier
; #define PG8_STAGE(bufoff, gbase, voff) do { _Pragma("unroll") for (int _i = 0; _i < 2; ++_i) \
;         __builtin_amdgcn_global_load_lds((const unsigned*)((const char*)(gbase) + (voff)[_i]), (PG8_LAS unsigned*)(lds + (bufoff) + ldsw + _i * 8192), 16, 0, 0); } while (0)
; #define PG8_LDA(dst, b, h) do { _Pragma("unroll") for (int m = 0; m < 4; ++m) _Pragma("unroll") for (int k = 0; k < 2; ++k) dst[m][k] = *(const PG8_LAS bf16x8*)(lds + PG8_SA(b, h) + aoff + m * 2048 + k * 1024); } while (0)
; #define PG8_MMA(ai, bj, At, Bt) do { __builtin_amdgcn_s_setprio(1); _Pragma("unroll") for (int m = 0; m < 4; ++m) _Pragma("unroll") for (int n = 0; n < 2; ++n) _Pragma("unroll") for (int k = 0; k < 2; ++k) \
;         acc[ai][bj][m][n] = __builtin_amdgcn_mfma_f32_16x16x32_bf16(Bt[n][k], At[m][k], acc[ai][bj][m][n], 0, 0, 0); __builtin_amdgcn_s_setprio(0); } while (0)
; #define PG8_WAIT_V(n) asm volatile("s_waitcnt vmcnt(" #n ")" ::: "memory")
; #define PG8_WAIT_L(n) asm volatile("s_waitcnt lgkmcnt(" #n ")" ::: "memory")
; #define PG8_BAR __builtin_amdgcn_s_barrier()
; #define PG8_SCHED __builtin_amdgcn_sched_barrier(0)
; template <class Epi, class Sched, bool ALIGN_EPI = false, bool SP2 = false>
; __device__ __forceinline__ void gemm_phase(PG8_LAS unsigned char* lds, const Gemm g, const Sched& S, const Epi& E) {
;     ...
;             PG8_WAIT_V(8); PG8_WAIT_L(0); PG8_BAR; PG8_MMA(0, 0, At, B0); PG8_MMA(0, 1, At, B1); PG8_BAR; PG8_SCHED;
;             PG8_LDA(At, 1, 1); PG8_STAGE(PG8_SB(1, 0), b3, voffB); PG8_STAGE(PG8_SB(1, 1), b3 + hstepB, voffB); PG8_STAGE(PG8_SA(1, 0), a3, voffA);
;             PG8_WAIT_V(8); PG8_WAIT_L(0); PG8_BAR; PG8_MMA(1, 0, At, B0); PG8_MMA(1, 1, At, B1); PG8_BAR; PG8_SCHED;
	v_mfma_f32_16x16x32_bf16 v[124:127], v[156:159], v[194:197], v[124:127]
	v_mfma_f32_16x16x32_bf16 v[120:123], v[170:173], v[194:197], v[120:123]
	v_mfma_f32_16x16x32_bf16 v[116:119], v[156:159], v[202:205], v[116:119]
	v_mfma_f32_16x16x32_bf16 v[108:111], v[170:173], v[202:205], v[108:111]
	v_mfma_f32_16x16x32_bf16 v[100:103], v[156:159], v[210:213], v[100:103]
	v_mfma_f32_16x16x32_bf16 v[92:95], v[170:173], v[210:213], v[92:95]
	v_mfma_f32_16x16x32_bf16 v[84:87], v[156:159], v[218:221], v[84:87]
	v_mfma_f32_16x16x32_bf16 v[76:79], v[170:173], v[218:221], v[76:79]
	v_mfma_f32_16x16x32_bf16 v[124:127], v[166:169], v[198:201], v[124:127]
	v_mfma_f32_16x16x32_bf16 v[120:123], v[174:177], v[198:201], v[120:123]
	v_mfma_f32_16x16x32_bf16 v[116:119], v[166:169], v[206:209], v[116:119]
	v_mfma_f32_16x16x32_bf16 v[108:111], v[174:177], v[206:209], v[108:111]
	v_mfma_f32_16x16x32_bf16 v[100:103], v[166:169], v[214:217], v[100:103]
	v_mfma_f32_16x16x32_bf16 v[92:95], v[174:177], v[214:217], v[92:95]
	v_mfma_f32_16x16x32_bf16 v[84:87], v[166:169], v[222:225], v[84:87]
	v_mfma_f32_16x16x32_bf16 v[76:79], v[174:177], v[222:225], v[76:79]
	v_mfma_f32_16x16x32_bf16 v[112:115], v[178:181], v[194:197], v[112:115]
	v_mfma_f32_16x16x32_bf16 v[104:107], v[186:189], v[194:197], v[104:107]
	v_mfma_f32_16x16x32_bf16 v[96:99], v[178:181], v[202:205], v[96:99]
	v_mfma_f32_16x16x32_bf16 v[88:91], v[186:189], v[202:205], v[88:91]
	v_mfma_f32_16x16x32_bf16 v[80:83], v[178:181], v[210:213], v[80:83]
	v_mfma_f32_16x16x32_bf16 v[72:75], v[186:189], v[210:213], v[72:75]
	v_mfma_f32_16x16x32_bf16 v[68:71], v[178:181], v[218:221], v[68:71]
	v_mfma_f32_16x16x32_bf16 v[64:67], v[186:189], v[218:221], v[64:67]
	v_mfma_f32_16x16x32_bf16 v[112:115], v[182:185], v[198:201], v[112:115]
	v_mfma_f32_16x16x32_bf16 v[104:107], v[190:193], v[198:201], v[104:107]
	v_mfma_f32_16x16x32_bf16 v[96:99], v[182:185], v[206:209], v[96:99]
	v_mfma_f32_16x16x32_bf16 v[88:91], v[190:193], v[206:209], v[88:91]
	v_mfma_f32_16x16x32_bf16 v[80:83], v[182:185], v[214:217], v[80:83]
	v_mfma_f32_16x16x32_bf16 v[72:75], v[190:193], v[214:217], v[72:75]
	v_mfma_f32_16x16x32_bf16 v[68:71], v[182:185], v[222:225], v[68:71]
	v_mfma_f32_16x16x32_bf16 v[64:67], v[190:193], v[222:225], v[64:67]
	s_barrier
	s_setprio 1
	s_add_i32 s56, s72, s28
	s_mov_b32 m0, s56
	ds_read_b128 v[194:197], v155 offset:49152
	ds_read_b128 v[198:201], v155 offset:50176
	ds_read_b128 v[202:205], v155 offset:51200
	ds_read_b128 v[206:209], v155 offset:52224
	ds_read_b128 v[210:213], v155 offset:53248
	ds_read_b128 v[214:217], v155 offset:54272
	ds_read_b128 v[218:221], v155 offset:55296
	ds_read_b128 v[222:225], v155 offset:56320
	global_load_lds_dwordx4 v130, s[98:99]
	s_add_i32 m0, s56, 0x2000
	s_add_u32 s54, s54, 0x80080
	s_addc_u32 s55, s55, 0
	s_add_i32 s56, s73, s28
	global_load_lds_dwordx4 v134, s[98:99]
	s_mov_b32 m0, s56
	s_nop 0
	global_load_lds_dwordx4 v130, s[54:55]
	s_add_i32 m0, s56, 0x2000
	s_nop 0
	global_load_lds_dwordx4 v134, s[54:55]
	s_mov_b32 m0, s35
	s_nop 0
	global_load_lds_dwordx4 v128, s[100:101]
	s_mov_b32 m0, s51
	s_nop 0
	global_load_lds_dwordx4 v132, s[100:101]
	s_waitcnt vmcnt(8)
	s_waitcnt lgkmcnt(0)
	s_setprio 0
	s_barrier
	v_mfma_f32_16x16x32_bf16 v[60:63], v[156:159], v[194:197], v[60:63]
	v_mfma_f32_16x16x32_bf16 v[56:59], v[170:173], v[194:197], v[56:59]
	v_mfma_f32_16x16x32_bf16 v[52:55], v[156:159], v[202:205], v[52:55]
	v_mfma_f32_16x16x32_bf16 v[44:47], v[170:173], v[202:205], v[44:47]
	v_mfma_f32_16x16x32_bf16 v[36:39], v[156:159], v[210:213], v[36:39]
	v_mfma_f32_16x16x32_bf16 v[28:31], v[170:173], v[210:213], v[28:31]
	v_mfma_f32_16x16x32_bf16 v[20:23], v[156:159], v[218:221], v[20:23]
	v_mfma_f32_16x16x32_bf16 v[12:15], v[170:173], v[218:221], v[12:15]
	v_mfma_f32_16x16x32_bf16 v[60:63], v[166:169], v[198:201], v[60:63]
	v_mfma_f32_16x16x32_bf16 v[56:59], v[174:177], v[198:201], v[56:59]
	v_mfma_f32_16x16x32_bf16 v[52:55], v[166:169], v[206:209], v[52:55]
	v_mfma_f32_16x16x32_bf16 v[44:47], v[174:177], v[206:209], v[44:47]
	v_mfma_f32_16x16x32_bf16 v[36:39], v[166:169], v[214:217], v[36:39]
	v_mfma_f32_16x16x32_bf16 v[28:31], v[174:177], v[214:217], v[28:31]
	v_mfma_f32_16x16x32_bf16 v[20:23], v[166:169], v[222:225], v[20:23]
	v_mfma_f32_16x16x32_bf16 v[12:15], v[174:177], v[222:225], v[12:15]
	v_mfma_f32_16x16x32_bf16 v[48:51], v[178:181], v[194:197], v[48:51]
	v_mfma_f32_16x16x32_bf16 v[40:43], v[186:189], v[194:197], v[40:43]
	v_mfma_f32_16x16x32_bf16 v[32:35], v[178:181], v[202:205], v[32:35]
	v_mfma_f32_16x16x32_bf16 v[24:27], v[186:189], v[202:205], v[24:27]
	v_mfma_f32_16x16x32_bf16 v[16:19], v[178:181], v[210:213], v[16:19]
	v_mfma_f32_16x16x32_bf16 v[8:11], v[186:189], v[210:213], v[8:11]
	v_mfma_f32_16x16x32_bf16 v[4:7], v[178:181], v[218:221], v[4:7]
	v_mfma_f32_16x16x32_bf16 v[0:3], v[186:189], v[218:221], v[0:3]
	v_mfma_f32_16x16x32_bf16 v[48:51], v[182:185], v[198:201], v[48:51]
	v_mfma_f32_16x16x32_bf16 v[40:43], v[190:193], v[198:201], v[40:43]
	v_mfma_f32_16x16x32_bf16 v[32:35], v[182:185], v[206:209], v[32:35]
	v_mfma_f32_16x16x32_bf16 v[24:27], v[190:193], v[206:209], v[24:27]
	v_mfma_f32_16x16x32_bf16 v[16:19], v[182:185], v[214:217], v[16:19]
	v_mfma_f32_16x16x32_bf16 v[8:11], v[190:193], v[214:217], v[8:11]
	v_mfma_f32_16x16x32_bf16 v[4:7], v[182:185], v[222:225], v[4:7]
	v_mfma_f32_16x16x32_bf16 v[0:3], v[190:193], v[222:225], v[0:3]
	s_barrier
	s_setprio 1
	s_add_i32 s71, s71, 2
	s_add_u32 s52, s52, 0x100
	s_addc_u32 s53, s53, 0
	s_add_u32 s69, s69, 0x100
	s_addc_u32 s70, s70, 0
	s_cmp_gt_u32 s71, 29
	s_cbranch_scc0 .LBB0_927
	s_and_b64 vcc, exec, s[18:19]
	s_cbranch_vccz .LBB0_930
	s_barrier

; #define PG8_STAGE(bufoff, gbase, voff) do { _Pragma("unroll") for (int _i = 0; _i < 2; ++_i) \
;         __builtin_amdgcn_global_load_lds((const unsigned*)((const char*)(gbase) + (voff)[_i]), (PG8_LAS unsigned*)(lds + (bufoff) + ldsw + _i * 8192), 16, 0, 0); } while (0)
; #define PG8_LDA(dst, b, h) do { _Pragma("unroll") for (int m = 0; m < 4; ++m) _Pragma("unroll") for (int k = 0; k < 2; ++k) dst[m][k] = *(const PG8_LAS bf16x8*)(lds + PG8_SA(b, h) + aoff + m * 2048 + k * 1024); } while (0)
; #define PG8_LDB(dst, b, h) do { _Pragma("unroll") for (int n = 0; n < 2; ++n) _Pragma("unroll") for (int k = 0; k < 2; ++k) dst[n][k] = *(const PG8_LAS bf16x8*)(lds + PG8_SB(b, h) + boff + n * 2048 + k * 1024); } while (0)
; #define PG8_MMA(ai, bj, At, Bt) do { __builtin_amdgcn_s_setprio(1); _Pragma("unroll") for (int m = 0; m < 4; ++m) _Pragma("unroll") for (int n = 0; n < 2; ++n) _Pragma("unroll") for (int k = 0; k < 2; ++k) \
;         acc[ai][bj][m][n] = __builtin_amdgcn_mfma_f32_16x16x32_bf16(Bt[n][k], At[m][k], acc[ai][bj][m][n], 0, 0, 0); __builtin_amdgcn_s_setprio(0); } while (0)
; #define PG8_WAIT_V(n) asm volatile("s_waitcnt vmcnt(" #n ")" ::: "memory")
; #define PG8_BAR __builtin_amdgcn_s_barrier()
; template <class Epi, class Sched, bool ALIGN_EPI = false, bool SP2 = false>
; __device__ __forceinline__ void gemm_phase(PG8_LAS unsigned char* lds, const Gemm g, const Sched& S, const Epi& E) {
;     ...
;             const bool last = (t == nt - 2);
;             const char* a1 = cA + (size_t)(t + 1) * kstep;
;             const char* a2 = last ? nA : cA + (size_t)(t + 2) * kstep; const char* b2 = last ? nB : cB + (size_t)(t + 2) * kstep;
;             const char* a3 = a2 + kstep; const char* b3 = b2 + kstep;
;             if (last && has_next) S.a_ready(nxt);
;             if constexpr (SP2) {
;             PG8_LDB(B0, 0, 0); PG8_LDB(B1, 0, 1); PG8_SCHED; PG8_LDA(At, 0, 0); PG8_STAGE(PG8_SA(1, 1), a1 + hstepA, voffA);
;             PG8_WAIT_V(8); PG8_WAIT_L(0); PG8_BAR; PG8_MMA(0, 0, At, B0); PG8_MMA(0, 1, At, B1); PG8_BAR; PG8_SCHED;
;     ...
; #pragma unroll
;         for (int a = 0; a < 2; ++a)
; #pragma unroll
;             for (int b = 0; b < 2; ++b)
; #pragma unroll
;                 for (int m = 0; m < 4; ++m)
; #pragma unroll
;                     for (int n = 0; n < 2; ++n) acc[a][b][m][n] = (f32x4){0.f, 0.f, 0.f, 0.f};
;         cur = nxt; cA = nA; cB = nB; ++ui;
.LBB0_946:
	v_mov_b64_e32 v[0:1], 0
	s_mov_b32 s19, 0
	s_mov_b64 s[54:55], -1
	s_mov_b64 s[56:57], 0
	v_mov_b64_e32 v[2:3], 0
	v_mov_b64_e32 v[4:5], 0
	v_mov_b64_e32 v[6:7], 0
	v_mov_b64_e32 v[8:9], 0
	v_mov_b64_e32 v[10:11], 0
	v_mov_b64_e32 v[12:13], 0
	v_mov_b64_e32 v[14:15], 0
	v_mov_b64_e32 v[24:25], 0
	v_mov_b64_e32 v[26:27], 0
	v_mov_b64_e32 v[28:29], 0
	v_mov_b64_e32 v[30:31], 0
	v_mov_b64_e32 v[40:41], 0
	v_mov_b64_e32 v[42:43], 0
	v_mov_b64_e32 v[44:45], 0
	v_mov_b64_e32 v[46:47], 0
	v_mov_b64_e32 v[16:17], 0
	v_mov_b64_e32 v[18:19], 0
	v_mov_b64_e32 v[20:21], 0
	v_mov_b64_e32 v[22:23], 0
	v_mov_b64_e32 v[32:33], 0
	v_mov_b64_e32 v[34:35], 0
	v_mov_b64_e32 v[36:37], 0
	v_mov_b64_e32 v[38:39], 0
	v_mov_b64_e32 v[48:49], 0
	v_mov_b64_e32 v[50:51], 0
	v_mov_b64_e32 v[52:53], 0
	v_mov_b64_e32 v[54:55], 0
	v_mov_b64_e32 v[56:57], 0
	v_mov_b64_e32 v[58:59], 0
	v_mov_b64_e32 v[60:61], 0
	v_mov_b64_e32 v[62:63], 0
	v_mov_b64_e32 v[64:65], 0
	v_mov_b64_e32 v[66:67], 0
	v_mov_b64_e32 v[68:69], 0
	v_mov_b64_e32 v[70:71], 0
	v_mov_b64_e32 v[72:73], 0
	v_mov_b64_e32 v[74:75], 0
	v_mov_b64_e32 v[76:77], 0
	v_mov_b64_e32 v[78:79], 0
	v_mov_b64_e32 v[88:89], 0
	v_mov_b64_e32 v[90:91], 0
	v_mov_b64_e32 v[92:93], 0
	v_mov_b64_e32 v[94:95], 0
	v_mov_b64_e32 v[104:105], 0
	v_mov_b64_e32 v[106:107], 0
	v_mov_b64_e32 v[108:109], 0
	v_mov_b64_e32 v[110:111], 0
	v_mov_b64_e32 v[80:81], 0
	v_mov_b64_e32 v[82:83], 0
	v_mov_b64_e32 v[84:85], 0
	v_mov_b64_e32 v[86:87], 0
	v_mov_b64_e32 v[96:97], 0
	v_mov_b64_e32 v[98:99], 0
	v_mov_b64_e32 v[100:101], 0
	v_mov_b64_e32 v[102:103], 0
	v_mov_b64_e32 v[112:113], 0
	v_mov_b64_e32 v[114:115], 0
	v_mov_b64_e32 v[116:117], 0
	v_mov_b64_e32 v[118:119], 0
	v_mov_b64_e32 v[120:121], 0
	v_mov_b64_e32 v[122:123], 0
	v_mov_b64_e32 v[124:125], 0
	v_mov_b64_e32 v[126:127], 0
	v_add_u32_e32 v241, 0x18000, v141
	v_add_u32_e32 v242, 0x1c000, v141
.LBB0_947:
	s_add_u32 s45, s50, s19
	s_addc_u32 s47, s51, 0
	s_add_u32 s49, s45, 0x100
	s_addc_u32 s60, s47, 0
	s_and_b64 s[58:59], s[56:57], exec
	s_cselect_b32 s61, s1, s60
	s_cselect_b32 s60, s0, s49
	s_add_u32 s19, s42, s19
	s_addc_u32 s49, s43, 0
	s_add_u32 s19, s19, 0x100
	s_addc_u32 s49, s49, 0
	s_and_b64 s[56:57], s[56:57], exec
	s_cselect_b32 s63, s53, s49
	s_cselect_b32 s62, s52, s19
	s_add_u32 s68, s45, 0x80080
	ds_read_b128 v[146:149], v143
	ds_read_b128 v[150:153], v143 offset:1024
	ds_read_b128 v[154:157], v143 offset:2048
	ds_read_b128 v[158:161], v143 offset:3072
	ds_read_b128 v[166:169], v144
	ds_read_b128 v[170:173], v144 offset:1024
	ds_read_b128 v[174:177], v144 offset:2048
	ds_read_b128 v[178:181], v144 offset:3072
	s_addc_u32 s69, s47, 0
	s_add_u32 s64, s62, 0x80000
	s_addc_u32 s65, s63, 0
	s_add_i32 s79, s71, s30
	s_add_i32 s78, s79, 0x2000
	s_add_i32 s77, 0, 0x18000
	s_add_i32 s76, 0, 0x1c000
	s_add_u32 s58, s60, 0x80000
	s_addc_u32 s59, s61, 0
	s_add_i32 s49, s77, s30
	s_add_i32 s45, s49, 0x2000
	s_add_u32 s56, s62, 0x80080
	s_addc_u32 s57, s63, 0
	s_add_i32 s47, s76, s30
	s_add_i32 s19, s47, 0x2000
	s_mov_b32 m0, s72
	ds_read_b128 v[182:185], v145
	ds_read_b128 v[186:189], v145 offset:1024
	ds_read_b128 v[190:193], v145 offset:2048
	ds_read_b128 v[194:197], v145 offset:3072
	ds_read_b128 v[198:201], v145 offset:4096
	ds_read_b128 v[202:205], v145 offset:5120
	ds_read_b128 v[206:209], v145 offset:6144
	ds_read_b128 v[210:213], v145 offset:7168
	global_load_lds_dwordx4 v128, s[68:69]
	s_mov_b32 m0, s73
	s_nop 0
	global_load_lds_dwordx4 v132, s[68:69]
	s_waitcnt vmcnt(8)
	s_waitcnt lgkmcnt(0)
	s_setprio 0
	s_barrier
	v_mfma_f32_16x16x32_bf16 v[124:127], v[146:149], v[182:185], v[124:127]
	v_mfma_f32_16x16x32_bf16 v[120:123], v[154:157], v[182:185], v[120:123]
	v_mfma_f32_16x16x32_bf16 v[116:119], v[146:149], v[190:193], v[116:119]
	v_mfma_f32_16x16x32_bf16 v[112:115], v[154:157], v[190:193], v[112:115]
	v_mfma_f32_16x16x32_bf16 v[100:103], v[146:149], v[198:201], v[100:103]
	v_mfma_f32_16x16x32_bf16 v[96:99], v[154:157], v[198:201], v[96:99]
	v_mfma_f32_16x16x32_bf16 v[84:87], v[146:149], v[206:209], v[84:87]
	v_mfma_f32_16x16x32_bf16 v[80:83], v[154:157], v[206:209], v[80:83]
	v_mfma_f32_16x16x32_bf16 v[124:127], v[150:153], v[186:189], v[124:127]
	v_mfma_f32_16x16x32_bf16 v[120:123], v[158:161], v[186:189], v[120:123]
	v_mfma_f32_16x16x32_bf16 v[116:119], v[150:153], v[194:197], v[116:119]
	v_mfma_f32_16x16x32_bf16 v[112:115], v[158:161], v[194:197], v[112:115]
	v_mfma_f32_16x16x32_bf16 v[100:103], v[150:153], v[202:205], v[100:103]
	v_mfma_f32_16x16x32_bf16 v[96:99], v[158:161], v[202:205], v[96:99]
	v_mfma_f32_16x16x32_bf16 v[84:87], v[150:153], v[210:213], v[84:87]
	v_mfma_f32_16x16x32_bf16 v[80:83], v[158:161], v[210:213], v[80:83]
	v_mfma_f32_16x16x32_bf16 v[108:111], v[166:169], v[182:185], v[108:111]
	v_mfma_f32_16x16x32_bf16 v[104:107], v[174:177], v[182:185], v[104:107]
	v_mfma_f32_16x16x32_bf16 v[92:95], v[166:169], v[190:193], v[92:95]
	v_mfma_f32_16x16x32_bf16 v[88:91], v[174:177], v[190:193], v[88:91]
	v_mfma_f32_16x16x32_bf16 v[76:79], v[166:169], v[198:201], v[76:79]
	v_mfma_f32_16x16x32_bf16 v[72:75], v[174:177], v[198:201], v[72:75]
	v_mfma_f32_16x16x32_bf16 v[68:71], v[166:169], v[206:209], v[68:71]
	v_mfma_f32_16x16x32_bf16 v[64:67], v[174:177], v[206:209], v[64:67]
	v_mfma_f32_16x16x32_bf16 v[108:111], v[170:173], v[186:189], v[108:111]
	v_mfma_f32_16x16x32_bf16 v[104:107], v[178:181], v[186:189], v[104:107]
	v_mfma_f32_16x16x32_bf16 v[92:95], v[170:173], v[194:197], v[92:95]
	v_mfma_f32_16x16x32_bf16 v[88:91], v[178:181], v[194:197], v[88:91]
	v_mfma_f32_16x16x32_bf16 v[76:79], v[170:173], v[202:205], v[76:79]
	v_mfma_f32_16x16x32_bf16 v[72:75], v[178:181], v[202:205], v[72:75]
	v_mfma_f32_16x16x32_bf16 v[68:71], v[170:173], v[210:213], v[68:71]
	v_mfma_f32_16x16x32_bf16 v[64:67], v[178:181], v[210:213], v[64:67]
	s_barrier
; #define PG8_STAGE(bufoff, gbase, voff) do { _Pragma("unroll") for (int _i = 0; _i < 2; ++_i) \
;         __builtin_amdgcn_global_load_lds((const unsigned*)((const char*)(gbase) + (voff)[_i]), (PG8_LAS unsigned*)(lds + (bufoff) + ldsw + _i * 8192), 16, 0, 0); } while (0)
; #define PG8_LDA(dst, b, h) do { _Pragma("unroll") for (int m = 0; m < 4; ++m) _Pragma("unroll") for (int k = 0; k < 2; ++k) dst[m][k] = *(const PG8_LAS bf16x8*)(lds + PG8_SA(b, h) + aoff + m * 2048 + k * 1024); } while (0)
; #define PG8_LDB(dst, b, h) do { _Pragma("unroll") for (int n = 0; n < 2; ++n) _Pragma("unroll") for (int k = 0; k < 2; ++k) dst[n][k] = *(const PG8_LAS bf16x8*)(lds + PG8_SB(b, h) + boff + n * 2048 + k * 1024); } while (0)
; #define PG8_MMA(ai, bj, At, Bt) do { __builtin_amdgcn_s_setprio(1); _Pragma("unroll") for (int m = 0; m < 4; ++m) _Pragma("unroll") for (int n = 0; n < 2; ++n) _Pragma("unroll") for (int k = 0; k < 2; ++k) \
;         acc[ai][bj][m][n] = __builtin_amdgcn_mfma_f32_16x16x32_bf16(Bt[n][k], At[m][k], acc[ai][bj][m][n], 0, 0, 0); __builtin_amdgcn_s_setprio(0); } while (0)
; #define PG8_WAIT_V(n) asm volatile("s_waitcnt vmcnt(" #n ")" ::: "memory")
; #define PG8_WAIT_L(n) asm volatile("s_waitcnt lgkmcnt(" #n ")" ::: "memory")
; #define PG8_BAR __builtin_amdgcn_s_barrier()
; #define PG8_SCHED __builtin_amdgcn_sched_barrier(0)
; template <class Epi, class Sched, bool ALIGN_EPI = false, bool SP2 = false>
; __device__ __forceinline__ void gemm_phase(PG8_LAS unsigned char* lds, const Gemm g, const Sched& S, const Epi& E) {
;     ...
;             PG8_LDA(At, 0, 1); PG8_STAGE(PG8_SB(0, 0), b2, voffB); PG8_STAGE(PG8_SB(0, 1), b2 + hstepB, voffB); PG8_STAGE(PG8_SA(0, 0), a2, voffA);
;             PG8_WAIT_V(8); PG8_WAIT_L(0); PG8_BAR; PG8_MMA(1, 0, At, B0); PG8_MMA(1, 1, At, B1); PG8_BAR; PG8_SCHED;
;             PG8_LDB(B0, 1, 0); PG8_LDB(B1, 1, 1); PG8_SCHED; PG8_LDA(At, 1, 0); PG8_STAGE(PG8_SA(0, 1), a2 + hstepA, voffA);
	s_setprio 1
	s_add_u32 s98, s62, s16
	s_addc_u32 s99, s63, s17
	s_add_u32 s100, s60, s16
	s_addc_u32 s101, s61, s17
	s_mov_b32 m0, s74
	ds_read_b128 v[182:185], v145 offset:16384
	ds_read_b128 v[186:189], v145 offset:17408
	ds_read_b128 v[190:193], v145 offset:18432
	ds_read_b128 v[194:197], v145 offset:19456
	ds_read_b128 v[198:201], v145 offset:20480
	ds_read_b128 v[202:205], v145 offset:21504
	ds_read_b128 v[206:209], v145 offset:22528
	ds_read_b128 v[210:213], v145 offset:23552
	global_load_lds_dwordx4 v130, s[62:63]
	s_mov_b32 m0, s75
	s_nop 0
	global_load_lds_dwordx4 v134, s[62:63]
	s_mov_b32 m0, s79
	s_nop 0
	global_load_lds_dwordx4 v130, s[64:65]
	s_mov_b32 m0, s78
	s_nop 0
	global_load_lds_dwordx4 v134, s[64:65]
	s_mov_b32 m0, s21
	s_nop 0
	global_load_lds_dwordx4 v128, s[60:61]
	s_mov_b32 m0, s23
	s_nop 0
	global_load_lds_dwordx4 v132, s[60:61]
	s_waitcnt vmcnt(8)
	s_waitcnt lgkmcnt(0)
	s_setprio 0
	s_barrier
	v_mfma_f32_16x16x32_bf16 v[60:63], v[146:149], v[182:185], v[60:63]
	v_mfma_f32_16x16x32_bf16 v[56:59], v[154:157], v[182:185], v[56:59]
	v_mfma_f32_16x16x32_bf16 v[52:55], v[146:149], v[190:193], v[52:55]
	v_mfma_f32_16x16x32_bf16 v[48:51], v[154:157], v[190:193], v[48:51]
	v_mfma_f32_16x16x32_bf16 v[36:39], v[146:149], v[198:201], v[36:39]
	v_mfma_f32_16x16x32_bf16 v[32:35], v[154:157], v[198:201], v[32:35]
	v_mfma_f32_16x16x32_bf16 v[20:23], v[146:149], v[206:209], v[20:23]
	v_mfma_f32_16x16x32_bf16 v[16:19], v[154:157], v[206:209], v[16:19]
	v_mfma_f32_16x16x32_bf16 v[60:63], v[150:153], v[186:189], v[60:63]
	v_mfma_f32_16x16x32_bf16 v[56:59], v[158:161], v[186:189], v[56:59]
	v_mfma_f32_16x16x32_bf16 v[52:55], v[150:153], v[194:197], v[52:55]
	v_mfma_f32_16x16x32_bf16 v[48:51], v[158:161], v[194:197], v[48:51]
	v_mfma_f32_16x16x32_bf16 v[36:39], v[150:153], v[202:205], v[36:39]
	v_mfma_f32_16x16x32_bf16 v[32:35], v[158:161], v[202:205], v[32:35]
	v_mfma_f32_16x16x32_bf16 v[20:23], v[150:153], v[210:213], v[20:23]
	v_mfma_f32_16x16x32_bf16 v[16:19], v[158:161], v[210:213], v[16:19]
	v_mfma_f32_16x16x32_bf16 v[44:47], v[166:169], v[182:185], v[44:47]
	v_mfma_f32_16x16x32_bf16 v[40:43], v[174:177], v[182:185], v[40:43]
	v_mfma_f32_16x16x32_bf16 v[28:31], v[166:169], v[190:193], v[28:31]
	v_mfma_f32_16x16x32_bf16 v[24:27], v[174:177], v[190:193], v[24:27]
	v_mfma_f32_16x16x32_bf16 v[12:15], v[166:169], v[198:201], v[12:15]
	v_mfma_f32_16x16x32_bf16 v[8:11], v[174:177], v[198:201], v[8:11]
	v_mfma_f32_16x16x32_bf16 v[4:7], v[166:169], v[206:209], v[4:7]
	v_mfma_f32_16x16x32_bf16 v[0:3], v[174:177], v[206:209], v[0:3]
	v_mfma_f32_16x16x32_bf16 v[44:47], v[170:173], v[186:189], v[44:47]
	v_mfma_f32_16x16x32_bf16 v[40:43], v[178:181], v[186:189], v[40:43]
	v_mfma_f32_16x16x32_bf16 v[28:31], v[170:173], v[194:197], v[28:31]
	v_mfma_f32_16x16x32_bf16 v[24:27], v[178:181], v[194:197], v[24:27]
	v_mfma_f32_16x16x32_bf16 v[12:15], v[170:173], v[202:205], v[12:15]
	v_mfma_f32_16x16x32_bf16 v[8:11], v[178:181], v[202:205], v[8:11]
	v_mfma_f32_16x16x32_bf16 v[4:7], v[170:173], v[210:213], v[4:7]
	v_mfma_f32_16x16x32_bf16 v[0:3], v[178:181], v[210:213], v[0:3]
	s_barrier
	s_setprio 1
	ds_read_b128 v[146:149], v241
	ds_read_b128 v[150:153], v241 offset:1024
	ds_read_b128 v[154:157], v241 offset:2048
	ds_read_b128 v[158:161], v241 offset:3072
	ds_read_b128 v[166:169], v242
	ds_read_b128 v[170:173], v242 offset:1024
	ds_read_b128 v[174:177], v242 offset:2048
	ds_read_b128 v[178:181], v242 offset:3072
	s_mov_b32 m0, s31
	ds_read_b128 v[182:185], v145 offset:32768
	ds_read_b128 v[186:189], v145 offset:33792
	ds_read_b128 v[190:193], v145 offset:34816
	ds_read_b128 v[194:197], v145 offset:35840
	ds_read_b128 v[198:201], v145 offset:36864
	ds_read_b128 v[202:205], v145 offset:37888
	ds_read_b128 v[206:209], v145 offset:38912
	ds_read_b128 v[210:213], v145 offset:39936
	global_load_lds_dwordx4 v128, s[58:59]
	s_mov_b32 m0, s33
	s_nop 0
	global_load_lds_dwordx4 v132, s[58:59]
	s_waitcnt vmcnt(8)
	s_waitcnt lgkmcnt(0)
	s_setprio 0
	s_barrier
; #define PG8_STAGE(bufoff, gbase, voff) do { _Pragma("unroll") for (int _i = 0; _i < 2; ++_i) \
;         __builtin_amdgcn_global_load_lds((const unsigned*)((const char*)(gbase) + (voff)[_i]), (PG8_LAS unsigned*)(lds + (bufoff) + ldsw + _i * 8192), 16, 0, 0); } while (0)
; #define PG8_LDA(dst, b, h) do { _Pragma("unroll") for (int m = 0; m < 4; ++m) _Pragma("unroll") for (int k = 0; k < 2; ++k) dst[m][k] = *(const PG8_LAS bf16x8*)(lds + PG8_SA(b, h) + aoff + m * 2048 + k * 1024); } while (0)
; #define PG8_MMA(ai, bj, At, Bt) do { __builtin_amdgcn_s_setprio(1); _Pragma("unroll") for (int m = 0; m < 4; ++m) _Pragma("unroll") for (int n = 0; n < 2; ++n) _Pragma("unroll") for (int k = 0; k < 2; ++k) \
;         acc[ai][bj][m][n] = __builtin_amdgcn_mfma_f32_16x16x32_bf16(Bt[n][k], At[m][k], acc[ai][bj][m][n], 0, 0, 0); __builtin_amdgcn_s_setprio(0); } while (0)
; #define PG8_WAIT_V(n) asm volatile("s_waitcnt vmcnt(" #n ")" ::: "memory")
; #define PG8_WAIT_L(n) asm volatile("s_waitcnt lgkmcnt(" #n ")" ::: "memory")
; #define PG8_BAR __builtin_amdgcn_s_barrier()
; #define PG8_SCHED __builtin_amdgcn_sched_barrier(0)
; template <class Epi, class Sched, bool ALIGN_EPI = false, bool SP2 = false>
; __device__ __forceinline__ void gemm_phase(PG8_LAS unsigned char* lds, const Gemm g, const Sched& S, const Epi& E) {
;     ...
;             PG8_WAIT_V(8); PG8_WAIT_L(0); PG8_BAR; PG8_MMA(0, 0, At, B0); PG8_MMA(0, 1, At, B1); PG8_BAR; PG8_SCHED;
;             PG8_LDA(At, 1, 1); PG8_STAGE(PG8_SB(1, 0), b3, voffB); PG8_STAGE(PG8_SB(1, 1), b3 + hstepB, voffB); PG8_STAGE(PG8_SA(1, 0), a3, voffA);
;             PG8_WAIT_V(8); PG8_WAIT_L(0); PG8_BAR; PG8_MMA(1, 0, At, B0); PG8_MMA(1, 1, At, B1); PG8_BAR; PG8_SCHED;
	v_mfma_f32_16x16x32_bf16 v[124:127], v[146:149], v[182:185], v[124:127]
	v_mfma_f32_16x16x32_bf16 v[120:123], v[154:157], v[182:185], v[120:123]
	v_mfma_f32_16x16x32_bf16 v[116:119], v[146:149], v[190:193], v[116:119]
	v_mfma_f32_16x16x32_bf16 v[112:115], v[154:157], v[190:193], v[112:115]
	v_mfma_f32_16x16x32_bf16 v[100:103], v[146:149], v[198:201], v[100:103]
	v_mfma_f32_16x16x32_bf16 v[96:99], v[154:157], v[198:201], v[96:99]
	v_mfma_f32_16x16x32_bf16 v[84:87], v[146:149], v[206:209], v[84:87]
	v_mfma_f32_16x16x32_bf16 v[80:83], v[154:157], v[206:209], v[80:83]
	v_mfma_f32_16x16x32_bf16 v[124:127], v[150:153], v[186:189], v[124:127]
	v_mfma_f32_16x16x32_bf16 v[120:123], v[158:161], v[186:189], v[120:123]
	v_mfma_f32_16x16x32_bf16 v[116:119], v[150:153], v[194:197], v[116:119]
	v_mfma_f32_16x16x32_bf16 v[112:115], v[158:161], v[194:197], v[112:115]
	v_mfma_f32_16x16x32_bf16 v[100:103], v[150:153], v[202:205], v[100:103]
	v_mfma_f32_16x16x32_bf16 v[96:99], v[158:161], v[202:205], v[96:99]
	v_mfma_f32_16x16x32_bf16 v[84:87], v[150:153], v[210:213], v[84:87]
	v_mfma_f32_16x16x32_bf16 v[80:83], v[158:161], v[210:213], v[80:83]
	v_mfma_f32_16x16x32_bf16 v[108:111], v[166:169], v[182:185], v[108:111]
	v_mfma_f32_16x16x32_bf16 v[104:107], v[174:177], v[182:185], v[104:107]
	v_mfma_f32_16x16x32_bf16 v[92:95], v[166:169], v[190:193], v[92:95]
	v_mfma_f32_16x16x32_bf16 v[88:91], v[174:177], v[190:193], v[88:91]
	v_mfma_f32_16x16x32_bf16 v[76:79], v[166:169], v[198:201], v[76:79]
	v_mfma_f32_16x16x32_bf16 v[72:75], v[174:177], v[198:201], v[72:75]
	v_mfma_f32_16x16x32_bf16 v[68:71], v[166:169], v[206:209], v[68:71]
	v_mfma_f32_16x16x32_bf16 v[64:67], v[174:177], v[206:209], v[64:67]
	v_mfma_f32_16x16x32_bf16 v[108:111], v[170:173], v[186:189], v[108:111]
	v_mfma_f32_16x16x32_bf16 v[104:107], v[178:181], v[186:189], v[104:107]
	v_mfma_f32_16x16x32_bf16 v[92:95], v[170:173], v[194:197], v[92:95]
	v_mfma_f32_16x16x32_bf16 v[88:91], v[178:181], v[194:197], v[88:91]
	v_mfma_f32_16x16x32_bf16 v[76:79], v[170:173], v[202:205], v[76:79]
	v_mfma_f32_16x16x32_bf16 v[72:75], v[178:181], v[202:205], v[72:75]
	v_mfma_f32_16x16x32_bf16 v[68:71], v[170:173], v[210:213], v[68:71]
	v_mfma_f32_16x16x32_bf16 v[64:67], v[178:181], v[210:213], v[64:67]
	s_barrier
	s_setprio 1
	s_mov_b32 m0, s49
	ds_read_b128 v[182:185], v145 offset:49152
	ds_read_b128 v[186:189], v145 offset:50176
	ds_read_b128 v[190:193], v145 offset:51200
	ds_read_b128 v[194:197], v145 offset:52224
	ds_read_b128 v[198:201], v145 offset:53248
	ds_read_b128 v[202:205], v145 offset:54272
	ds_read_b128 v[206:209], v145 offset:55296
	ds_read_b128 v[210:213], v145 offset:56320
	global_load_lds_dwordx4 v130, s[98:99]
	s_mov_b32 m0, s45
	s_nop 0
	global_load_lds_dwordx4 v134, s[98:99]
	s_mov_b32 m0, s47
	s_nop 0
	global_load_lds_dwordx4 v130, s[56:57]
	s_mov_b32 m0, s19
	s_nop 0
	global_load_lds_dwordx4 v134, s[56:57]
	s_mov_b32 m0, s35
	s_nop 0
	global_load_lds_dwordx4 v128, s[100:101]
	s_mov_b32 m0, s70
	s_nop 0
	global_load_lds_dwordx4 v132, s[100:101]
	s_waitcnt vmcnt(8)
	s_waitcnt lgkmcnt(0)
	s_setprio 0
	s_barrier
	v_mfma_f32_16x16x32_bf16 v[60:63], v[146:149], v[182:185], v[60:63]
	v_mfma_f32_16x16x32_bf16 v[56:59], v[154:157], v[182:185], v[56:59]
	v_mfma_f32_16x16x32_bf16 v[52:55], v[146:149], v[190:193], v[52:55]
	v_mfma_f32_16x16x32_bf16 v[48:51], v[154:157], v[190:193], v[48:51]
	v_mfma_f32_16x16x32_bf16 v[36:39], v[146:149], v[198:201], v[36:39]
	v_mfma_f32_16x16x32_bf16 v[32:35], v[154:157], v[198:201], v[32:35]
	v_mfma_f32_16x16x32_bf16 v[20:23], v[146:149], v[206:209], v[20:23]
	v_mfma_f32_16x16x32_bf16 v[16:19], v[154:157], v[206:209], v[16:19]
	v_mfma_f32_16x16x32_bf16 v[60:63], v[150:153], v[186:189], v[60:63]
	v_mfma_f32_16x16x32_bf16 v[56:59], v[158:161], v[186:189], v[56:59]
	v_mfma_f32_16x16x32_bf16 v[52:55], v[150:153], v[194:197], v[52:55]
	v_mfma_f32_16x16x32_bf16 v[48:51], v[158:161], v[194:197], v[48:51]
	v_mfma_f32_16x16x32_bf16 v[36:39], v[150:153], v[202:205], v[36:39]
	v_mfma_f32_16x16x32_bf16 v[32:35], v[158:161], v[202:205], v[32:35]
	v_mfma_f32_16x16x32_bf16 v[20:23], v[150:153], v[210:213], v[20:23]
	v_mfma_f32_16x16x32_bf16 v[16:19], v[158:161], v[210:213], v[16:19]
	v_mfma_f32_16x16x32_bf16 v[44:47], v[166:169], v[182:185], v[44:47]
	v_mfma_f32_16x16x32_bf16 v[40:43], v[174:177], v[182:185], v[40:43]
	v_mfma_f32_16x16x32_bf16 v[28:31], v[166:169], v[190:193], v[28:31]
	v_mfma_f32_16x16x32_bf16 v[24:27], v[174:177], v[190:193], v[24:27]
	v_mfma_f32_16x16x32_bf16 v[12:15], v[166:169], v[198:201], v[12:15]
	v_mfma_f32_16x16x32_bf16 v[8:11], v[174:177], v[198:201], v[8:11]
	v_mfma_f32_16x16x32_bf16 v[4:7], v[166:169], v[206:209], v[4:7]
	v_mfma_f32_16x16x32_bf16 v[0:3], v[174:177], v[206:209], v[0:3]
	v_mfma_f32_16x16x32_bf16 v[44:47], v[170:173], v[186:189], v[44:47]
	v_mfma_f32_16x16x32_bf16 v[40:43], v[178:181], v[186:189], v[40:43]
	v_mfma_f32_16x16x32_bf16 v[28:31], v[170:173], v[194:197], v[28:31]
	v_mfma_f32_16x16x32_bf16 v[24:27], v[178:181], v[194:197], v[24:27]
	v_mfma_f32_16x16x32_bf16 v[12:15], v[170:173], v[202:205], v[12:15]
	v_mfma_f32_16x16x32_bf16 v[8:11], v[178:181], v[202:205], v[8:11]
	v_mfma_f32_16x16x32_bf16 v[4:7], v[170:173], v[210:213], v[4:7]
	v_mfma_f32_16x16x32_bf16 v[0:3], v[178:181], v[210:213], v[0:3]
	s_barrier
	s_setprio 1
	s_movk_i32 s19, 0x100
	s_andn2_b64 vcc, exec, s[54:55]
	s_mov_b64 s[56:57], -1
	s_mov_b64 s[54:55], 0
	s_cbranch_vccz .LBB0_947
	s_and_b64 vcc, exec, s[40:41]
	s_cbranch_vccz .LBB0_950
	s_barrier

; #define PG8_STAGE(bufoff, gbase, voff) do { _Pragma("unroll") for (int _i = 0; _i < 2; ++_i) \
;         __builtin_amdgcn_global_load_lds((const unsigned*)((const char*)(gbase) + (voff)[_i]), (PG8_LAS unsigned*)(lds + (bufoff) + ldsw + _i * 8192), 16, 0, 0); } while (0)
; #define PG8_LDA(dst, b, h) do { _Pragma("unroll") for (int m = 0; m < 4; ++m) _Pragma("unroll") for (int k = 0; k < 2; ++k) dst[m][k] = *(const PG8_LAS bf16x8*)(lds + PG8_SA(b, h) + aoff + m * 2048 + k * 1024); } while (0)
; #define PG8_LDB(dst, b, h) do { _Pragma("unroll") for (int n = 0; n < 2; ++n) _Pragma("unroll") for (int k = 0; k < 2; ++k) dst[n][k] = *(const PG8_LAS bf16x8*)(lds + PG8_SB(b, h) + boff + n * 2048 + k * 1024); } while (0)
; #define PG8_MMA(ai, bj, At, Bt) do { __builtin_amdgcn_s_setprio(1); _Pragma("unroll") for (int m = 0; m < 4; ++m) _Pragma("unroll") for (int n = 0; n < 2; ++n) _Pragma("unroll") for (int k = 0; k < 2; ++k) \
;         acc[ai][bj][m][n] = __builtin_amdgcn_mfma_f32_16x16x32_bf16(Bt[n][k], At[m][k], acc[ai][bj][m][n], 0, 0, 0); __builtin_amdgcn_s_setprio(0); } while (0)
; #define PG8_WAIT_V(n) asm volatile("s_waitcnt vmcnt(" #n ")" ::: "memory")
; #define PG8_WAIT_L(n) asm volatile("s_waitcnt lgkmcnt(" #n ")" ::: "memory")
; #define PG8_BAR __builtin_amdgcn_s_barrier()
; #define PG8_SCHED __builtin_amdgcn_sched_barrier(0)
; template <class Epi, class Sched, bool ALIGN_EPI = false, bool SP2 = false>
; __device__ __forceinline__ void gemm_phase(PG8_LAS unsigned char* lds, const Gemm g, const Sched& S, const Epi& E) {
;     ...
;             PG8_LDB(B0, 0, 0); PG8_LDB(B1, 0, 1); PG8_SCHED; PG8_LDA(At, 0, 0); PG8_STAGE(PG8_SA(1, 1), a1 + hstepA, voffA);
;             PG8_WAIT_V(8); PG8_WAIT_L(0); PG8_BAR; PG8_MMA(0, 0, At, B0); PG8_MMA(0, 1, At, B1); PG8_BAR; PG8_SCHED;
;     ...
; #pragma unroll
;         for (int a = 0; a < 2; ++a)
; #pragma unroll
;             for (int b = 0; b < 2; ++b)
; #pragma unroll
;                 for (int m = 0; m < 4; ++m)
; #pragma unroll
;                     for (int n = 0; n < 2; ++n) acc[a][b][m][n] = (f32x4){0.f, 0.f, 0.f, 0.f};
;         cur = nxt; cA = nA; cB = nB; ++ui;
.LBB0_1081:
	s_ashr_i32 s41, s40, 31
	s_lshl_b64 s[42:43], s[40:41], 20
	s_add_u32 s42, s26, s42
	s_addc_u32 s43, s27, s43
	s_and_b64 s[44:45], s[4:5], exec
	s_cselect_b32 s41, s43, s49
	s_cselect_b32 s62, s42, s48
	s_ashr_i32 s39, s38, 31
	s_lshl_b64 s[44:45], s[38:39], 20
	v_readlane_b32 s52, v240, 18
	v_readlane_b32 s53, v240, 19
	s_add_u32 s44, s52, s44
	s_addc_u32 s45, s53, s45
	s_and_b64 s[52:53], s[4:5], exec
	s_cselect_b32 s39, s45, s51
	s_cselect_b32 s63, s44, s50
	s_add_u32 s48, s48, 0x80080
	s_addc_u32 s49, s49, 0
	s_add_u32 s64, s50, 0x100
	v_mov_b64_e32 v[0:1], 0
	s_addc_u32 s65, s51, 0
	s_mov_b32 s66, -2
	v_mov_b64_e32 v[2:3], 0
	v_mov_b64_e32 v[4:5], 0
	v_mov_b64_e32 v[6:7], 0
	v_mov_b64_e32 v[12:13], 0
	v_mov_b64_e32 v[14:15], 0
	v_mov_b64_e32 v[20:21], 0
	v_mov_b64_e32 v[22:23], 0
	v_mov_b64_e32 v[28:29], 0
	v_mov_b64_e32 v[30:31], 0
	v_mov_b64_e32 v[36:37], 0
	v_mov_b64_e32 v[38:39], 0
	v_mov_b64_e32 v[44:45], 0
	v_mov_b64_e32 v[46:47], 0
	v_mov_b64_e32 v[52:53], 0
	v_mov_b64_e32 v[54:55], 0
	v_mov_b64_e32 v[8:9], 0
	v_mov_b64_e32 v[10:11], 0
	v_mov_b64_e32 v[16:17], 0
	v_mov_b64_e32 v[18:19], 0
	v_mov_b64_e32 v[24:25], 0
	v_mov_b64_e32 v[26:27], 0
	v_mov_b64_e32 v[32:33], 0
	v_mov_b64_e32 v[34:35], 0
	v_mov_b64_e32 v[40:41], 0
	v_mov_b64_e32 v[42:43], 0
	v_mov_b64_e32 v[48:49], 0
	v_mov_b64_e32 v[50:51], 0
	v_mov_b64_e32 v[56:57], 0
	v_mov_b64_e32 v[58:59], 0
	v_mov_b64_e32 v[60:61], 0
	v_mov_b64_e32 v[62:63], 0
	v_mov_b64_e32 v[64:65], 0
	v_mov_b64_e32 v[66:67], 0
	v_mov_b64_e32 v[68:69], 0
	v_mov_b64_e32 v[70:71], 0
	v_mov_b64_e32 v[76:77], 0
	v_mov_b64_e32 v[78:79], 0
	v_mov_b64_e32 v[84:85], 0
	v_mov_b64_e32 v[86:87], 0
	v_mov_b64_e32 v[92:93], 0
	v_mov_b64_e32 v[94:95], 0
	v_mov_b64_e32 v[100:101], 0
	v_mov_b64_e32 v[102:103], 0
	v_mov_b64_e32 v[108:109], 0
	v_mov_b64_e32 v[110:111], 0
	v_mov_b64_e32 v[116:117], 0
	v_mov_b64_e32 v[118:119], 0
	v_mov_b64_e32 v[72:73], 0
	v_mov_b64_e32 v[74:75], 0
	v_mov_b64_e32 v[80:81], 0
	v_mov_b64_e32 v[82:83], 0
	v_mov_b64_e32 v[88:89], 0
	v_mov_b64_e32 v[90:91], 0
	v_mov_b64_e32 v[96:97], 0
	v_mov_b64_e32 v[98:99], 0
	v_mov_b64_e32 v[104:105], 0
	v_mov_b64_e32 v[106:107], 0
	v_mov_b64_e32 v[112:113], 0
	v_mov_b64_e32 v[114:115], 0
	v_mov_b64_e32 v[120:121], 0
	v_mov_b64_e32 v[122:123], 0
	v_mov_b64_e32 v[124:125], 0
	v_mov_b64_e32 v[126:127], 0
	v_add_u32_e32 v241, 0x18000, v145
	v_add_u32_e32 v242, 0x1c000, v145
.LBB0_1082:
	ds_read_b128 v[150:153], v147
	ds_read_b128 v[154:157], v147 offset:1024
	ds_read_b128 v[158:161], v147 offset:2048
	ds_read_b128 v[166:169], v147 offset:3072
	ds_read_b128 v[170:173], v148
	ds_read_b128 v[174:177], v148 offset:1024
	ds_read_b128 v[178:181], v148 offset:2048
	ds_read_b128 v[182:185], v148 offset:3072
	s_add_u32 s50, s48, 0xfff80080
	s_addc_u32 s51, s49, -1
	s_cmp_eq_u32 s66, 28
	s_cselect_b32 s53, s41, s51
	s_cselect_b32 s52, s62, s50
	s_cselect_b32 s51, s39, s65
	s_cselect_b32 s50, s63, s64
	s_add_i32 m0, s30, 0xc000
	ds_read_b128 v[186:189], v149
	ds_read_b128 v[190:193], v149 offset:1024
	ds_read_b128 v[194:197], v149 offset:2048
	ds_read_b128 v[198:201], v149 offset:3072
	ds_read_b128 v[202:205], v149 offset:4096
	ds_read_b128 v[206:209], v149 offset:5120
	ds_read_b128 v[210:213], v149 offset:6144
	ds_read_b128 v[214:217], v149 offset:7168
	global_load_lds_dwordx4 v136, s[48:49]
	s_add_i32 m0, s30, 0xe000
	s_nop 0
	global_load_lds_dwordx4 v138, s[48:49]
	s_waitcnt vmcnt(8)
	s_waitcnt lgkmcnt(0)
	s_setprio 0
	s_barrier
	v_mfma_f32_16x16x32_bf16 v[124:127], v[150:153], v[186:189], v[124:127]
	v_mfma_f32_16x16x32_bf16 v[120:123], v[158:161], v[186:189], v[120:123]
	v_mfma_f32_16x16x32_bf16 v[112:115], v[150:153], v[194:197], v[112:115]
	v_mfma_f32_16x16x32_bf16 v[104:107], v[158:161], v[194:197], v[104:107]
	v_mfma_f32_16x16x32_bf16 v[96:99], v[150:153], v[202:205], v[96:99]
	v_mfma_f32_16x16x32_bf16 v[88:91], v[158:161], v[202:205], v[88:91]
	v_mfma_f32_16x16x32_bf16 v[80:83], v[150:153], v[210:213], v[80:83]
	v_mfma_f32_16x16x32_bf16 v[72:75], v[158:161], v[210:213], v[72:75]
	v_mfma_f32_16x16x32_bf16 v[124:127], v[154:157], v[190:193], v[124:127]
	v_mfma_f32_16x16x32_bf16 v[120:123], v[166:169], v[190:193], v[120:123]
	v_mfma_f32_16x16x32_bf16 v[112:115], v[154:157], v[198:201], v[112:115]
	v_mfma_f32_16x16x32_bf16 v[104:107], v[166:169], v[198:201], v[104:107]
	v_mfma_f32_16x16x32_bf16 v[96:99], v[154:157], v[206:209], v[96:99]
	v_mfma_f32_16x16x32_bf16 v[88:91], v[166:169], v[206:209], v[88:91]
	v_mfma_f32_16x16x32_bf16 v[80:83], v[154:157], v[214:217], v[80:83]
	v_mfma_f32_16x16x32_bf16 v[72:75], v[166:169], v[214:217], v[72:75]
	v_mfma_f32_16x16x32_bf16 v[116:119], v[170:173], v[186:189], v[116:119]
	v_mfma_f32_16x16x32_bf16 v[108:111], v[178:181], v[186:189], v[108:111]
	v_mfma_f32_16x16x32_bf16 v[100:103], v[170:173], v[194:197], v[100:103]
	v_mfma_f32_16x16x32_bf16 v[92:95], v[178:181], v[194:197], v[92:95]
	v_mfma_f32_16x16x32_bf16 v[84:87], v[170:173], v[202:205], v[84:87]
	v_mfma_f32_16x16x32_bf16 v[76:79], v[178:181], v[202:205], v[76:79]
	v_mfma_f32_16x16x32_bf16 v[68:71], v[170:173], v[210:213], v[68:71]
	v_mfma_f32_16x16x32_bf16 v[64:67], v[178:181], v[210:213], v[64:67]
	v_mfma_f32_16x16x32_bf16 v[116:119], v[174:177], v[190:193], v[116:119]
	v_mfma_f32_16x16x32_bf16 v[108:111], v[182:185], v[190:193], v[108:111]
	v_mfma_f32_16x16x32_bf16 v[100:103], v[174:177], v[198:201], v[100:103]
	v_mfma_f32_16x16x32_bf16 v[92:95], v[182:185], v[198:201], v[92:95]
	v_mfma_f32_16x16x32_bf16 v[84:87], v[174:177], v[206:209], v[84:87]
	v_mfma_f32_16x16x32_bf16 v[76:79], v[182:185], v[206:209], v[76:79]
	v_mfma_f32_16x16x32_bf16 v[68:71], v[174:177], v[214:217], v[68:71]
	v_mfma_f32_16x16x32_bf16 v[64:67], v[182:185], v[214:217], v[64:67]
	s_barrier
; #define PG8_STAGE(bufoff, gbase, voff) do { _Pragma("unroll") for (int _i = 0; _i < 2; ++_i) \
;         __builtin_amdgcn_global_load_lds((const unsigned*)((const char*)(gbase) + (voff)[_i]), (PG8_LAS unsigned*)(lds + (bufoff) + ldsw + _i * 8192), 16, 0, 0); } while (0)
; #define PG8_LDA(dst, b, h) do { _Pragma("unroll") for (int m = 0; m < 4; ++m) _Pragma("unroll") for (int k = 0; k < 2; ++k) dst[m][k] = *(const PG8_LAS bf16x8*)(lds + PG8_SA(b, h) + aoff + m * 2048 + k * 1024); } while (0)
; #define PG8_LDB(dst, b, h) do { _Pragma("unroll") for (int n = 0; n < 2; ++n) _Pragma("unroll") for (int k = 0; k < 2; ++k) dst[n][k] = *(const PG8_LAS bf16x8*)(lds + PG8_SB(b, h) + boff + n * 2048 + k * 1024); } while (0)
; #define PG8_MMA(ai, bj, At, Bt) do { __builtin_amdgcn_s_setprio(1); _Pragma("unroll") for (int m = 0; m < 4; ++m) _Pragma("unroll") for (int n = 0; n < 2; ++n) _Pragma("unroll") for (int k = 0; k < 2; ++k) \
;         acc[ai][bj][m][n] = __builtin_amdgcn_mfma_f32_16x16x32_bf16(Bt[n][k], At[m][k], acc[ai][bj][m][n], 0, 0, 0); __builtin_amdgcn_s_setprio(0); } while (0)
; #define PG8_WAIT_V(n) asm volatile("s_waitcnt vmcnt(" #n ")" ::: "memory")
; #define PG8_WAIT_L(n) asm volatile("s_waitcnt lgkmcnt(" #n ")" ::: "memory")
; #define PG8_BAR __builtin_amdgcn_s_barrier()
; #define PG8_SCHED __builtin_amdgcn_sched_barrier(0)
; template <class Epi, class Sched, bool ALIGN_EPI = false, bool SP2 = false>
; __device__ __forceinline__ void gemm_phase(PG8_LAS unsigned char* lds, const Gemm g, const Sched& S, const Epi& E) {
;     ...
;             PG8_LDA(At, 0, 1); PG8_STAGE(PG8_SB(0, 0), b2, voffB); PG8_STAGE(PG8_SB(0, 1), b2 + hstepB, voffB); PG8_STAGE(PG8_SA(0, 0), a2, voffA);
;             PG8_WAIT_V(8); PG8_WAIT_L(0); PG8_BAR; PG8_MMA(1, 0, At, B0); PG8_MMA(1, 1, At, B1); PG8_BAR; PG8_SCHED;
;             PG8_LDB(B0, 1, 0); PG8_LDB(B1, 1, 1); PG8_SCHED; PG8_LDA(At, 1, 0); PG8_STAGE(PG8_SA(0, 1), a2 + hstepA, voffA);
	s_setprio 1
	s_add_u32 s98, s50, s10
	s_addc_u32 s99, s51, s11
	s_add_u32 s100, s52, s10
	s_addc_u32 s101, s53, s11
	s_add_i32 s67, s55, s28
	s_mov_b32 m0, s67
	ds_read_b128 v[186:189], v149 offset:16384
	ds_read_b128 v[190:193], v149 offset:17408
	ds_read_b128 v[194:197], v149 offset:18432
	ds_read_b128 v[198:201], v149 offset:19456
	ds_read_b128 v[202:205], v149 offset:20480
	ds_read_b128 v[206:209], v149 offset:21504
	ds_read_b128 v[210:213], v149 offset:22528
	ds_read_b128 v[214:217], v149 offset:23552
	global_load_lds_dwordx4 v132, s[50:51]
	s_add_i32 m0, s67, 0x2000
	s_add_u32 s68, s50, 0x80000
	s_addc_u32 s69, s51, 0
	s_add_i32 s67, s56, s28
	global_load_lds_dwordx4 v128, s[50:51]
	s_mov_b32 m0, s67
	s_nop 0
	global_load_lds_dwordx4 v132, s[68:69]
	s_add_i32 m0, s67, 0x2000
	s_nop 0
	global_load_lds_dwordx4 v128, s[68:69]
	s_mov_b32 m0, s30
	s_nop 0
	global_load_lds_dwordx4 v134, s[52:53]
	s_mov_b32 m0, s31
	s_nop 0
	global_load_lds_dwordx4 v130, s[52:53]
	s_waitcnt vmcnt(8)
	s_waitcnt lgkmcnt(0)
	s_setprio 0
	s_barrier
	v_mfma_f32_16x16x32_bf16 v[60:63], v[150:153], v[186:189], v[60:63]
	v_mfma_f32_16x16x32_bf16 v[56:59], v[158:161], v[186:189], v[56:59]
	v_mfma_f32_16x16x32_bf16 v[48:51], v[150:153], v[194:197], v[48:51]
	v_mfma_f32_16x16x32_bf16 v[40:43], v[158:161], v[194:197], v[40:43]
	v_mfma_f32_16x16x32_bf16 v[32:35], v[150:153], v[202:205], v[32:35]
	v_mfma_f32_16x16x32_bf16 v[24:27], v[158:161], v[202:205], v[24:27]
	v_mfma_f32_16x16x32_bf16 v[16:19], v[150:153], v[210:213], v[16:19]
	v_mfma_f32_16x16x32_bf16 v[8:11], v[158:161], v[210:213], v[8:11]
	v_mfma_f32_16x16x32_bf16 v[60:63], v[154:157], v[190:193], v[60:63]
	v_mfma_f32_16x16x32_bf16 v[56:59], v[166:169], v[190:193], v[56:59]
	v_mfma_f32_16x16x32_bf16 v[48:51], v[154:157], v[198:201], v[48:51]
	v_mfma_f32_16x16x32_bf16 v[40:43], v[166:169], v[198:201], v[40:43]
	v_mfma_f32_16x16x32_bf16 v[32:35], v[154:157], v[206:209], v[32:35]
	v_mfma_f32_16x16x32_bf16 v[24:27], v[166:169], v[206:209], v[24:27]
	v_mfma_f32_16x16x32_bf16 v[16:19], v[154:157], v[214:217], v[16:19]
	v_mfma_f32_16x16x32_bf16 v[8:11], v[166:169], v[214:217], v[8:11]
	v_mfma_f32_16x16x32_bf16 v[52:55], v[170:173], v[186:189], v[52:55]
	v_mfma_f32_16x16x32_bf16 v[44:47], v[178:181], v[186:189], v[44:47]
	v_mfma_f32_16x16x32_bf16 v[36:39], v[170:173], v[194:197], v[36:39]
	v_mfma_f32_16x16x32_bf16 v[28:31], v[178:181], v[194:197], v[28:31]
	v_mfma_f32_16x16x32_bf16 v[20:23], v[170:173], v[202:205], v[20:23]
	v_mfma_f32_16x16x32_bf16 v[12:15], v[178:181], v[202:205], v[12:15]
	v_mfma_f32_16x16x32_bf16 v[4:7], v[170:173], v[210:213], v[4:7]
	v_mfma_f32_16x16x32_bf16 v[0:3], v[178:181], v[210:213], v[0:3]
	v_mfma_f32_16x16x32_bf16 v[52:55], v[174:177], v[190:193], v[52:55]
	v_mfma_f32_16x16x32_bf16 v[44:47], v[182:185], v[190:193], v[44:47]
	v_mfma_f32_16x16x32_bf16 v[36:39], v[174:177], v[198:201], v[36:39]
	v_mfma_f32_16x16x32_bf16 v[28:31], v[182:185], v[198:201], v[28:31]
	v_mfma_f32_16x16x32_bf16 v[20:23], v[174:177], v[206:209], v[20:23]
	v_mfma_f32_16x16x32_bf16 v[12:15], v[182:185], v[206:209], v[12:15]
	v_mfma_f32_16x16x32_bf16 v[4:7], v[174:177], v[214:217], v[4:7]
	v_mfma_f32_16x16x32_bf16 v[0:3], v[182:185], v[214:217], v[0:3]
	s_barrier
	s_setprio 1
	s_add_i32 s67, 0, 0x18000
	s_add_i32 s68, 0, 0x1c000
	ds_read_b128 v[150:153], v241
	ds_read_b128 v[154:157], v241 offset:1024
	ds_read_b128 v[158:161], v241 offset:2048
	ds_read_b128 v[166:169], v241 offset:3072
	ds_read_b128 v[170:173], v242
	ds_read_b128 v[174:177], v242 offset:1024
	ds_read_b128 v[178:181], v242 offset:2048
	ds_read_b128 v[182:185], v242 offset:3072
	s_add_u32 s52, s52, 0x80000
	s_addc_u32 s53, s53, 0
	s_mov_b32 m0, s33
	ds_read_b128 v[186:189], v149 offset:32768
	ds_read_b128 v[190:193], v149 offset:33792
	ds_read_b128 v[194:197], v149 offset:34816
	ds_read_b128 v[198:201], v149 offset:35840
	ds_read_b128 v[202:205], v149 offset:36864
	ds_read_b128 v[206:209], v149 offset:37888
	ds_read_b128 v[210:213], v149 offset:38912
	ds_read_b128 v[214:217], v149 offset:39936
	global_load_lds_dwordx4 v134, s[52:53]
	s_mov_b32 m0, s34
	s_nop 0
	global_load_lds_dwordx4 v130, s[52:53]
	s_waitcnt vmcnt(8)
	s_waitcnt lgkmcnt(0)
	s_setprio 0
	s_barrier
; #define PG8_STAGE(bufoff, gbase, voff) do { _Pragma("unroll") for (int _i = 0; _i < 2; ++_i) \
;         __builtin_amdgcn_global_load_lds((const unsigned*)((const char*)(gbase) + (voff)[_i]), (PG8_LAS unsigned*)(lds + (bufoff) + ldsw + _i * 8192), 16, 0, 0); } while (0)
; #define PG8_LDA(dst, b, h) do { _Pragma("unroll") for (int m = 0; m < 4; ++m) _Pragma("unroll") for (int k = 0; k < 2; ++k) dst[m][k] = *(const PG8_LAS bf16x8*)(lds + PG8_SA(b, h) + aoff + m * 2048 + k * 1024); } while (0)
; #define PG8_MMA(ai, bj, At, Bt) do { __builtin_amdgcn_s_setprio(1); _Pragma("unroll") for (int m = 0; m < 4; ++m) _Pragma("unroll") for (int n = 0; n < 2; ++n) _Pragma("unroll") for (int k = 0; k < 2; ++k) \
;         acc[ai][bj][m][n] = __builtin_amdgcn_mfma_f32_16x16x32_bf16(Bt[n][k], At[m][k], acc[ai][bj][m][n], 0, 0, 0); __builtin_amdgcn_s_setprio(0); } while (0)
; #define PG8_WAIT_V(n) asm volatile("s_waitcnt vmcnt(" #n ")" ::: "memory")
; #define PG8_WAIT_L(n) asm volatile("s_waitcnt lgkmcnt(" #n ")" ::: "memory")
; #define PG8_BAR __builtin_amdgcn_s_barrier()
; #define PG8_SCHED __builtin_amdgcn_sched_barrier(0)
; template <class Epi, class Sched, bool ALIGN_EPI = false, bool SP2 = false>
; __device__ __forceinline__ void gemm_phase(PG8_LAS unsigned char* lds, const Gemm g, const Sched& S, const Epi& E) {
;     ...
;             PG8_WAIT_V(8); PG8_WAIT_L(0); PG8_BAR; PG8_MMA(0, 0, At, B0); PG8_MMA(0, 1, At, B1); PG8_BAR; PG8_SCHED;
;             PG8_LDA(At, 1, 1); PG8_STAGE(PG8_SB(1, 0), b3, voffB); PG8_STAGE(PG8_SB(1, 1), b3 + hstepB, voffB); PG8_STAGE(PG8_SA(1, 0), a3, voffA);
;             PG8_WAIT_V(8); PG8_WAIT_L(0); PG8_BAR; PG8_MMA(1, 0, At, B0); PG8_MMA(1, 1, At, B1); PG8_BAR; PG8_SCHED;
;     ...
;         if constexpr (ALIGN_EPI) { if (wr == 0) PG8_BAR; }
	v_mfma_f32_16x16x32_bf16 v[124:127], v[150:153], v[186:189], v[124:127]
	v_mfma_f32_16x16x32_bf16 v[120:123], v[158:161], v[186:189], v[120:123]
	v_mfma_f32_16x16x32_bf16 v[112:115], v[150:153], v[194:197], v[112:115]
	v_mfma_f32_16x16x32_bf16 v[104:107], v[158:161], v[194:197], v[104:107]
	v_mfma_f32_16x16x32_bf16 v[96:99], v[150:153], v[202:205], v[96:99]
	v_mfma_f32_16x16x32_bf16 v[88:91], v[158:161], v[202:205], v[88:91]
	v_mfma_f32_16x16x32_bf16 v[80:83], v[150:153], v[210:213], v[80:83]
	v_mfma_f32_16x16x32_bf16 v[72:75], v[158:161], v[210:213], v[72:75]
	v_mfma_f32_16x16x32_bf16 v[124:127], v[154:157], v[190:193], v[124:127]
	v_mfma_f32_16x16x32_bf16 v[120:123], v[166:169], v[190:193], v[120:123]
	v_mfma_f32_16x16x32_bf16 v[112:115], v[154:157], v[198:201], v[112:115]
	v_mfma_f32_16x16x32_bf16 v[104:107], v[166:169], v[198:201], v[104:107]
	v_mfma_f32_16x16x32_bf16 v[96:99], v[154:157], v[206:209], v[96:99]
	v_mfma_f32_16x16x32_bf16 v[88:91], v[166:169], v[206:209], v[88:91]
	v_mfma_f32_16x16x32_bf16 v[80:83], v[154:157], v[214:217], v[80:83]
	v_mfma_f32_16x16x32_bf16 v[72:75], v[166:169], v[214:217], v[72:75]
	v_mfma_f32_16x16x32_bf16 v[116:119], v[170:173], v[186:189], v[116:119]
	v_mfma_f32_16x16x32_bf16 v[108:111], v[178:181], v[186:189], v[108:111]
	v_mfma_f32_16x16x32_bf16 v[100:103], v[170:173], v[194:197], v[100:103]
	v_mfma_f32_16x16x32_bf16 v[92:95], v[178:181], v[194:197], v[92:95]
	v_mfma_f32_16x16x32_bf16 v[84:87], v[170:173], v[202:205], v[84:87]
	v_mfma_f32_16x16x32_bf16 v[76:79], v[178:181], v[202:205], v[76:79]
	v_mfma_f32_16x16x32_bf16 v[68:71], v[170:173], v[210:213], v[68:71]
	v_mfma_f32_16x16x32_bf16 v[64:67], v[178:181], v[210:213], v[64:67]
	v_mfma_f32_16x16x32_bf16 v[116:119], v[174:177], v[190:193], v[116:119]
	v_mfma_f32_16x16x32_bf16 v[108:111], v[182:185], v[190:193], v[108:111]
	v_mfma_f32_16x16x32_bf16 v[100:103], v[174:177], v[198:201], v[100:103]
	v_mfma_f32_16x16x32_bf16 v[92:95], v[182:185], v[198:201], v[92:95]
	v_mfma_f32_16x16x32_bf16 v[84:87], v[174:177], v[206:209], v[84:87]
	v_mfma_f32_16x16x32_bf16 v[76:79], v[182:185], v[206:209], v[76:79]
	v_mfma_f32_16x16x32_bf16 v[68:71], v[174:177], v[214:217], v[68:71]
	v_mfma_f32_16x16x32_bf16 v[64:67], v[182:185], v[214:217], v[64:67]
	s_barrier
	s_setprio 1
	s_add_i32 s52, s67, s28
	s_mov_b32 m0, s52
	ds_read_b128 v[186:189], v149 offset:49152
	ds_read_b128 v[190:193], v149 offset:50176
	ds_read_b128 v[194:197], v149 offset:51200
	ds_read_b128 v[198:201], v149 offset:52224
	ds_read_b128 v[202:205], v149 offset:53248
	ds_read_b128 v[206:209], v149 offset:54272
	ds_read_b128 v[210:213], v149 offset:55296
	ds_read_b128 v[214:217], v149 offset:56320
	global_load_lds_dwordx4 v132, s[98:99]
	s_add_i32 m0, s52, 0x2000
	s_add_u32 s50, s50, 0x80080
	s_addc_u32 s51, s51, 0
	s_add_i32 s52, s68, s28
	global_load_lds_dwordx4 v128, s[98:99]
	s_mov_b32 m0, s52
	s_nop 0
	global_load_lds_dwordx4 v132, s[50:51]
	s_add_i32 m0, s52, 0x2000
	s_nop 0
	global_load_lds_dwordx4 v128, s[50:51]
	s_mov_b32 m0, s47
	s_nop 0
	global_load_lds_dwordx4 v134, s[100:101]
	s_mov_b32 m0, s54
	s_nop 0
	global_load_lds_dwordx4 v130, s[100:101]
	s_waitcnt vmcnt(8)
	s_waitcnt lgkmcnt(0)
	s_setprio 0
	s_barrier
	v_mfma_f32_16x16x32_bf16 v[60:63], v[150:153], v[186:189], v[60:63]
	v_mfma_f32_16x16x32_bf16 v[56:59], v[158:161], v[186:189], v[56:59]
	v_mfma_f32_16x16x32_bf16 v[48:51], v[150:153], v[194:197], v[48:51]
	v_mfma_f32_16x16x32_bf16 v[40:43], v[158:161], v[194:197], v[40:43]
	v_mfma_f32_16x16x32_bf16 v[32:35], v[150:153], v[202:205], v[32:35]
	v_mfma_f32_16x16x32_bf16 v[24:27], v[158:161], v[202:205], v[24:27]
	v_mfma_f32_16x16x32_bf16 v[16:19], v[150:153], v[210:213], v[16:19]
	v_mfma_f32_16x16x32_bf16 v[8:11], v[158:161], v[210:213], v[8:11]
	v_mfma_f32_16x16x32_bf16 v[60:63], v[154:157], v[190:193], v[60:63]
	v_mfma_f32_16x16x32_bf16 v[56:59], v[166:169], v[190:193], v[56:59]
	v_mfma_f32_16x16x32_bf16 v[48:51], v[154:157], v[198:201], v[48:51]
	v_mfma_f32_16x16x32_bf16 v[40:43], v[166:169], v[198:201], v[40:43]
	v_mfma_f32_16x16x32_bf16 v[32:35], v[154:157], v[206:209], v[32:35]
	v_mfma_f32_16x16x32_bf16 v[24:27], v[166:169], v[206:209], v[24:27]
	v_mfma_f32_16x16x32_bf16 v[16:19], v[154:157], v[214:217], v[16:19]
	v_mfma_f32_16x16x32_bf16 v[8:11], v[166:169], v[214:217], v[8:11]
	v_mfma_f32_16x16x32_bf16 v[52:55], v[170:173], v[186:189], v[52:55]
	v_mfma_f32_16x16x32_bf16 v[44:47], v[178:181], v[186:189], v[44:47]
	v_mfma_f32_16x16x32_bf16 v[36:39], v[170:173], v[194:197], v[36:39]
	v_mfma_f32_16x16x32_bf16 v[28:31], v[178:181], v[194:197], v[28:31]
	v_mfma_f32_16x16x32_bf16 v[20:23], v[170:173], v[202:205], v[20:23]
	v_mfma_f32_16x16x32_bf16 v[12:15], v[178:181], v[202:205], v[12:15]
	v_mfma_f32_16x16x32_bf16 v[4:7], v[170:173], v[210:213], v[4:7]
	v_mfma_f32_16x16x32_bf16 v[0:3], v[178:181], v[210:213], v[0:3]
	v_mfma_f32_16x16x32_bf16 v[52:55], v[174:177], v[190:193], v[52:55]
	v_mfma_f32_16x16x32_bf16 v[44:47], v[182:185], v[190:193], v[44:47]
	v_mfma_f32_16x16x32_bf16 v[36:39], v[174:177], v[198:201], v[36:39]
	v_mfma_f32_16x16x32_bf16 v[28:31], v[182:185], v[198:201], v[28:31]
	v_mfma_f32_16x16x32_bf16 v[20:23], v[174:177], v[206:209], v[20:23]
	v_mfma_f32_16x16x32_bf16 v[12:15], v[182:185], v[206:209], v[12:15]
	v_mfma_f32_16x16x32_bf16 v[4:7], v[174:177], v[214:217], v[4:7]
	v_mfma_f32_16x16x32_bf16 v[0:3], v[182:185], v[214:217], v[0:3]
	s_barrier
	s_setprio 1
	s_add_i32 s66, s66, 2
	s_add_u32 s48, s48, 0x100
	s_addc_u32 s49, s49, 0
	s_add_u32 s64, s64, 0x100
	s_addc_u32 s65, s65, 0
	s_cmp_gt_u32 s66, 29
	s_cbranch_scc0 .LBB0_1082
	s_and_b64 vcc, exec, s[16:17]
	s_cbranch_vccz .LBB0_1085
	s_barrier

; #define PG8_STAGE(bufoff, gbase, voff) do { _Pragma("unroll") for (int _i = 0; _i < 2; ++_i) \
;         __builtin_amdgcn_global_load_lds((const unsigned*)((const char*)(gbase) + (voff)[_i]), (PG8_LAS unsigned*)(lds + (bufoff) + ldsw + _i * 8192), 16, 0, 0); } while (0)
; #define PG8_LDA(dst, b, h) do { _Pragma("unroll") for (int m = 0; m < 4; ++m) _Pragma("unroll") for (int k = 0; k < 2; ++k) dst[m][k] = *(const PG8_LAS bf16x8*)(lds + PG8_SA(b, h) + aoff + m * 2048 + k * 1024); } while (0)
; #define PG8_LDB(dst, b, h) do { _Pragma("unroll") for (int n = 0; n < 2; ++n) _Pragma("unroll") for (int k = 0; k < 2; ++k) dst[n][k] = *(const PG8_LAS bf16x8*)(lds + PG8_SB(b, h) + boff + n * 2048 + k * 1024); } while (0)
; #define PG8_WAIT_V(n) asm volatile("s_waitcnt vmcnt(" #n ")" ::: "memory")
; #define PG8_WAIT_L(n) asm volatile("s_waitcnt lgkmcnt(" #n ")" ::: "memory")
; #define PG8_BAR __builtin_amdgcn_s_barrier()
; #define PG8_SCHED __builtin_amdgcn_sched_barrier(0)
; template <class Epi, class Sched, bool ALIGN_EPI = false, bool SP2 = false>
; __device__ __forceinline__ void gemm_phase(PG8_LAS unsigned char* lds, const Gemm g, const Sched& S, const Epi& E) {
;     ...
;         const char* nA = has_next ? (const char*)g.A + (size_t)nxt.pm * tstepA + (size_t)nxt.kz * kzb : cA; const char* nB = has_next ? (const char*)g.Bt + (size_t)nxt.pn * tstepB + (size_t)nxt.kz * kzb : cB;
;         for (int t = 0; t < nt; t += 2) {
;             const bool last = (t == nt - 2);
;             const char* a1 = cA + (size_t)(t + 1) * kstep;
;             const char* a2 = last ? nA : cA + (size_t)(t + 2) * kstep; const char* b2 = last ? nB : cB + (size_t)(t + 2) * kstep;
;             const char* a3 = a2 + kstep; const char* b3 = b2 + kstep;
;             if (last && has_next) S.a_ready(nxt);
;             if constexpr (SP2) {
;             PG8_LDB(B0, 0, 0); PG8_LDB(B1, 0, 1); PG8_SCHED; PG8_LDA(At, 0, 0); PG8_STAGE(PG8_SA(1, 1), a1 + hstepA, voffA);
;             PG8_WAIT_V(8); PG8_WAIT_L(0); PG8_BAR; PG8_MMA(0, 0, At, B0); PG8_MMA(0, 1, At, B1); PG8_BAR; PG8_SCHED;
;     ...
;         for (int a = 0; a < 2; ++a)
; #pragma unroll
;             for (int b = 0; b < 2; ++b)
; #pragma unroll
;                 for (int m = 0; m < 4; ++m)
; #pragma unroll
;                     for (int n = 0; n < 2; ++n) acc[a][b][m][n] = (f32x4){0.f, 0.f, 0.f, 0.f};
.LBB0_1160:
	s_ashr_i32 s41, s40, 31
	s_lshl_b64 s[42:43], s[40:41], 22
	s_add_u32 s42, s12, s42
	s_addc_u32 s43, s13, s43
	s_and_b64 s[44:45], s[4:5], exec
	s_cselect_b32 s41, s43, s49
	s_cselect_b32 s61, s42, s48
	s_ashr_i32 s39, s38, 31
	s_lshl_b64 s[44:45], s[38:39], 22
	v_readlane_b32 s52, v240, 20
	v_readlane_b32 s53, v240, 21
	s_add_u32 s44, s52, s44
	s_addc_u32 s45, s53, s45
	s_and_b64 s[52:53], s[4:5], exec
	s_cselect_b32 s39, s45, s51
	s_cselect_b32 s62, s44, s50
	s_add_u32 s48, s48, 0x200080
	s_addc_u32 s49, s49, 0
	s_add_u32 s63, s50, 0x100
	v_mov_b64_e32 v[0:1], 0
	s_addc_u32 s64, s51, 0
	s_mov_b32 s65, -2
	v_mov_b64_e32 v[2:3], 0
	v_mov_b64_e32 v[4:5], 0
	v_mov_b64_e32 v[6:7], 0
	v_mov_b64_e32 v[8:9], 0
	v_mov_b64_e32 v[10:11], 0
	v_mov_b64_e32 v[16:17], 0
	v_mov_b64_e32 v[18:19], 0
	v_mov_b64_e32 v[24:25], 0
	v_mov_b64_e32 v[26:27], 0
	v_mov_b64_e32 v[32:33], 0
	v_mov_b64_e32 v[34:35], 0
	v_mov_b64_e32 v[40:41], 0
	v_mov_b64_e32 v[42:43], 0
	v_mov_b64_e32 v[48:49], 0
	v_mov_b64_e32 v[50:51], 0
	v_mov_b64_e32 v[12:13], 0
	v_mov_b64_e32 v[14:15], 0
	v_mov_b64_e32 v[20:21], 0
	v_mov_b64_e32 v[22:23], 0
	v_mov_b64_e32 v[28:29], 0
	v_mov_b64_e32 v[30:31], 0
	v_mov_b64_e32 v[36:37], 0
	v_mov_b64_e32 v[38:39], 0
	v_mov_b64_e32 v[44:45], 0
	v_mov_b64_e32 v[46:47], 0
	v_mov_b64_e32 v[52:53], 0
	v_mov_b64_e32 v[54:55], 0
	v_mov_b64_e32 v[56:57], 0
	v_mov_b64_e32 v[58:59], 0
	v_mov_b64_e32 v[60:61], 0
	v_mov_b64_e32 v[62:63], 0
	v_mov_b64_e32 v[64:65], 0
	v_mov_b64_e32 v[66:67], 0
	v_mov_b64_e32 v[68:69], 0
	v_mov_b64_e32 v[70:71], 0
	v_mov_b64_e32 v[76:77], 0
	v_mov_b64_e32 v[78:79], 0
	v_mov_b64_e32 v[84:85], 0
	v_mov_b64_e32 v[86:87], 0
	v_mov_b64_e32 v[88:89], 0
	v_mov_b64_e32 v[90:91], 0
	v_mov_b64_e32 v[96:97], 0
	v_mov_b64_e32 v[98:99], 0
	v_mov_b64_e32 v[104:105], 0
	v_mov_b64_e32 v[106:107], 0
	v_mov_b64_e32 v[112:113], 0
	v_mov_b64_e32 v[114:115], 0
	v_mov_b64_e32 v[72:73], 0
	v_mov_b64_e32 v[74:75], 0
	v_mov_b64_e32 v[80:81], 0
	v_mov_b64_e32 v[82:83], 0
	v_mov_b64_e32 v[92:93], 0
	v_mov_b64_e32 v[94:95], 0
	v_mov_b64_e32 v[100:101], 0
	v_mov_b64_e32 v[102:103], 0
	v_mov_b64_e32 v[108:109], 0
	v_mov_b64_e32 v[110:111], 0
	v_mov_b64_e32 v[116:117], 0
	v_mov_b64_e32 v[118:119], 0
	v_mov_b64_e32 v[120:121], 0
	v_mov_b64_e32 v[122:123], 0
	v_mov_b64_e32 v[124:125], 0
	v_mov_b64_e32 v[126:127], 0
	v_add_u32_e32 v241, 0x18000, v155
	v_add_u32_e32 v242, 0x1c000, v155
.LBB0_1161:
	ds_read_b128 v[166:169], v157
	ds_read_b128 v[170:173], v157 offset:1024
	ds_read_b128 v[174:177], v157 offset:2048
	ds_read_b128 v[178:181], v157 offset:3072
	ds_read_b128 v[182:185], v158
	ds_read_b128 v[186:189], v158 offset:1024
	ds_read_b128 v[190:193], v158 offset:2048
	ds_read_b128 v[194:197], v158 offset:3072
	s_add_u32 s50, s48, 0xffe00080
	s_addc_u32 s51, s49, -1
	s_cmpk_eq_i32 s65, 0x7c
	s_cselect_b32 s53, s41, s51
	s_cselect_b32 s52, s61, s50
	s_cselect_b32 s51, s39, s64
	s_cselect_b32 s50, s62, s63
	s_add_i32 m0, s29, 0xc000
	ds_read_b128 v[198:201], v159
	ds_read_b128 v[202:205], v159 offset:1024
	ds_read_b128 v[206:209], v159 offset:2048
	ds_read_b128 v[210:213], v159 offset:3072
	ds_read_b128 v[214:217], v159 offset:4096
	ds_read_b128 v[218:221], v159 offset:5120
	ds_read_b128 v[222:225], v159 offset:6144
	ds_read_b128 v[226:229], v159 offset:7168
	global_load_lds_dwordx4 v136, s[48:49]
	s_add_i32 m0, s29, 0xe000
	s_nop 0
	global_load_lds_dwordx4 v138, s[48:49]
	s_waitcnt vmcnt(8)
	s_waitcnt lgkmcnt(0)
	s_setprio 0
	s_barrier
	v_mfma_f32_16x16x32_bf16 v[124:127], v[166:169], v[198:201], v[124:127]
	v_mfma_f32_16x16x32_bf16 v[120:123], v[174:177], v[198:201], v[120:123]
	v_mfma_f32_16x16x32_bf16 v[116:119], v[166:169], v[206:209], v[116:119]
	v_mfma_f32_16x16x32_bf16 v[108:111], v[174:177], v[206:209], v[108:111]
	v_mfma_f32_16x16x32_bf16 v[100:103], v[166:169], v[214:217], v[100:103]
	v_mfma_f32_16x16x32_bf16 v[92:95], v[174:177], v[214:217], v[92:95]
	v_mfma_f32_16x16x32_bf16 v[80:83], v[166:169], v[222:225], v[80:83]
	v_mfma_f32_16x16x32_bf16 v[72:75], v[174:177], v[222:225], v[72:75]
	v_mfma_f32_16x16x32_bf16 v[124:127], v[170:173], v[202:205], v[124:127]
	v_mfma_f32_16x16x32_bf16 v[120:123], v[178:181], v[202:205], v[120:123]
	v_mfma_f32_16x16x32_bf16 v[116:119], v[170:173], v[210:213], v[116:119]
	v_mfma_f32_16x16x32_bf16 v[108:111], v[178:181], v[210:213], v[108:111]
	v_mfma_f32_16x16x32_bf16 v[100:103], v[170:173], v[218:221], v[100:103]
	v_mfma_f32_16x16x32_bf16 v[92:95], v[178:181], v[218:221], v[92:95]
	v_mfma_f32_16x16x32_bf16 v[80:83], v[170:173], v[226:229], v[80:83]
	v_mfma_f32_16x16x32_bf16 v[72:75], v[178:181], v[226:229], v[72:75]
	v_mfma_f32_16x16x32_bf16 v[112:115], v[182:185], v[198:201], v[112:115]
	v_mfma_f32_16x16x32_bf16 v[104:107], v[190:193], v[198:201], v[104:107]
	v_mfma_f32_16x16x32_bf16 v[96:99], v[182:185], v[206:209], v[96:99]
	v_mfma_f32_16x16x32_bf16 v[88:91], v[190:193], v[206:209], v[88:91]
	v_mfma_f32_16x16x32_bf16 v[84:87], v[182:185], v[214:217], v[84:87]
	v_mfma_f32_16x16x32_bf16 v[76:79], v[190:193], v[214:217], v[76:79]
	v_mfma_f32_16x16x32_bf16 v[68:71], v[182:185], v[222:225], v[68:71]
	v_mfma_f32_16x16x32_bf16 v[64:67], v[190:193], v[222:225], v[64:67]
	v_mfma_f32_16x16x32_bf16 v[112:115], v[186:189], v[202:205], v[112:115]
	v_mfma_f32_16x16x32_bf16 v[104:107], v[194:197], v[202:205], v[104:107]
	v_mfma_f32_16x16x32_bf16 v[96:99], v[186:189], v[210:213], v[96:99]
	v_mfma_f32_16x16x32_bf16 v[88:91], v[194:197], v[210:213], v[88:91]
	v_mfma_f32_16x16x32_bf16 v[84:87], v[186:189], v[218:221], v[84:87]
	v_mfma_f32_16x16x32_bf16 v[76:79], v[194:197], v[218:221], v[76:79]
	v_mfma_f32_16x16x32_bf16 v[68:71], v[186:189], v[226:229], v[68:71]
	v_mfma_f32_16x16x32_bf16 v[64:67], v[194:197], v[226:229], v[64:67]
	s_barrier
; #define PG8_STAGE(bufoff, gbase, voff) do { _Pragma("unroll") for (int _i = 0; _i < 2; ++_i) \
;         __builtin_amdgcn_global_load_lds((const unsigned*)((const char*)(gbase) + (voff)[_i]), (PG8_LAS unsigned*)(lds + (bufoff) + ldsw + _i * 8192), 16, 0, 0); } while (0)
; #define PG8_LDA(dst, b, h) do { _Pragma("unroll") for (int m = 0; m < 4; ++m) _Pragma("unroll") for (int k = 0; k < 2; ++k) dst[m][k] = *(const PG8_LAS bf16x8*)(lds + PG8_SA(b, h) + aoff + m * 2048 + k * 1024); } while (0)
; #define PG8_LDB(dst, b, h) do { _Pragma("unroll") for (int n = 0; n < 2; ++n) _Pragma("unroll") for (int k = 0; k < 2; ++k) dst[n][k] = *(const PG8_LAS bf16x8*)(lds + PG8_SB(b, h) + boff + n * 2048 + k * 1024); } while (0)
; #define PG8_MMA(ai, bj, At, Bt) do { __builtin_amdgcn_s_setprio(1); _Pragma("unroll") for (int m = 0; m < 4; ++m) _Pragma("unroll") for (int n = 0; n < 2; ++n) _Pragma("unroll") for (int k = 0; k < 2; ++k) \
;         acc[ai][bj][m][n] = __builtin_amdgcn_mfma_f32_16x16x32_bf16(Bt[n][k], At[m][k], acc[ai][bj][m][n], 0, 0, 0); __builtin_amdgcn_s_setprio(0); } while (0)
; #define PG8_WAIT_V(n) asm volatile("s_waitcnt vmcnt(" #n ")" ::: "memory")
; #define PG8_WAIT_L(n) asm volatile("s_waitcnt lgkmcnt(" #n ")" ::: "memory")
; #define PG8_BAR __builtin_amdgcn_s_barrier()
; #define PG8_SCHED __builtin_amdgcn_sched_barrier(0)
; template <class Epi, class Sched, bool ALIGN_EPI = false, bool SP2 = false>
; __device__ __forceinline__ void gemm_phase(PG8_LAS unsigned char* lds, const Gemm g, const Sched& S, const Epi& E) {
;     ...
;             PG8_LDA(At, 0, 1); PG8_STAGE(PG8_SB(0, 0), b2, voffB); PG8_STAGE(PG8_SB(0, 1), b2 + hstepB, voffB); PG8_STAGE(PG8_SA(0, 0), a2, voffA);
;             PG8_WAIT_V(8); PG8_WAIT_L(0); PG8_BAR; PG8_MMA(1, 0, At, B0); PG8_MMA(1, 1, At, B1); PG8_BAR; PG8_SCHED;
;             PG8_LDB(B0, 1, 0); PG8_LDB(B1, 1, 1); PG8_SCHED; PG8_LDA(At, 1, 0); PG8_STAGE(PG8_SA(0, 1), a2 + hstepA, voffA);
	s_setprio 1
	s_add_u32 s98, s50, s10
	s_addc_u32 s99, s51, s11
	s_add_u32 s100, s52, s10
	s_addc_u32 s101, s53, s11
	s_add_i32 s66, s54, s28
	s_mov_b32 m0, s66
	ds_read_b128 v[198:201], v159 offset:16384
	ds_read_b128 v[202:205], v159 offset:17408
	ds_read_b128 v[206:209], v159 offset:18432
	ds_read_b128 v[210:213], v159 offset:19456
	ds_read_b128 v[214:217], v159 offset:20480
	ds_read_b128 v[218:221], v159 offset:21504
	ds_read_b128 v[222:225], v159 offset:22528
	ds_read_b128 v[226:229], v159 offset:23552
	global_load_lds_dwordx4 v130, s[50:51]
	s_add_i32 m0, s66, 0x2000
	s_add_u32 s66, s50, 0x200000
	s_addc_u32 s67, s51, 0
	s_add_i32 s68, s55, s28
	global_load_lds_dwordx4 v134, s[50:51]
	s_mov_b32 m0, s68
	s_nop 0
	global_load_lds_dwordx4 v130, s[66:67]
	s_add_i32 m0, s68, 0x2000
	s_nop 0
	global_load_lds_dwordx4 v134, s[66:67]
	s_mov_b32 m0, s29
	s_nop 0
	global_load_lds_dwordx4 v128, s[52:53]
	s_mov_b32 m0, s30
	s_nop 0
	global_load_lds_dwordx4 v132, s[52:53]
	s_waitcnt vmcnt(8)
	s_waitcnt lgkmcnt(0)
	s_setprio 0
	s_barrier
	v_mfma_f32_16x16x32_bf16 v[60:63], v[166:169], v[198:201], v[60:63]
	v_mfma_f32_16x16x32_bf16 v[56:59], v[174:177], v[198:201], v[56:59]
	v_mfma_f32_16x16x32_bf16 v[52:55], v[166:169], v[206:209], v[52:55]
	v_mfma_f32_16x16x32_bf16 v[44:47], v[174:177], v[206:209], v[44:47]
	v_mfma_f32_16x16x32_bf16 v[36:39], v[166:169], v[214:217], v[36:39]
	v_mfma_f32_16x16x32_bf16 v[28:31], v[174:177], v[214:217], v[28:31]
	v_mfma_f32_16x16x32_bf16 v[20:23], v[166:169], v[222:225], v[20:23]
	v_mfma_f32_16x16x32_bf16 v[12:15], v[174:177], v[222:225], v[12:15]
	v_mfma_f32_16x16x32_bf16 v[60:63], v[170:173], v[202:205], v[60:63]
	v_mfma_f32_16x16x32_bf16 v[56:59], v[178:181], v[202:205], v[56:59]
	v_mfma_f32_16x16x32_bf16 v[52:55], v[170:173], v[210:213], v[52:55]
	v_mfma_f32_16x16x32_bf16 v[44:47], v[178:181], v[210:213], v[44:47]
	v_mfma_f32_16x16x32_bf16 v[36:39], v[170:173], v[218:221], v[36:39]
	v_mfma_f32_16x16x32_bf16 v[28:31], v[178:181], v[218:221], v[28:31]
	v_mfma_f32_16x16x32_bf16 v[20:23], v[170:173], v[226:229], v[20:23]
	v_mfma_f32_16x16x32_bf16 v[12:15], v[178:181], v[226:229], v[12:15]
	v_mfma_f32_16x16x32_bf16 v[48:51], v[182:185], v[198:201], v[48:51]
	v_mfma_f32_16x16x32_bf16 v[40:43], v[190:193], v[198:201], v[40:43]
	v_mfma_f32_16x16x32_bf16 v[32:35], v[182:185], v[206:209], v[32:35]
	v_mfma_f32_16x16x32_bf16 v[24:27], v[190:193], v[206:209], v[24:27]
	v_mfma_f32_16x16x32_bf16 v[16:19], v[182:185], v[214:217], v[16:19]
	v_mfma_f32_16x16x32_bf16 v[8:11], v[190:193], v[214:217], v[8:11]
	v_mfma_f32_16x16x32_bf16 v[4:7], v[182:185], v[222:225], v[4:7]
	v_mfma_f32_16x16x32_bf16 v[0:3], v[190:193], v[222:225], v[0:3]
	v_mfma_f32_16x16x32_bf16 v[48:51], v[186:189], v[202:205], v[48:51]
	v_mfma_f32_16x16x32_bf16 v[40:43], v[194:197], v[202:205], v[40:43]
	v_mfma_f32_16x16x32_bf16 v[32:35], v[186:189], v[210:213], v[32:35]
	v_mfma_f32_16x16x32_bf16 v[24:27], v[194:197], v[210:213], v[24:27]
	v_mfma_f32_16x16x32_bf16 v[16:19], v[186:189], v[218:221], v[16:19]
	v_mfma_f32_16x16x32_bf16 v[8:11], v[194:197], v[218:221], v[8:11]
	v_mfma_f32_16x16x32_bf16 v[4:7], v[186:189], v[226:229], v[4:7]
	v_mfma_f32_16x16x32_bf16 v[0:3], v[194:197], v[226:229], v[0:3]
	s_barrier
	s_setprio 1
	s_add_i32 s66, 0, 0x18000
	s_add_i32 s67, 0, 0x1c000
	ds_read_b128 v[166:169], v241
	ds_read_b128 v[170:173], v241 offset:1024
	ds_read_b128 v[174:177], v241 offset:2048
	ds_read_b128 v[178:181], v241 offset:3072
	ds_read_b128 v[182:185], v242
	ds_read_b128 v[186:189], v242 offset:1024
	ds_read_b128 v[190:193], v242 offset:2048
	ds_read_b128 v[194:197], v242 offset:3072
	s_add_u32 s52, s52, 0x200000
	s_addc_u32 s53, s53, 0
	s_mov_b32 m0, s31
	ds_read_b128 v[198:201], v159 offset:32768
	ds_read_b128 v[202:205], v159 offset:33792
	ds_read_b128 v[206:209], v159 offset:34816
	ds_read_b128 v[210:213], v159 offset:35840
	ds_read_b128 v[214:217], v159 offset:36864
	ds_read_b128 v[218:221], v159 offset:37888
	ds_read_b128 v[222:225], v159 offset:38912
	ds_read_b128 v[226:229], v159 offset:39936
	global_load_lds_dwordx4 v128, s[52:53]
	s_mov_b32 m0, s33
	s_nop 0
	global_load_lds_dwordx4 v132, s[52:53]
	s_waitcnt vmcnt(8)
	s_waitcnt lgkmcnt(0)
	s_setprio 0
	s_barrier
; #define PG8_STAGE(bufoff, gbase, voff) do { _Pragma("unroll") for (int _i = 0; _i < 2; ++_i) \
;         __builtin_amdgcn_global_load_lds((const unsigned*)((const char*)(gbase) + (voff)[_i]), (PG8_LAS unsigned*)(lds + (bufoff) + ldsw + _i * 8192), 16, 0, 0); } while (0)
; #define PG8_LDA(dst, b, h) do { _Pragma("unroll") for (int m = 0; m < 4; ++m) _Pragma("unroll") for (int k = 0; k < 2; ++k) dst[m][k] = *(const PG8_LAS bf16x8*)(lds + PG8_SA(b, h) + aoff + m * 2048 + k * 1024); } while (0)
; #define PG8_MMA(ai, bj, At, Bt) do { __builtin_amdgcn_s_setprio(1); _Pragma("unroll") for (int m = 0; m < 4; ++m) _Pragma("unroll") for (int n = 0; n < 2; ++n) _Pragma("unroll") for (int k = 0; k < 2; ++k) \
;         acc[ai][bj][m][n] = __builtin_amdgcn_mfma_f32_16x16x32_bf16(Bt[n][k], At[m][k], acc[ai][bj][m][n], 0, 0, 0); __builtin_amdgcn_s_setprio(0); } while (0)
; #define PG8_WAIT_V(n) asm volatile("s_waitcnt vmcnt(" #n ")" ::: "memory")
; #define PG8_WAIT_L(n) asm volatile("s_waitcnt lgkmcnt(" #n ")" ::: "memory")
; #define PG8_BAR __builtin_amdgcn_s_barrier()
; #define PG8_SCHED __builtin_amdgcn_sched_barrier(0)
; template <class Epi, class Sched, bool ALIGN_EPI = false, bool SP2 = false>
; __device__ __forceinline__ void gemm_phase(PG8_LAS unsigned char* lds, const Gemm g, const Sched& S, const Epi& E) {
;     ...
;             PG8_WAIT_V(8); PG8_WAIT_L(0); PG8_BAR; PG8_MMA(0, 0, At, B0); PG8_MMA(0, 1, At, B1); PG8_BAR; PG8_SCHED;
;             PG8_LDA(At, 1, 1); PG8_STAGE(PG8_SB(1, 0), b3, voffB); PG8_STAGE(PG8_SB(1, 1), b3 + hstepB, voffB); PG8_STAGE(PG8_SA(1, 0), a3, voffA);
;             PG8_WAIT_V(8); PG8_WAIT_L(0); PG8_BAR; PG8_MMA(1, 0, At, B0); PG8_MMA(1, 1, At, B1); PG8_BAR; PG8_SCHED;
;     ...
;         if constexpr (ALIGN_EPI) { if (wr == 0) PG8_BAR; }
	v_mfma_f32_16x16x32_bf16 v[124:127], v[166:169], v[198:201], v[124:127]
	v_mfma_f32_16x16x32_bf16 v[120:123], v[174:177], v[198:201], v[120:123]
	v_mfma_f32_16x16x32_bf16 v[116:119], v[166:169], v[206:209], v[116:119]
	v_mfma_f32_16x16x32_bf16 v[108:111], v[174:177], v[206:209], v[108:111]
	v_mfma_f32_16x16x32_bf16 v[100:103], v[166:169], v[214:217], v[100:103]
	v_mfma_f32_16x16x32_bf16 v[92:95], v[174:177], v[214:217], v[92:95]
	v_mfma_f32_16x16x32_bf16 v[80:83], v[166:169], v[222:225], v[80:83]
	v_mfma_f32_16x16x32_bf16 v[72:75], v[174:177], v[222:225], v[72:75]
	v_mfma_f32_16x16x32_bf16 v[124:127], v[170:173], v[202:205], v[124:127]
	v_mfma_f32_16x16x32_bf16 v[120:123], v[178:181], v[202:205], v[120:123]
	v_mfma_f32_16x16x32_bf16 v[116:119], v[170:173], v[210:213], v[116:119]
	v_mfma_f32_16x16x32_bf16 v[108:111], v[178:181], v[210:213], v[108:111]
	v_mfma_f32_16x16x32_bf16 v[100:103], v[170:173], v[218:221], v[100:103]
	v_mfma_f32_16x16x32_bf16 v[92:95], v[178:181], v[218:221], v[92:95]
	v_mfma_f32_16x16x32_bf16 v[80:83], v[170:173], v[226:229], v[80:83]
	v_mfma_f32_16x16x32_bf16 v[72:75], v[178:181], v[226:229], v[72:75]
	v_mfma_f32_16x16x32_bf16 v[112:115], v[182:185], v[198:201], v[112:115]
	v_mfma_f32_16x16x32_bf16 v[104:107], v[190:193], v[198:201], v[104:107]
	v_mfma_f32_16x16x32_bf16 v[96:99], v[182:185], v[206:209], v[96:99]
	v_mfma_f32_16x16x32_bf16 v[88:91], v[190:193], v[206:209], v[88:91]
	v_mfma_f32_16x16x32_bf16 v[84:87], v[182:185], v[214:217], v[84:87]
	v_mfma_f32_16x16x32_bf16 v[76:79], v[190:193], v[214:217], v[76:79]
	v_mfma_f32_16x16x32_bf16 v[68:71], v[182:185], v[222:225], v[68:71]
	v_mfma_f32_16x16x32_bf16 v[64:67], v[190:193], v[222:225], v[64:67]
	v_mfma_f32_16x16x32_bf16 v[112:115], v[186:189], v[202:205], v[112:115]
	v_mfma_f32_16x16x32_bf16 v[104:107], v[194:197], v[202:205], v[104:107]
	v_mfma_f32_16x16x32_bf16 v[96:99], v[186:189], v[210:213], v[96:99]
	v_mfma_f32_16x16x32_bf16 v[88:91], v[194:197], v[210:213], v[88:91]
	v_mfma_f32_16x16x32_bf16 v[84:87], v[186:189], v[218:221], v[84:87]
	v_mfma_f32_16x16x32_bf16 v[76:79], v[194:197], v[218:221], v[76:79]
	v_mfma_f32_16x16x32_bf16 v[68:71], v[186:189], v[226:229], v[68:71]
	v_mfma_f32_16x16x32_bf16 v[64:67], v[194:197], v[226:229], v[64:67]
	s_barrier
	s_setprio 1
	s_add_i32 s52, s66, s28
	s_mov_b32 m0, s52
	ds_read_b128 v[198:201], v159 offset:49152
	ds_read_b128 v[202:205], v159 offset:50176
	ds_read_b128 v[206:209], v159 offset:51200
	ds_read_b128 v[210:213], v159 offset:52224
	ds_read_b128 v[214:217], v159 offset:53248
	ds_read_b128 v[218:221], v159 offset:54272
	ds_read_b128 v[222:225], v159 offset:55296
	ds_read_b128 v[226:229], v159 offset:56320
	global_load_lds_dwordx4 v130, s[98:99]
	s_add_i32 m0, s52, 0x2000
	s_add_u32 s50, s50, 0x200080
	s_addc_u32 s51, s51, 0
	s_add_i32 s52, s67, s28
	global_load_lds_dwordx4 v134, s[98:99]
	s_mov_b32 m0, s52
	s_nop 0
	global_load_lds_dwordx4 v130, s[50:51]
	s_add_i32 m0, s52, 0x2000
	s_nop 0
	global_load_lds_dwordx4 v134, s[50:51]
	s_mov_b32 m0, s35
	s_nop 0
	global_load_lds_dwordx4 v128, s[100:101]
	s_mov_b32 m0, s47
	s_nop 0
	global_load_lds_dwordx4 v132, s[100:101]
	s_waitcnt vmcnt(8)
	s_waitcnt lgkmcnt(0)
	s_setprio 0
	s_barrier
	v_mfma_f32_16x16x32_bf16 v[60:63], v[166:169], v[198:201], v[60:63]
	v_mfma_f32_16x16x32_bf16 v[56:59], v[174:177], v[198:201], v[56:59]
	v_mfma_f32_16x16x32_bf16 v[52:55], v[166:169], v[206:209], v[52:55]
	v_mfma_f32_16x16x32_bf16 v[44:47], v[174:177], v[206:209], v[44:47]
	v_mfma_f32_16x16x32_bf16 v[36:39], v[166:169], v[214:217], v[36:39]
	v_mfma_f32_16x16x32_bf16 v[28:31], v[174:177], v[214:217], v[28:31]
	v_mfma_f32_16x16x32_bf16 v[20:23], v[166:169], v[222:225], v[20:23]
	v_mfma_f32_16x16x32_bf16 v[12:15], v[174:177], v[222:225], v[12:15]
	v_mfma_f32_16x16x32_bf16 v[60:63], v[170:173], v[202:205], v[60:63]
	v_mfma_f32_16x16x32_bf16 v[56:59], v[178:181], v[202:205], v[56:59]
	v_mfma_f32_16x16x32_bf16 v[52:55], v[170:173], v[210:213], v[52:55]
	v_mfma_f32_16x16x32_bf16 v[44:47], v[178:181], v[210:213], v[44:47]
	v_mfma_f32_16x16x32_bf16 v[36:39], v[170:173], v[218:221], v[36:39]
	v_mfma_f32_16x16x32_bf16 v[28:31], v[178:181], v[218:221], v[28:31]
	v_mfma_f32_16x16x32_bf16 v[20:23], v[170:173], v[226:229], v[20:23]
	v_mfma_f32_16x16x32_bf16 v[12:15], v[178:181], v[226:229], v[12:15]
	v_mfma_f32_16x16x32_bf16 v[48:51], v[182:185], v[198:201], v[48:51]
	v_mfma_f32_16x16x32_bf16 v[40:43], v[190:193], v[198:201], v[40:43]
	v_mfma_f32_16x16x32_bf16 v[32:35], v[182:185], v[206:209], v[32:35]
	v_mfma_f32_16x16x32_bf16 v[24:27], v[190:193], v[206:209], v[24:27]
	v_mfma_f32_16x16x32_bf16 v[16:19], v[182:185], v[214:217], v[16:19]
	v_mfma_f32_16x16x32_bf16 v[8:11], v[190:193], v[214:217], v[8:11]
	v_mfma_f32_16x16x32_bf16 v[4:7], v[182:185], v[222:225], v[4:7]
	v_mfma_f32_16x16x32_bf16 v[0:3], v[190:193], v[222:225], v[0:3]
	v_mfma_f32_16x16x32_bf16 v[48:51], v[186:189], v[202:205], v[48:51]
	v_mfma_f32_16x16x32_bf16 v[40:43], v[194:197], v[202:205], v[40:43]
	v_mfma_f32_16x16x32_bf16 v[32:35], v[186:189], v[210:213], v[32:35]
	v_mfma_f32_16x16x32_bf16 v[24:27], v[194:197], v[210:213], v[24:27]
	v_mfma_f32_16x16x32_bf16 v[16:19], v[186:189], v[218:221], v[16:19]
	v_mfma_f32_16x16x32_bf16 v[8:11], v[194:197], v[218:221], v[8:11]
	v_mfma_f32_16x16x32_bf16 v[4:7], v[186:189], v[226:229], v[4:7]
	v_mfma_f32_16x16x32_bf16 v[0:3], v[194:197], v[226:229], v[0:3]
	s_barrier
	s_setprio 1
	s_add_i32 s65, s65, 2
	s_add_u32 s48, s48, 0x100
	s_addc_u32 s49, s49, 0
	s_add_u32 s63, s63, 0x100
	s_addc_u32 s64, s64, 0
	s_cmpk_gt_u32 s65, 0x7d
	s_cbranch_scc0 .LBB0_1161
	s_and_b64 vcc, exec, s[16:17]
	s_cbranch_vccz .LBB0_1164
	s_barrier

; #define PG8_STAGE(bufoff, gbase, voff) do { _Pragma("unroll") for (int _i = 0; _i < 2; ++_i) \
;         __builtin_amdgcn_global_load_lds((const unsigned*)((const char*)(gbase) + (voff)[_i]), (PG8_LAS unsigned*)(lds + (bufoff) + ldsw + _i * 8192), 16, 0, 0); } while (0)
; #define PG8_LDA(dst, b, h) do { _Pragma("unroll") for (int m = 0; m < 4; ++m) _Pragma("unroll") for (int k = 0; k < 2; ++k) dst[m][k] = *(const PG8_LAS bf16x8*)(lds + PG8_SA(b, h) + aoff + m * 2048 + k * 1024); } while (0)
; #define PG8_LDB(dst, b, h) do { _Pragma("unroll") for (int n = 0; n < 2; ++n) _Pragma("unroll") for (int k = 0; k < 2; ++k) dst[n][k] = *(const PG8_LAS bf16x8*)(lds + PG8_SB(b, h) + boff + n * 2048 + k * 1024); } while (0)
; #define PG8_WAIT_V(n) asm volatile("s_waitcnt vmcnt(" #n ")" ::: "memory")
; #define PG8_WAIT_L(n) asm volatile("s_waitcnt lgkmcnt(" #n ")" ::: "memory")
; #define PG8_BAR __builtin_amdgcn_s_barrier()
; #define PG8_SCHED __builtin_amdgcn_sched_barrier(0)
; template <class Epi, class Sched, bool ALIGN_EPI = false, bool SP2 = false>
; __device__ __forceinline__ void gemm_phase(PG8_LAS unsigned char* lds, const Gemm g, const Sched& S, const Epi& E) {
;     ...
;         const char* nA = has_next ? (const char*)g.A + (size_t)nxt.pm * tstepA + (size_t)nxt.kz * kzb : cA; const char* nB = has_next ? (const char*)g.Bt + (size_t)nxt.pn * tstepB + (size_t)nxt.kz * kzb : cB;
;         for (int t = 0; t < nt; t += 2) {
;             const bool last = (t == nt - 2);
;             const char* a1 = cA + (size_t)(t + 1) * kstep;
;             const char* a2 = last ? nA : cA + (size_t)(t + 2) * kstep; const char* b2 = last ? nB : cB + (size_t)(t + 2) * kstep;
;             const char* a3 = a2 + kstep; const char* b3 = b2 + kstep;
;             if (last && has_next) S.a_ready(nxt);
;             if constexpr (SP2) {
;             PG8_LDB(B0, 0, 0); PG8_LDB(B1, 0, 1); PG8_SCHED; PG8_LDA(At, 0, 0); PG8_STAGE(PG8_SA(1, 1), a1 + hstepA, voffA);
;             PG8_WAIT_V(8); PG8_WAIT_L(0); PG8_BAR; PG8_MMA(0, 0, At, B0); PG8_MMA(0, 1, At, B1); PG8_BAR; PG8_SCHED;
;     ...
;         for (int a = 0; a < 2; ++a)
; #pragma unroll
;             for (int b = 0; b < 2; ++b)
; #pragma unroll
;                 for (int m = 0; m < 4; ++m)
; #pragma unroll
;                     for (int n = 0; n < 2; ++n) acc[a][b][m][n] = (f32x4){0.f, 0.f, 0.f, 0.f};
.LBB0_1180:
	s_add_u32 s46, s46, 0x200080
	s_addc_u32 s47, s47, 0
	s_add_u32 s19, s48, 0x100
	v_mov_b64_e32 v[0:1], 0
	s_addc_u32 s39, s49, 0
	s_mov_b32 s41, -2
	v_mov_b64_e32 v[2:3], 0
	v_mov_b64_e32 v[4:5], 0
	v_mov_b64_e32 v[6:7], 0
	v_mov_b64_e32 v[8:9], 0
	v_mov_b64_e32 v[10:11], 0
	v_mov_b64_e32 v[12:13], 0
	v_mov_b64_e32 v[14:15], 0
	v_mov_b64_e32 v[24:25], 0
	v_mov_b64_e32 v[26:27], 0
	v_mov_b64_e32 v[28:29], 0
	v_mov_b64_e32 v[30:31], 0
	v_mov_b64_e32 v[40:41], 0
	v_mov_b64_e32 v[42:43], 0
	v_mov_b64_e32 v[44:45], 0
	v_mov_b64_e32 v[46:47], 0
	v_mov_b64_e32 v[16:17], 0
	v_mov_b64_e32 v[18:19], 0
	v_mov_b64_e32 v[20:21], 0
	v_mov_b64_e32 v[22:23], 0
	v_mov_b64_e32 v[32:33], 0
	v_mov_b64_e32 v[34:35], 0
	v_mov_b64_e32 v[36:37], 0
	v_mov_b64_e32 v[38:39], 0
	v_mov_b64_e32 v[48:49], 0
	v_mov_b64_e32 v[50:51], 0
	v_mov_b64_e32 v[52:53], 0
	v_mov_b64_e32 v[54:55], 0
	v_mov_b64_e32 v[56:57], 0
	v_mov_b64_e32 v[58:59], 0
	v_mov_b64_e32 v[60:61], 0
	v_mov_b64_e32 v[62:63], 0
	v_mov_b64_e32 v[64:65], 0
	v_mov_b64_e32 v[66:67], 0
	v_mov_b64_e32 v[68:69], 0
	v_mov_b64_e32 v[70:71], 0
	v_mov_b64_e32 v[72:73], 0
	v_mov_b64_e32 v[74:75], 0
	v_mov_b64_e32 v[76:77], 0
	v_mov_b64_e32 v[78:79], 0
	v_mov_b64_e32 v[88:89], 0
	v_mov_b64_e32 v[90:91], 0
	v_mov_b64_e32 v[92:93], 0
	v_mov_b64_e32 v[94:95], 0
	v_mov_b64_e32 v[104:105], 0
	v_mov_b64_e32 v[106:107], 0
	v_mov_b64_e32 v[108:109], 0
	v_mov_b64_e32 v[110:111], 0
	v_mov_b64_e32 v[80:81], 0
	v_mov_b64_e32 v[82:83], 0
	v_mov_b64_e32 v[84:85], 0
	v_mov_b64_e32 v[86:87], 0
	v_mov_b64_e32 v[96:97], 0
	v_mov_b64_e32 v[98:99], 0
	v_mov_b64_e32 v[100:101], 0
	v_mov_b64_e32 v[102:103], 0
	v_mov_b64_e32 v[112:113], 0
	v_mov_b64_e32 v[114:115], 0
	v_mov_b64_e32 v[116:117], 0
	v_mov_b64_e32 v[118:119], 0
	v_mov_b64_e32 v[120:121], 0
	v_mov_b64_e32 v[122:123], 0
	v_mov_b64_e32 v[124:125], 0
	v_mov_b64_e32 v[126:127], 0
	v_add_u32_e32 v241, 0x18000, v145
	v_add_u32_e32 v242, 0x1c000, v145
.LBB0_1181:
	ds_read_b128 v[150:153], v146
	ds_read_b128 v[154:157], v146 offset:1024
	ds_read_b128 v[158:161], v146 offset:2048
	ds_read_b128 v[166:169], v146 offset:3072
	ds_read_b128 v[170:173], v147
	ds_read_b128 v[174:177], v147 offset:1024
	ds_read_b128 v[178:181], v147 offset:2048
	ds_read_b128 v[182:185], v147 offset:3072
	s_add_u32 s43, s46, 0xffe00080
	s_addc_u32 s48, s47, -1
	s_cmp_eq_u32 s41, 12
	s_cselect_b32 s51, s1, s48
	s_cselect_b32 s50, s0, s43
	s_cselect_b32 s49, s45, s39
	s_cselect_b32 s48, s44, s19
	s_mov_b32 m0, s55
	ds_read_b128 v[186:189], v148
	ds_read_b128 v[190:193], v148 offset:1024
	ds_read_b128 v[194:197], v148 offset:2048
	ds_read_b128 v[198:201], v148 offset:3072
	ds_read_b128 v[202:205], v148 offset:4096
	ds_read_b128 v[206:209], v148 offset:5120
	ds_read_b128 v[210:213], v148 offset:6144
	ds_read_b128 v[214:217], v148 offset:7168
	global_load_lds_dwordx4 v136, s[46:47]
	s_mov_b32 m0, s56
	s_nop 0
	global_load_lds_dwordx4 v138, s[46:47]
	s_waitcnt vmcnt(8)
	s_waitcnt lgkmcnt(0)
	s_setprio 0
	s_barrier
	v_mfma_f32_16x16x32_bf16 v[124:127], v[150:153], v[186:189], v[124:127]
	v_mfma_f32_16x16x32_bf16 v[120:123], v[158:161], v[186:189], v[120:123]
	v_mfma_f32_16x16x32_bf16 v[116:119], v[150:153], v[194:197], v[116:119]
	v_mfma_f32_16x16x32_bf16 v[112:115], v[158:161], v[194:197], v[112:115]
	v_mfma_f32_16x16x32_bf16 v[100:103], v[150:153], v[202:205], v[100:103]
	v_mfma_f32_16x16x32_bf16 v[96:99], v[158:161], v[202:205], v[96:99]
	v_mfma_f32_16x16x32_bf16 v[84:87], v[150:153], v[210:213], v[84:87]
	v_mfma_f32_16x16x32_bf16 v[80:83], v[158:161], v[210:213], v[80:83]
	v_mfma_f32_16x16x32_bf16 v[124:127], v[154:157], v[190:193], v[124:127]
	v_mfma_f32_16x16x32_bf16 v[120:123], v[166:169], v[190:193], v[120:123]
	v_mfma_f32_16x16x32_bf16 v[116:119], v[154:157], v[198:201], v[116:119]
	v_mfma_f32_16x16x32_bf16 v[112:115], v[166:169], v[198:201], v[112:115]
	v_mfma_f32_16x16x32_bf16 v[100:103], v[154:157], v[206:209], v[100:103]
	v_mfma_f32_16x16x32_bf16 v[96:99], v[166:169], v[206:209], v[96:99]
	v_mfma_f32_16x16x32_bf16 v[84:87], v[154:157], v[214:217], v[84:87]
	v_mfma_f32_16x16x32_bf16 v[80:83], v[166:169], v[214:217], v[80:83]
	v_mfma_f32_16x16x32_bf16 v[108:111], v[170:173], v[186:189], v[108:111]
	v_mfma_f32_16x16x32_bf16 v[104:107], v[178:181], v[186:189], v[104:107]
	v_mfma_f32_16x16x32_bf16 v[92:95], v[170:173], v[194:197], v[92:95]
	v_mfma_f32_16x16x32_bf16 v[88:91], v[178:181], v[194:197], v[88:91]
	v_mfma_f32_16x16x32_bf16 v[76:79], v[170:173], v[202:205], v[76:79]
	v_mfma_f32_16x16x32_bf16 v[72:75], v[178:181], v[202:205], v[72:75]
	v_mfma_f32_16x16x32_bf16 v[68:71], v[170:173], v[210:213], v[68:71]
	v_mfma_f32_16x16x32_bf16 v[64:67], v[178:181], v[210:213], v[64:67]
	v_mfma_f32_16x16x32_bf16 v[108:111], v[174:177], v[190:193], v[108:111]
	v_mfma_f32_16x16x32_bf16 v[104:107], v[182:185], v[190:193], v[104:107]
	v_mfma_f32_16x16x32_bf16 v[92:95], v[174:177], v[198:201], v[92:95]
	v_mfma_f32_16x16x32_bf16 v[88:91], v[182:185], v[198:201], v[88:91]
	v_mfma_f32_16x16x32_bf16 v[76:79], v[174:177], v[206:209], v[76:79]
	v_mfma_f32_16x16x32_bf16 v[72:75], v[182:185], v[206:209], v[72:75]
	v_mfma_f32_16x16x32_bf16 v[68:71], v[174:177], v[214:217], v[68:71]
	v_mfma_f32_16x16x32_bf16 v[64:67], v[182:185], v[214:217], v[64:67]
	s_barrier
; #define PG8_STAGE(bufoff, gbase, voff) do { _Pragma("unroll") for (int _i = 0; _i < 2; ++_i) \
;         __builtin_amdgcn_global_load_lds((const unsigned*)((const char*)(gbase) + (voff)[_i]), (PG8_LAS unsigned*)(lds + (bufoff) + ldsw + _i * 8192), 16, 0, 0); } while (0)
; #define PG8_LDA(dst, b, h) do { _Pragma("unroll") for (int m = 0; m < 4; ++m) _Pragma("unroll") for (int k = 0; k < 2; ++k) dst[m][k] = *(const PG8_LAS bf16x8*)(lds + PG8_SA(b, h) + aoff + m * 2048 + k * 1024); } while (0)
; #define PG8_LDB(dst, b, h) do { _Pragma("unroll") for (int n = 0; n < 2; ++n) _Pragma("unroll") for (int k = 0; k < 2; ++k) dst[n][k] = *(const PG8_LAS bf16x8*)(lds + PG8_SB(b, h) + boff + n * 2048 + k * 1024); } while (0)
; #define PG8_MMA(ai, bj, At, Bt) do { __builtin_amdgcn_s_setprio(1); _Pragma("unroll") for (int m = 0; m < 4; ++m) _Pragma("unroll") for (int n = 0; n < 2; ++n) _Pragma("unroll") for (int k = 0; k < 2; ++k) \
;         acc[ai][bj][m][n] = __builtin_amdgcn_mfma_f32_16x16x32_bf16(Bt[n][k], At[m][k], acc[ai][bj][m][n], 0, 0, 0); __builtin_amdgcn_s_setprio(0); } while (0)
; #define PG8_WAIT_V(n) asm volatile("s_waitcnt vmcnt(" #n ")" ::: "memory")
; #define PG8_WAIT_L(n) asm volatile("s_waitcnt lgkmcnt(" #n ")" ::: "memory")
; #define PG8_BAR __builtin_amdgcn_s_barrier()
; #define PG8_SCHED __builtin_amdgcn_sched_barrier(0)
; template <class Epi, class Sched, bool ALIGN_EPI = false, bool SP2 = false>
; __device__ __forceinline__ void gemm_phase(PG8_LAS unsigned char* lds, const Gemm g, const Sched& S, const Epi& E) {
;     ...
;             PG8_LDA(At, 0, 1); PG8_STAGE(PG8_SB(0, 0), b2, voffB); PG8_STAGE(PG8_SB(0, 1), b2 + hstepB, voffB); PG8_STAGE(PG8_SA(0, 0), a2, voffA);
;             PG8_WAIT_V(8); PG8_WAIT_L(0); PG8_BAR; PG8_MMA(1, 0, At, B0); PG8_MMA(1, 1, At, B1); PG8_BAR; PG8_SCHED;
;             PG8_LDB(B0, 1, 0); PG8_LDB(B1, 1, 1); PG8_SCHED; PG8_LDA(At, 1, 0); PG8_STAGE(PG8_SA(0, 1), a2 + hstepA, voffA);
	s_setprio 1
	s_add_u32 s98, s48, s16
	s_addc_u32 s99, s49, s17
	s_add_u32 s100, s50, s16
	s_addc_u32 s101, s51, s17
	s_add_i32 s43, s53, s30
	s_mov_b32 m0, s43
	ds_read_b128 v[186:189], v148 offset:16384
	ds_read_b128 v[190:193], v148 offset:17408
	ds_read_b128 v[194:197], v148 offset:18432
	ds_read_b128 v[198:201], v148 offset:19456
	ds_read_b128 v[202:205], v148 offset:20480
	ds_read_b128 v[206:209], v148 offset:21504
	ds_read_b128 v[210:213], v148 offset:22528
	ds_read_b128 v[214:217], v148 offset:23552
	global_load_lds_dwordx4 v130, s[48:49]
	s_add_i32 m0, s43, 0x2000
	s_add_u32 s58, s48, 0x200000
	s_addc_u32 s59, s49, 0
	s_add_i32 s43, s54, s30
	global_load_lds_dwordx4 v134, s[48:49]
	s_mov_b32 m0, s43
	s_nop 0
	global_load_lds_dwordx4 v130, s[58:59]
	s_add_i32 m0, s43, 0x2000
	s_nop 0
	global_load_lds_dwordx4 v134, s[58:59]
	s_mov_b32 m0, s21
	s_nop 0
	global_load_lds_dwordx4 v128, s[50:51]
	s_mov_b32 m0, s23
	s_nop 0
	global_load_lds_dwordx4 v132, s[50:51]
	s_waitcnt vmcnt(8)
	s_waitcnt lgkmcnt(0)
	s_setprio 0
	s_barrier
	v_mfma_f32_16x16x32_bf16 v[60:63], v[150:153], v[186:189], v[60:63]
	v_mfma_f32_16x16x32_bf16 v[56:59], v[158:161], v[186:189], v[56:59]
	v_mfma_f32_16x16x32_bf16 v[52:55], v[150:153], v[194:197], v[52:55]
	v_mfma_f32_16x16x32_bf16 v[48:51], v[158:161], v[194:197], v[48:51]
	v_mfma_f32_16x16x32_bf16 v[36:39], v[150:153], v[202:205], v[36:39]
	v_mfma_f32_16x16x32_bf16 v[32:35], v[158:161], v[202:205], v[32:35]
	v_mfma_f32_16x16x32_bf16 v[20:23], v[150:153], v[210:213], v[20:23]
	v_mfma_f32_16x16x32_bf16 v[16:19], v[158:161], v[210:213], v[16:19]
	v_mfma_f32_16x16x32_bf16 v[60:63], v[154:157], v[190:193], v[60:63]
	v_mfma_f32_16x16x32_bf16 v[56:59], v[166:169], v[190:193], v[56:59]
	v_mfma_f32_16x16x32_bf16 v[52:55], v[154:157], v[198:201], v[52:55]
	v_mfma_f32_16x16x32_bf16 v[48:51], v[166:169], v[198:201], v[48:51]
	v_mfma_f32_16x16x32_bf16 v[36:39], v[154:157], v[206:209], v[36:39]
	v_mfma_f32_16x16x32_bf16 v[32:35], v[166:169], v[206:209], v[32:35]
	v_mfma_f32_16x16x32_bf16 v[20:23], v[154:157], v[214:217], v[20:23]
	v_mfma_f32_16x16x32_bf16 v[16:19], v[166:169], v[214:217], v[16:19]
	v_mfma_f32_16x16x32_bf16 v[44:47], v[170:173], v[186:189], v[44:47]
	v_mfma_f32_16x16x32_bf16 v[40:43], v[178:181], v[186:189], v[40:43]
	v_mfma_f32_16x16x32_bf16 v[28:31], v[170:173], v[194:197], v[28:31]
	v_mfma_f32_16x16x32_bf16 v[24:27], v[178:181], v[194:197], v[24:27]
	v_mfma_f32_16x16x32_bf16 v[12:15], v[170:173], v[202:205], v[12:15]
	v_mfma_f32_16x16x32_bf16 v[8:11], v[178:181], v[202:205], v[8:11]
	v_mfma_f32_16x16x32_bf16 v[4:7], v[170:173], v[210:213], v[4:7]
	v_mfma_f32_16x16x32_bf16 v[0:3], v[178:181], v[210:213], v[0:3]
	v_mfma_f32_16x16x32_bf16 v[44:47], v[174:177], v[190:193], v[44:47]
	v_mfma_f32_16x16x32_bf16 v[40:43], v[182:185], v[190:193], v[40:43]
	v_mfma_f32_16x16x32_bf16 v[28:31], v[174:177], v[198:201], v[28:31]
	v_mfma_f32_16x16x32_bf16 v[24:27], v[182:185], v[198:201], v[24:27]
	v_mfma_f32_16x16x32_bf16 v[12:15], v[174:177], v[206:209], v[12:15]
	v_mfma_f32_16x16x32_bf16 v[8:11], v[182:185], v[206:209], v[8:11]
	v_mfma_f32_16x16x32_bf16 v[4:7], v[174:177], v[214:217], v[4:7]
	v_mfma_f32_16x16x32_bf16 v[0:3], v[182:185], v[214:217], v[0:3]
	s_barrier
	s_setprio 1
	s_add_i32 s43, 0, 0x18000
	s_add_i32 s57, 0, 0x1c000
	ds_read_b128 v[150:153], v241
	ds_read_b128 v[154:157], v241 offset:1024
	ds_read_b128 v[158:161], v241 offset:2048
	ds_read_b128 v[166:169], v241 offset:3072
	ds_read_b128 v[170:173], v242
	ds_read_b128 v[174:177], v242 offset:1024
	ds_read_b128 v[178:181], v242 offset:2048
	ds_read_b128 v[182:185], v242 offset:3072
	s_add_u32 s50, s50, 0x200000
	s_addc_u32 s51, s51, 0
	s_mov_b32 m0, s31
	ds_read_b128 v[186:189], v148 offset:32768
	ds_read_b128 v[190:193], v148 offset:33792
	ds_read_b128 v[194:197], v148 offset:34816
	ds_read_b128 v[198:201], v148 offset:35840
	ds_read_b128 v[202:205], v148 offset:36864
	ds_read_b128 v[206:209], v148 offset:37888
	ds_read_b128 v[210:213], v148 offset:38912
	ds_read_b128 v[214:217], v148 offset:39936
	global_load_lds_dwordx4 v128, s[50:51]
	s_mov_b32 m0, s33
	s_nop 0
	global_load_lds_dwordx4 v132, s[50:51]
	s_waitcnt vmcnt(8)
	s_waitcnt lgkmcnt(0)
	s_setprio 0
	s_barrier
; #define PG8_STAGE(bufoff, gbase, voff) do { _Pragma("unroll") for (int _i = 0; _i < 2; ++_i) \
;         __builtin_amdgcn_global_load_lds((const unsigned*)((const char*)(gbase) + (voff)[_i]), (PG8_LAS unsigned*)(lds + (bufoff) + ldsw + _i * 8192), 16, 0, 0); } while (0)
; #define PG8_LDA(dst, b, h) do { _Pragma("unroll") for (int m = 0; m < 4; ++m) _Pragma("unroll") for (int k = 0; k < 2; ++k) dst[m][k] = *(const PG8_LAS bf16x8*)(lds + PG8_SA(b, h) + aoff + m * 2048 + k * 1024); } while (0)
; #define PG8_MMA(ai, bj, At, Bt) do { __builtin_amdgcn_s_setprio(1); _Pragma("unroll") for (int m = 0; m < 4; ++m) _Pragma("unroll") for (int n = 0; n < 2; ++n) _Pragma("unroll") for (int k = 0; k < 2; ++k) \
;         acc[ai][bj][m][n] = __builtin_amdgcn_mfma_f32_16x16x32_bf16(Bt[n][k], At[m][k], acc[ai][bj][m][n], 0, 0, 0); __builtin_amdgcn_s_setprio(0); } while (0)
; #define PG8_WAIT_V(n) asm volatile("s_waitcnt vmcnt(" #n ")" ::: "memory")
; #define PG8_WAIT_L(n) asm volatile("s_waitcnt lgkmcnt(" #n ")" ::: "memory")
; #define PG8_BAR __builtin_amdgcn_s_barrier()
; #define PG8_SCHED __builtin_amdgcn_sched_barrier(0)
; template <class Epi, class Sched, bool ALIGN_EPI = false, bool SP2 = false>
; __device__ __forceinline__ void gemm_phase(PG8_LAS unsigned char* lds, const Gemm g, const Sched& S, const Epi& E) {
;     ...
;             PG8_WAIT_V(8); PG8_WAIT_L(0); PG8_BAR; PG8_MMA(0, 0, At, B0); PG8_MMA(0, 1, At, B1); PG8_BAR; PG8_SCHED;
;             PG8_LDA(At, 1, 1); PG8_STAGE(PG8_SB(1, 0), b3, voffB); PG8_STAGE(PG8_SB(1, 1), b3 + hstepB, voffB); PG8_STAGE(PG8_SA(1, 0), a3, voffA);
;             PG8_WAIT_V(8); PG8_WAIT_L(0); PG8_BAR; PG8_MMA(1, 0, At, B0); PG8_MMA(1, 1, At, B1); PG8_BAR; PG8_SCHED;
;     ...
;         if constexpr (ALIGN_EPI) { if (wr == 0) PG8_BAR; }
	v_mfma_f32_16x16x32_bf16 v[124:127], v[150:153], v[186:189], v[124:127]
	v_mfma_f32_16x16x32_bf16 v[120:123], v[158:161], v[186:189], v[120:123]
	v_mfma_f32_16x16x32_bf16 v[116:119], v[150:153], v[194:197], v[116:119]
	v_mfma_f32_16x16x32_bf16 v[112:115], v[158:161], v[194:197], v[112:115]
	v_mfma_f32_16x16x32_bf16 v[100:103], v[150:153], v[202:205], v[100:103]
	v_mfma_f32_16x16x32_bf16 v[96:99], v[158:161], v[202:205], v[96:99]
	v_mfma_f32_16x16x32_bf16 v[84:87], v[150:153], v[210:213], v[84:87]
	v_mfma_f32_16x16x32_bf16 v[80:83], v[158:161], v[210:213], v[80:83]
	v_mfma_f32_16x16x32_bf16 v[124:127], v[154:157], v[190:193], v[124:127]
	v_mfma_f32_16x16x32_bf16 v[120:123], v[166:169], v[190:193], v[120:123]
	v_mfma_f32_16x16x32_bf16 v[116:119], v[154:157], v[198:201], v[116:119]
	v_mfma_f32_16x16x32_bf16 v[112:115], v[166:169], v[198:201], v[112:115]
	v_mfma_f32_16x16x32_bf16 v[100:103], v[154:157], v[206:209], v[100:103]
	v_mfma_f32_16x16x32_bf16 v[96:99], v[166:169], v[206:209], v[96:99]
	v_mfma_f32_16x16x32_bf16 v[84:87], v[154:157], v[214:217], v[84:87]
	v_mfma_f32_16x16x32_bf16 v[80:83], v[166:169], v[214:217], v[80:83]
	v_mfma_f32_16x16x32_bf16 v[108:111], v[170:173], v[186:189], v[108:111]
	v_mfma_f32_16x16x32_bf16 v[104:107], v[178:181], v[186:189], v[104:107]
	v_mfma_f32_16x16x32_bf16 v[92:95], v[170:173], v[194:197], v[92:95]
	v_mfma_f32_16x16x32_bf16 v[88:91], v[178:181], v[194:197], v[88:91]
	v_mfma_f32_16x16x32_bf16 v[76:79], v[170:173], v[202:205], v[76:79]
	v_mfma_f32_16x16x32_bf16 v[72:75], v[178:181], v[202:205], v[72:75]
	v_mfma_f32_16x16x32_bf16 v[68:71], v[170:173], v[210:213], v[68:71]
	v_mfma_f32_16x16x32_bf16 v[64:67], v[178:181], v[210:213], v[64:67]
	v_mfma_f32_16x16x32_bf16 v[108:111], v[174:177], v[190:193], v[108:111]
	v_mfma_f32_16x16x32_bf16 v[104:107], v[182:185], v[190:193], v[104:107]
	v_mfma_f32_16x16x32_bf16 v[92:95], v[174:177], v[198:201], v[92:95]
	v_mfma_f32_16x16x32_bf16 v[88:91], v[182:185], v[198:201], v[88:91]
	v_mfma_f32_16x16x32_bf16 v[76:79], v[174:177], v[206:209], v[76:79]
	v_mfma_f32_16x16x32_bf16 v[72:75], v[182:185], v[206:209], v[72:75]
	v_mfma_f32_16x16x32_bf16 v[68:71], v[174:177], v[214:217], v[68:71]
	v_mfma_f32_16x16x32_bf16 v[64:67], v[182:185], v[214:217], v[64:67]
	s_barrier
	s_setprio 1
	s_add_i32 s43, s43, s30
	s_mov_b32 m0, s43
	ds_read_b128 v[186:189], v148 offset:49152
	ds_read_b128 v[190:193], v148 offset:50176
	ds_read_b128 v[194:197], v148 offset:51200
	ds_read_b128 v[198:201], v148 offset:52224
	ds_read_b128 v[202:205], v148 offset:53248
	ds_read_b128 v[206:209], v148 offset:54272
	ds_read_b128 v[210:213], v148 offset:55296
	ds_read_b128 v[214:217], v148 offset:56320
	global_load_lds_dwordx4 v130, s[98:99]
	s_add_i32 m0, s43, 0x2000
	s_add_u32 s48, s48, 0x200080
	s_addc_u32 s49, s49, 0
	s_add_i32 s43, s57, s30
	global_load_lds_dwordx4 v134, s[98:99]
	s_mov_b32 m0, s43
	s_nop 0
	global_load_lds_dwordx4 v130, s[48:49]
	s_add_i32 m0, s43, 0x2000
	s_nop 0
	global_load_lds_dwordx4 v134, s[48:49]
	s_mov_b32 m0, s35
	s_nop 0
	global_load_lds_dwordx4 v128, s[100:101]
	s_mov_b32 m0, s52
	s_nop 0
	global_load_lds_dwordx4 v132, s[100:101]
	s_waitcnt vmcnt(8)
	s_waitcnt lgkmcnt(0)
	s_setprio 0
	s_barrier
	v_mfma_f32_16x16x32_bf16 v[60:63], v[150:153], v[186:189], v[60:63]
	v_mfma_f32_16x16x32_bf16 v[56:59], v[158:161], v[186:189], v[56:59]
	v_mfma_f32_16x16x32_bf16 v[52:55], v[150:153], v[194:197], v[52:55]
	v_mfma_f32_16x16x32_bf16 v[48:51], v[158:161], v[194:197], v[48:51]
	v_mfma_f32_16x16x32_bf16 v[36:39], v[150:153], v[202:205], v[36:39]
	v_mfma_f32_16x16x32_bf16 v[32:35], v[158:161], v[202:205], v[32:35]
	v_mfma_f32_16x16x32_bf16 v[20:23], v[150:153], v[210:213], v[20:23]
	v_mfma_f32_16x16x32_bf16 v[16:19], v[158:161], v[210:213], v[16:19]
	v_mfma_f32_16x16x32_bf16 v[60:63], v[154:157], v[190:193], v[60:63]
	v_mfma_f32_16x16x32_bf16 v[56:59], v[166:169], v[190:193], v[56:59]
	v_mfma_f32_16x16x32_bf16 v[52:55], v[154:157], v[198:201], v[52:55]
	v_mfma_f32_16x16x32_bf16 v[48:51], v[166:169], v[198:201], v[48:51]
	v_mfma_f32_16x16x32_bf16 v[36:39], v[154:157], v[206:209], v[36:39]
	v_mfma_f32_16x16x32_bf16 v[32:35], v[166:169], v[206:209], v[32:35]
	v_mfma_f32_16x16x32_bf16 v[20:23], v[154:157], v[214:217], v[20:23]
	v_mfma_f32_16x16x32_bf16 v[16:19], v[166:169], v[214:217], v[16:19]
	v_mfma_f32_16x16x32_bf16 v[44:47], v[170:173], v[186:189], v[44:47]
	v_mfma_f32_16x16x32_bf16 v[40:43], v[178:181], v[186:189], v[40:43]
	v_mfma_f32_16x16x32_bf16 v[28:31], v[170:173], v[194:197], v[28:31]
	v_mfma_f32_16x16x32_bf16 v[24:27], v[178:181], v[194:197], v[24:27]
	v_mfma_f32_16x16x32_bf16 v[12:15], v[170:173], v[202:205], v[12:15]
	v_mfma_f32_16x16x32_bf16 v[8:11], v[178:181], v[202:205], v[8:11]
	v_mfma_f32_16x16x32_bf16 v[4:7], v[170:173], v[210:213], v[4:7]
	v_mfma_f32_16x16x32_bf16 v[0:3], v[178:181], v[210:213], v[0:3]
	v_mfma_f32_16x16x32_bf16 v[44:47], v[174:177], v[190:193], v[44:47]
	v_mfma_f32_16x16x32_bf16 v[40:43], v[182:185], v[190:193], v[40:43]
	v_mfma_f32_16x16x32_bf16 v[28:31], v[174:177], v[198:201], v[28:31]
	v_mfma_f32_16x16x32_bf16 v[24:27], v[182:185], v[198:201], v[24:27]
	v_mfma_f32_16x16x32_bf16 v[12:15], v[174:177], v[206:209], v[12:15]
	v_mfma_f32_16x16x32_bf16 v[8:11], v[182:185], v[206:209], v[8:11]
	v_mfma_f32_16x16x32_bf16 v[4:7], v[174:177], v[214:217], v[4:7]
	v_mfma_f32_16x16x32_bf16 v[0:3], v[182:185], v[214:217], v[0:3]
	s_barrier
	s_setprio 1
	s_add_i32 s41, s41, 2
	s_add_u32 s46, s46, 0x100
	s_addc_u32 s47, s47, 0
	s_add_u32 s19, s19, 0x100
	s_addc_u32 s39, s39, 0
	s_cmp_gt_u32 s41, 13
	s_cbranch_scc0 .LBB0_1181
	s_and_b64 vcc, exec, s[36:37]
	s_cbranch_vccz .LBB0_1184
	s_barrier

; #define PG8_STAGE(bufoff, gbase, voff) do { _Pragma("unroll") for (int _i = 0; _i < 2; ++_i) \
;         __builtin_amdgcn_global_load_lds((const unsigned*)((const char*)(gbase) + (voff)[_i]), (PG8_LAS unsigned*)(lds + (bufoff) + ldsw + _i * 8192), 16, 0, 0); } while (0)
; #define PG8_LDA(dst, b, h) do { _Pragma("unroll") for (int m = 0; m < 4; ++m) _Pragma("unroll") for (int k = 0; k < 2; ++k) dst[m][k] = *(const PG8_LAS bf16x8*)(lds + PG8_SA(b, h) + aoff + m * 2048 + k * 1024); } while (0)
; #define PG8_LDB(dst, b, h) do { _Pragma("unroll") for (int n = 0; n < 2; ++n) _Pragma("unroll") for (int k = 0; k < 2; ++k) dst[n][k] = *(const PG8_LAS bf16x8*)(lds + PG8_SB(b, h) + boff + n * 2048 + k * 1024); } while (0)
; #define PG8_WAIT_V(n) asm volatile("s_waitcnt vmcnt(" #n ")" ::: "memory")
; #define PG8_WAIT_L(n) asm volatile("s_waitcnt lgkmcnt(" #n ")" ::: "memory")
; #define PG8_BAR __builtin_amdgcn_s_barrier()
; template <class Epi, class Sched, bool ALIGN_EPI = false, bool SP2 = false>
; __device__ __forceinline__ void gemm_phase(PG8_LAS unsigned char* lds, const Gemm g, const Sched& S, const Epi& E) {
;     ...
;         const bool has_next = S.next(ui + 1, nxt);
;         const char* nA = has_next ? (const char*)g.A + (size_t)nxt.pm * tstepA + (size_t)nxt.kz * kzb : cA; const char* nB = has_next ? (const char*)g.Bt + (size_t)nxt.pn * tstepB + (size_t)nxt.kz * kzb : cB;
;         for (int t = 0; t < nt; t += 2) {
;             const bool last = (t == nt - 2);
;             const char* a1 = cA + (size_t)(t + 1) * kstep;
;             const char* a2 = last ? nA : cA + (size_t)(t + 2) * kstep; const char* b2 = last ? nB : cB + (size_t)(t + 2) * kstep;
;             const char* a3 = a2 + kstep; const char* b3 = b2 + kstep;
;             if (last && has_next) S.a_ready(nxt);
;             if constexpr (SP2) {
;             PG8_LDB(B0, 0, 0); PG8_LDB(B1, 0, 1); PG8_SCHED; PG8_LDA(At, 0, 0); PG8_STAGE(PG8_SA(1, 1), a1 + hstepA, voffA);
;             PG8_WAIT_V(8); PG8_WAIT_L(0); PG8_BAR; PG8_MMA(0, 0, At, B0); PG8_MMA(0, 1, At, B1); PG8_BAR; PG8_SCHED;
;     ...
;         for (int a = 0; a < 2; ++a)
; #pragma unroll
;             for (int b = 0; b < 2; ++b)
; #pragma unroll
;                 for (int m = 0; m < 4; ++m)
; #pragma unroll
;                     for (int n = 0; n < 2; ++n) acc[a][b][m][n] = (f32x4){0.f, 0.f, 0.f, 0.f};
.LBB0_1261:
	s_ashr_i32 s23, s22, 31
	s_lshl_b64 s[36:37], s[22:23], 17
	s_add_u32 s36, s29, s36
	s_addc_u32 s37, s30, s37
	s_and_b64 s[38:39], s[4:5], exec
	s_cselect_b32 s23, s37, s45
	s_cselect_b32 s69, s36, s44
	s_ashr_i32 s21, s20, 31
	s_lshl_b64 s[38:39], s[20:21], 17
	v_readlane_b32 s46, v240, 22
	v_readlane_b32 s47, v240, 23
	s_add_u32 s38, s46, s38
	s_addc_u32 s39, s47, s39
	s_and_b64 s[46:47], s[4:5], exec
	v_mov_b64_e32 v[0:1], 0
	s_cselect_b32 s21, s39, s43
	s_cselect_b32 s70, s38, s42
	s_mov_b32 s50, 0
	s_mov_b64 s[46:47], -1
	s_mov_b64 s[48:49], 0
	v_mov_b64_e32 v[2:3], 0
	v_mov_b64_e32 v[4:5], 0
	v_mov_b64_e32 v[6:7], 0
	v_mov_b64_e32 v[8:9], 0
	v_mov_b64_e32 v[10:11], 0
	v_mov_b64_e32 v[16:17], 0
	v_mov_b64_e32 v[18:19], 0
	v_mov_b64_e32 v[24:25], 0
	v_mov_b64_e32 v[26:27], 0
	v_mov_b64_e32 v[32:33], 0
	v_mov_b64_e32 v[34:35], 0
	v_mov_b64_e32 v[40:41], 0
	v_mov_b64_e32 v[42:43], 0
	v_mov_b64_e32 v[48:49], 0
	v_mov_b64_e32 v[50:51], 0
	v_mov_b64_e32 v[12:13], 0
	v_mov_b64_e32 v[14:15], 0
	v_mov_b64_e32 v[20:21], 0
	v_mov_b64_e32 v[22:23], 0
	v_mov_b64_e32 v[28:29], 0
	v_mov_b64_e32 v[30:31], 0
	v_mov_b64_e32 v[36:37], 0
	v_mov_b64_e32 v[38:39], 0
	v_mov_b64_e32 v[44:45], 0
	v_mov_b64_e32 v[46:47], 0
	v_mov_b64_e32 v[52:53], 0
	v_mov_b64_e32 v[54:55], 0
	v_mov_b64_e32 v[56:57], 0
	v_mov_b64_e32 v[58:59], 0
	v_mov_b64_e32 v[60:61], 0
	v_mov_b64_e32 v[62:63], 0
	v_mov_b64_e32 v[64:65], 0
	v_mov_b64_e32 v[66:67], 0
	v_mov_b64_e32 v[68:69], 0
	v_mov_b64_e32 v[70:71], 0
	v_mov_b64_e32 v[72:73], 0
	v_mov_b64_e32 v[74:75], 0
	v_mov_b64_e32 v[80:81], 0
	v_mov_b64_e32 v[82:83], 0
	v_mov_b64_e32 v[88:89], 0
	v_mov_b64_e32 v[90:91], 0
	v_mov_b64_e32 v[96:97], 0
	v_mov_b64_e32 v[98:99], 0
	v_mov_b64_e32 v[104:105], 0
	v_mov_b64_e32 v[106:107], 0
	v_mov_b64_e32 v[112:113], 0
	v_mov_b64_e32 v[114:115], 0
	v_mov_b64_e32 v[76:77], 0
	v_mov_b64_e32 v[78:79], 0
	v_mov_b64_e32 v[84:85], 0
	v_mov_b64_e32 v[86:87], 0
	v_mov_b64_e32 v[92:93], 0
	v_mov_b64_e32 v[94:95], 0
	v_mov_b64_e32 v[100:101], 0
	v_mov_b64_e32 v[102:103], 0
	v_mov_b64_e32 v[108:109], 0
	v_mov_b64_e32 v[110:111], 0
	v_mov_b64_e32 v[116:117], 0
	v_mov_b64_e32 v[118:119], 0
	v_mov_b64_e32 v[120:121], 0
	v_mov_b64_e32 v[122:123], 0
	v_mov_b64_e32 v[124:125], 0
	v_mov_b64_e32 v[126:127], 0
	v_add_u32_e32 v241, 0x18000, v143
	v_add_u32_e32 v242, 0x1c000, v143
.LBB0_1262:
	s_add_u32 s51, s44, s50
	s_addc_u32 s56, s45, 0
	s_add_u32 s54, s51, 0x100
	s_addc_u32 s55, s56, 0
	s_and_b64 s[52:53], s[48:49], exec
	s_cselect_b32 s53, s23, s55
	s_cselect_b32 s52, s69, s54
	s_add_u32 s50, s42, s50
	s_addc_u32 s54, s43, 0
	s_add_u32 s50, s50, 0x100
	s_addc_u32 s54, s54, 0
	s_and_b64 s[48:49], s[48:49], exec
	s_cselect_b32 s55, s21, s54
	s_cselect_b32 s54, s70, s50
	s_add_u32 s58, s51, 0x10080
	ds_read_b128 v[148:151], v145
	ds_read_b128 v[152:155], v145 offset:1024
	ds_read_b128 v[156:159], v145 offset:2048
	ds_read_b128 v[166:169], v145 offset:3072
	ds_read_b128 v[170:173], v146
	ds_read_b128 v[174:177], v146 offset:1024
	ds_read_b128 v[178:181], v146 offset:2048
	ds_read_b128 v[182:185], v146 offset:3072
	s_addc_u32 s59, s56, 0
	s_add_i32 s80, s63, s28
	s_add_i32 m0, s33, 0xc000
	s_add_i32 s81, s33, 0xe000
	s_add_i32 s77, s80, 0x2000
	s_add_u32 s56, s54, 0x10000
	s_addc_u32 s57, s55, 0
	s_add_i32 s79, s64, s28
	s_add_i32 s78, s79, 0x2000
	s_add_i32 s76, 0, 0x18000
	s_add_i32 s75, 0, 0x1c000
	s_add_u32 s50, s52, 0x10000
	s_addc_u32 s51, s53, 0
	s_add_i32 s74, s76, s28
	s_add_i32 s72, s74, 0x2000
	s_add_u32 s48, s54, 0x10080
	s_addc_u32 s49, s55, 0
	s_add_i32 s73, s75, s28
	s_add_i32 s71, s73, 0x2000
	ds_read_b128 v[186:189], v147
	ds_read_b128 v[190:193], v147 offset:1024
	ds_read_b128 v[194:197], v147 offset:2048
	ds_read_b128 v[198:201], v147 offset:3072
	ds_read_b128 v[202:205], v147 offset:4096
	ds_read_b128 v[206:209], v147 offset:5120
	ds_read_b128 v[210:213], v147 offset:6144
	ds_read_b128 v[214:217], v147 offset:7168
	global_load_lds_dwordx4 v134, s[58:59]
	s_mov_b32 m0, s81
	s_nop 0
	global_load_lds_dwordx4 v130, s[58:59]
	s_waitcnt vmcnt(8)
	s_waitcnt lgkmcnt(0)
	s_setprio 0
	s_barrier
	v_mfma_f32_16x16x32_bf16 v[124:127], v[148:151], v[186:189], v[124:127]
	v_mfma_f32_16x16x32_bf16 v[120:123], v[156:159], v[186:189], v[120:123]
	v_mfma_f32_16x16x32_bf16 v[116:119], v[148:151], v[194:197], v[116:119]
	v_mfma_f32_16x16x32_bf16 v[108:111], v[156:159], v[194:197], v[108:111]
	v_mfma_f32_16x16x32_bf16 v[100:103], v[148:151], v[202:205], v[100:103]
	v_mfma_f32_16x16x32_bf16 v[92:95], v[156:159], v[202:205], v[92:95]
	v_mfma_f32_16x16x32_bf16 v[84:87], v[148:151], v[210:213], v[84:87]
	v_mfma_f32_16x16x32_bf16 v[76:79], v[156:159], v[210:213], v[76:79]
	v_mfma_f32_16x16x32_bf16 v[124:127], v[152:155], v[190:193], v[124:127]
	v_mfma_f32_16x16x32_bf16 v[120:123], v[166:169], v[190:193], v[120:123]
	v_mfma_f32_16x16x32_bf16 v[116:119], v[152:155], v[198:201], v[116:119]
	v_mfma_f32_16x16x32_bf16 v[108:111], v[166:169], v[198:201], v[108:111]
	v_mfma_f32_16x16x32_bf16 v[100:103], v[152:155], v[206:209], v[100:103]
	v_mfma_f32_16x16x32_bf16 v[92:95], v[166:169], v[206:209], v[92:95]
	v_mfma_f32_16x16x32_bf16 v[84:87], v[152:155], v[214:217], v[84:87]
	v_mfma_f32_16x16x32_bf16 v[76:79], v[166:169], v[214:217], v[76:79]
	v_mfma_f32_16x16x32_bf16 v[112:115], v[170:173], v[186:189], v[112:115]
	v_mfma_f32_16x16x32_bf16 v[104:107], v[178:181], v[186:189], v[104:107]
	v_mfma_f32_16x16x32_bf16 v[96:99], v[170:173], v[194:197], v[96:99]
	v_mfma_f32_16x16x32_bf16 v[88:91], v[178:181], v[194:197], v[88:91]
	v_mfma_f32_16x16x32_bf16 v[80:83], v[170:173], v[202:205], v[80:83]
	v_mfma_f32_16x16x32_bf16 v[72:75], v[178:181], v[202:205], v[72:75]
	v_mfma_f32_16x16x32_bf16 v[68:71], v[170:173], v[210:213], v[68:71]
	v_mfma_f32_16x16x32_bf16 v[64:67], v[178:181], v[210:213], v[64:67]
	v_mfma_f32_16x16x32_bf16 v[112:115], v[174:177], v[190:193], v[112:115]
	v_mfma_f32_16x16x32_bf16 v[104:107], v[182:185], v[190:193], v[104:107]
	v_mfma_f32_16x16x32_bf16 v[96:99], v[174:177], v[198:201], v[96:99]
	v_mfma_f32_16x16x32_bf16 v[88:91], v[182:185], v[198:201], v[88:91]
	v_mfma_f32_16x16x32_bf16 v[80:83], v[174:177], v[206:209], v[80:83]
	v_mfma_f32_16x16x32_bf16 v[72:75], v[182:185], v[206:209], v[72:75]
	v_mfma_f32_16x16x32_bf16 v[68:71], v[174:177], v[214:217], v[68:71]
	v_mfma_f32_16x16x32_bf16 v[64:67], v[182:185], v[214:217], v[64:67]
	s_barrier
; #define PG8_STAGE(bufoff, gbase, voff) do { _Pragma("unroll") for (int _i = 0; _i < 2; ++_i) \
;         __builtin_amdgcn_global_load_lds((const unsigned*)((const char*)(gbase) + (voff)[_i]), (PG8_LAS unsigned*)(lds + (bufoff) + ldsw + _i * 8192), 16, 0, 0); } while (0)
; #define PG8_LDA(dst, b, h) do { _Pragma("unroll") for (int m = 0; m < 4; ++m) _Pragma("unroll") for (int k = 0; k < 2; ++k) dst[m][k] = *(const PG8_LAS bf16x8*)(lds + PG8_SA(b, h) + aoff + m * 2048 + k * 1024); } while (0)
; #define PG8_LDB(dst, b, h) do { _Pragma("unroll") for (int n = 0; n < 2; ++n) _Pragma("unroll") for (int k = 0; k < 2; ++k) dst[n][k] = *(const PG8_LAS bf16x8*)(lds + PG8_SB(b, h) + boff + n * 2048 + k * 1024); } while (0)
; #define PG8_MMA(ai, bj, At, Bt) do { __builtin_amdgcn_s_setprio(1); _Pragma("unroll") for (int m = 0; m < 4; ++m) _Pragma("unroll") for (int n = 0; n < 2; ++n) _Pragma("unroll") for (int k = 0; k < 2; ++k) \
;         acc[ai][bj][m][n] = __builtin_amdgcn_mfma_f32_16x16x32_bf16(Bt[n][k], At[m][k], acc[ai][bj][m][n], 0, 0, 0); __builtin_amdgcn_s_setprio(0); } while (0)
; #define PG8_WAIT_V(n) asm volatile("s_waitcnt vmcnt(" #n ")" ::: "memory")
; #define PG8_WAIT_L(n) asm volatile("s_waitcnt lgkmcnt(" #n ")" ::: "memory")
; #define PG8_BAR __builtin_amdgcn_s_barrier()
; #define PG8_SCHED __builtin_amdgcn_sched_barrier(0)
; template <class Epi, class Sched, bool ALIGN_EPI = false, bool SP2 = false>
; __device__ __forceinline__ void gemm_phase(PG8_LAS unsigned char* lds, const Gemm g, const Sched& S, const Epi& E) {
;     ...
;             PG8_LDA(At, 0, 1); PG8_STAGE(PG8_SB(0, 0), b2, voffB); PG8_STAGE(PG8_SB(0, 1), b2 + hstepB, voffB); PG8_STAGE(PG8_SA(0, 0), a2, voffA);
;             PG8_WAIT_V(8); PG8_WAIT_L(0); PG8_BAR; PG8_MMA(1, 0, At, B0); PG8_MMA(1, 1, At, B1); PG8_BAR; PG8_SCHED;
;             PG8_LDB(B0, 1, 0); PG8_LDB(B1, 1, 1); PG8_SCHED; PG8_LDA(At, 1, 0); PG8_STAGE(PG8_SA(0, 1), a2 + hstepA, voffA);
	s_setprio 1
	s_add_u32 s98, s54, s8
	s_addc_u32 s99, s55, s9
	s_add_u32 s100, s52, s8
	s_addc_u32 s101, s53, s9
	s_mov_b32 m0, s80
	ds_read_b128 v[186:189], v147 offset:16384
	ds_read_b128 v[190:193], v147 offset:17408
	ds_read_b128 v[194:197], v147 offset:18432
	ds_read_b128 v[198:201], v147 offset:19456
	ds_read_b128 v[202:205], v147 offset:20480
	ds_read_b128 v[206:209], v147 offset:21504
	ds_read_b128 v[210:213], v147 offset:22528
	ds_read_b128 v[214:217], v147 offset:23552
	global_load_lds_dwordx4 v132, s[54:55]
	s_mov_b32 m0, s77
	s_nop 0
	global_load_lds_dwordx4 v128, s[54:55]
	s_mov_b32 m0, s79
	s_nop 0
	global_load_lds_dwordx4 v132, s[56:57]
	s_mov_b32 m0, s78
	s_nop 0
	global_load_lds_dwordx4 v128, s[56:57]
	s_mov_b32 m0, s33
	s_nop 0
	global_load_lds_dwordx4 v134, s[52:53]
	s_mov_b32 m0, s34
	s_nop 0
	global_load_lds_dwordx4 v130, s[52:53]
	s_waitcnt vmcnt(8)
	s_waitcnt lgkmcnt(0)
	s_setprio 0
	s_barrier
	v_mfma_f32_16x16x32_bf16 v[60:63], v[148:151], v[186:189], v[60:63]
	v_mfma_f32_16x16x32_bf16 v[56:59], v[156:159], v[186:189], v[56:59]
	v_mfma_f32_16x16x32_bf16 v[52:55], v[148:151], v[194:197], v[52:55]
	v_mfma_f32_16x16x32_bf16 v[44:47], v[156:159], v[194:197], v[44:47]
	v_mfma_f32_16x16x32_bf16 v[36:39], v[148:151], v[202:205], v[36:39]
	v_mfma_f32_16x16x32_bf16 v[28:31], v[156:159], v[202:205], v[28:31]
	v_mfma_f32_16x16x32_bf16 v[20:23], v[148:151], v[210:213], v[20:23]
	v_mfma_f32_16x16x32_bf16 v[12:15], v[156:159], v[210:213], v[12:15]
	v_mfma_f32_16x16x32_bf16 v[60:63], v[152:155], v[190:193], v[60:63]
	v_mfma_f32_16x16x32_bf16 v[56:59], v[166:169], v[190:193], v[56:59]
	v_mfma_f32_16x16x32_bf16 v[52:55], v[152:155], v[198:201], v[52:55]
	v_mfma_f32_16x16x32_bf16 v[44:47], v[166:169], v[198:201], v[44:47]
	v_mfma_f32_16x16x32_bf16 v[36:39], v[152:155], v[206:209], v[36:39]
	v_mfma_f32_16x16x32_bf16 v[28:31], v[166:169], v[206:209], v[28:31]
	v_mfma_f32_16x16x32_bf16 v[20:23], v[152:155], v[214:217], v[20:23]
	v_mfma_f32_16x16x32_bf16 v[12:15], v[166:169], v[214:217], v[12:15]
	v_mfma_f32_16x16x32_bf16 v[48:51], v[170:173], v[186:189], v[48:51]
	v_mfma_f32_16x16x32_bf16 v[40:43], v[178:181], v[186:189], v[40:43]
	v_mfma_f32_16x16x32_bf16 v[32:35], v[170:173], v[194:197], v[32:35]
	v_mfma_f32_16x16x32_bf16 v[24:27], v[178:181], v[194:197], v[24:27]
	v_mfma_f32_16x16x32_bf16 v[16:19], v[170:173], v[202:205], v[16:19]
	v_mfma_f32_16x16x32_bf16 v[8:11], v[178:181], v[202:205], v[8:11]
	v_mfma_f32_16x16x32_bf16 v[4:7], v[170:173], v[210:213], v[4:7]
	v_mfma_f32_16x16x32_bf16 v[0:3], v[178:181], v[210:213], v[0:3]
	v_mfma_f32_16x16x32_bf16 v[48:51], v[174:177], v[190:193], v[48:51]
	v_mfma_f32_16x16x32_bf16 v[40:43], v[182:185], v[190:193], v[40:43]
	v_mfma_f32_16x16x32_bf16 v[32:35], v[174:177], v[198:201], v[32:35]
	v_mfma_f32_16x16x32_bf16 v[24:27], v[182:185], v[198:201], v[24:27]
	v_mfma_f32_16x16x32_bf16 v[16:19], v[174:177], v[206:209], v[16:19]
	v_mfma_f32_16x16x32_bf16 v[8:11], v[182:185], v[206:209], v[8:11]
	v_mfma_f32_16x16x32_bf16 v[4:7], v[174:177], v[214:217], v[4:7]
	v_mfma_f32_16x16x32_bf16 v[0:3], v[182:185], v[214:217], v[0:3]
	s_barrier
	s_setprio 1
	ds_read_b128 v[148:151], v241
	ds_read_b128 v[152:155], v241 offset:1024
	ds_read_b128 v[156:159], v241 offset:2048
	ds_read_b128 v[166:169], v241 offset:3072
	ds_read_b128 v[170:173], v242
	ds_read_b128 v[174:177], v242 offset:1024
	ds_read_b128 v[178:181], v242 offset:2048
	ds_read_b128 v[182:185], v242 offset:3072
	s_mov_b32 m0, s35
	ds_read_b128 v[186:189], v147 offset:32768
	ds_read_b128 v[190:193], v147 offset:33792
	ds_read_b128 v[194:197], v147 offset:34816
	ds_read_b128 v[198:201], v147 offset:35840
	ds_read_b128 v[202:205], v147 offset:36864
	ds_read_b128 v[206:209], v147 offset:37888
	ds_read_b128 v[210:213], v147 offset:38912
	ds_read_b128 v[214:217], v147 offset:39936
	global_load_lds_dwordx4 v134, s[50:51]
	s_mov_b32 m0, s41
	s_nop 0
	global_load_lds_dwordx4 v130, s[50:51]
	s_waitcnt vmcnt(8)
	s_waitcnt lgkmcnt(0)
	s_setprio 0
	s_barrier
; #define PG8_STAGE(bufoff, gbase, voff) do { _Pragma("unroll") for (int _i = 0; _i < 2; ++_i) \
;         __builtin_amdgcn_global_load_lds((const unsigned*)((const char*)(gbase) + (voff)[_i]), (PG8_LAS unsigned*)(lds + (bufoff) + ldsw + _i * 8192), 16, 0, 0); } while (0)
; #define PG8_LDA(dst, b, h) do { _Pragma("unroll") for (int m = 0; m < 4; ++m) _Pragma("unroll") for (int k = 0; k < 2; ++k) dst[m][k] = *(const PG8_LAS bf16x8*)(lds + PG8_SA(b, h) + aoff + m * 2048 + k * 1024); } while (0)
; #define PG8_MMA(ai, bj, At, Bt) do { __builtin_amdgcn_s_setprio(1); _Pragma("unroll") for (int m = 0; m < 4; ++m) _Pragma("unroll") for (int n = 0; n < 2; ++n) _Pragma("unroll") for (int k = 0; k < 2; ++k) \
;         acc[ai][bj][m][n] = __builtin_amdgcn_mfma_f32_16x16x32_bf16(Bt[n][k], At[m][k], acc[ai][bj][m][n], 0, 0, 0); __builtin_amdgcn_s_setprio(0); } while (0)
; #define PG8_WAIT_V(n) asm volatile("s_waitcnt vmcnt(" #n ")" ::: "memory")
; #define PG8_WAIT_L(n) asm volatile("s_waitcnt lgkmcnt(" #n ")" ::: "memory")
; #define PG8_BAR __builtin_amdgcn_s_barrier()
; #define PG8_SCHED __builtin_amdgcn_sched_barrier(0)
; template <class Epi, class Sched, bool ALIGN_EPI = false, bool SP2 = false>
; __device__ __forceinline__ void gemm_phase(PG8_LAS unsigned char* lds, const Gemm g, const Sched& S, const Epi& E) {
;     ...
;             PG8_WAIT_V(8); PG8_WAIT_L(0); PG8_BAR; PG8_MMA(0, 0, At, B0); PG8_MMA(0, 1, At, B1); PG8_BAR; PG8_SCHED;
;             PG8_LDA(At, 1, 1); PG8_STAGE(PG8_SB(1, 0), b3, voffB); PG8_STAGE(PG8_SB(1, 1), b3 + hstepB, voffB); PG8_STAGE(PG8_SA(1, 0), a3, voffA);
;             PG8_WAIT_V(8); PG8_WAIT_L(0); PG8_BAR; PG8_MMA(1, 0, At, B0); PG8_MMA(1, 1, At, B1); PG8_BAR; PG8_SCHED;
;     ...
;         if constexpr (ALIGN_EPI) { if (wr == 0) PG8_BAR; }
	v_mfma_f32_16x16x32_bf16 v[124:127], v[148:151], v[186:189], v[124:127]
	v_mfma_f32_16x16x32_bf16 v[120:123], v[156:159], v[186:189], v[120:123]
	v_mfma_f32_16x16x32_bf16 v[116:119], v[148:151], v[194:197], v[116:119]
	v_mfma_f32_16x16x32_bf16 v[108:111], v[156:159], v[194:197], v[108:111]
	v_mfma_f32_16x16x32_bf16 v[100:103], v[148:151], v[202:205], v[100:103]
	v_mfma_f32_16x16x32_bf16 v[92:95], v[156:159], v[202:205], v[92:95]
	v_mfma_f32_16x16x32_bf16 v[84:87], v[148:151], v[210:213], v[84:87]
	v_mfma_f32_16x16x32_bf16 v[76:79], v[156:159], v[210:213], v[76:79]
	v_mfma_f32_16x16x32_bf16 v[124:127], v[152:155], v[190:193], v[124:127]
	v_mfma_f32_16x16x32_bf16 v[120:123], v[166:169], v[190:193], v[120:123]
	v_mfma_f32_16x16x32_bf16 v[116:119], v[152:155], v[198:201], v[116:119]
	v_mfma_f32_16x16x32_bf16 v[108:111], v[166:169], v[198:201], v[108:111]
	v_mfma_f32_16x16x32_bf16 v[100:103], v[152:155], v[206:209], v[100:103]
	v_mfma_f32_16x16x32_bf16 v[92:95], v[166:169], v[206:209], v[92:95]
	v_mfma_f32_16x16x32_bf16 v[84:87], v[152:155], v[214:217], v[84:87]
	v_mfma_f32_16x16x32_bf16 v[76:79], v[166:169], v[214:217], v[76:79]
	v_mfma_f32_16x16x32_bf16 v[112:115], v[170:173], v[186:189], v[112:115]
	v_mfma_f32_16x16x32_bf16 v[104:107], v[178:181], v[186:189], v[104:107]
	v_mfma_f32_16x16x32_bf16 v[96:99], v[170:173], v[194:197], v[96:99]
	v_mfma_f32_16x16x32_bf16 v[88:91], v[178:181], v[194:197], v[88:91]
	v_mfma_f32_16x16x32_bf16 v[80:83], v[170:173], v[202:205], v[80:83]
	v_mfma_f32_16x16x32_bf16 v[72:75], v[178:181], v[202:205], v[72:75]
	v_mfma_f32_16x16x32_bf16 v[68:71], v[170:173], v[210:213], v[68:71]
	v_mfma_f32_16x16x32_bf16 v[64:67], v[178:181], v[210:213], v[64:67]
	v_mfma_f32_16x16x32_bf16 v[112:115], v[174:177], v[190:193], v[112:115]
	v_mfma_f32_16x16x32_bf16 v[104:107], v[182:185], v[190:193], v[104:107]
	v_mfma_f32_16x16x32_bf16 v[96:99], v[174:177], v[198:201], v[96:99]
	v_mfma_f32_16x16x32_bf16 v[88:91], v[182:185], v[198:201], v[88:91]
	v_mfma_f32_16x16x32_bf16 v[80:83], v[174:177], v[206:209], v[80:83]
	v_mfma_f32_16x16x32_bf16 v[72:75], v[182:185], v[206:209], v[72:75]
	v_mfma_f32_16x16x32_bf16 v[68:71], v[174:177], v[214:217], v[68:71]
	v_mfma_f32_16x16x32_bf16 v[64:67], v[182:185], v[214:217], v[64:67]
	s_barrier
	s_setprio 1
	s_mov_b32 m0, s74
	ds_read_b128 v[186:189], v147 offset:49152
	ds_read_b128 v[190:193], v147 offset:50176
	ds_read_b128 v[194:197], v147 offset:51200
	ds_read_b128 v[198:201], v147 offset:52224
	ds_read_b128 v[202:205], v147 offset:53248
	ds_read_b128 v[206:209], v147 offset:54272
	ds_read_b128 v[210:213], v147 offset:55296
	ds_read_b128 v[214:217], v147 offset:56320
	global_load_lds_dwordx4 v132, s[98:99]
	s_mov_b32 m0, s72
	s_nop 0
	global_load_lds_dwordx4 v128, s[98:99]
	s_mov_b32 m0, s73
	s_nop 0
	global_load_lds_dwordx4 v132, s[48:49]
	s_mov_b32 m0, s71
	s_nop 0
	global_load_lds_dwordx4 v128, s[48:49]
	s_mov_b32 m0, s61
	s_nop 0
	global_load_lds_dwordx4 v134, s[100:101]
	s_mov_b32 m0, s62
	s_nop 0
	global_load_lds_dwordx4 v130, s[100:101]
	s_waitcnt vmcnt(8)
	s_waitcnt lgkmcnt(0)
	s_setprio 0
	s_barrier
	v_mfma_f32_16x16x32_bf16 v[60:63], v[148:151], v[186:189], v[60:63]
	v_mfma_f32_16x16x32_bf16 v[56:59], v[156:159], v[186:189], v[56:59]
	v_mfma_f32_16x16x32_bf16 v[52:55], v[148:151], v[194:197], v[52:55]
	v_mfma_f32_16x16x32_bf16 v[44:47], v[156:159], v[194:197], v[44:47]
	v_mfma_f32_16x16x32_bf16 v[36:39], v[148:151], v[202:205], v[36:39]
	v_mfma_f32_16x16x32_bf16 v[28:31], v[156:159], v[202:205], v[28:31]
	v_mfma_f32_16x16x32_bf16 v[20:23], v[148:151], v[210:213], v[20:23]
	v_mfma_f32_16x16x32_bf16 v[12:15], v[156:159], v[210:213], v[12:15]
	v_mfma_f32_16x16x32_bf16 v[60:63], v[152:155], v[190:193], v[60:63]
	v_mfma_f32_16x16x32_bf16 v[56:59], v[166:169], v[190:193], v[56:59]
	v_mfma_f32_16x16x32_bf16 v[52:55], v[152:155], v[198:201], v[52:55]
	v_mfma_f32_16x16x32_bf16 v[44:47], v[166:169], v[198:201], v[44:47]
	v_mfma_f32_16x16x32_bf16 v[36:39], v[152:155], v[206:209], v[36:39]
	v_mfma_f32_16x16x32_bf16 v[28:31], v[166:169], v[206:209], v[28:31]
	v_mfma_f32_16x16x32_bf16 v[20:23], v[152:155], v[214:217], v[20:23]
	v_mfma_f32_16x16x32_bf16 v[12:15], v[166:169], v[214:217], v[12:15]
	v_mfma_f32_16x16x32_bf16 v[48:51], v[170:173], v[186:189], v[48:51]
	v_mfma_f32_16x16x32_bf16 v[40:43], v[178:181], v[186:189], v[40:43]
	v_mfma_f32_16x16x32_bf16 v[32:35], v[170:173], v[194:197], v[32:35]
	v_mfma_f32_16x16x32_bf16 v[24:27], v[178:181], v[194:197], v[24:27]
	v_mfma_f32_16x16x32_bf16 v[16:19], v[170:173], v[202:205], v[16:19]
	v_mfma_f32_16x16x32_bf16 v[8:11], v[178:181], v[202:205], v[8:11]
	v_mfma_f32_16x16x32_bf16 v[4:7], v[170:173], v[210:213], v[4:7]
	v_mfma_f32_16x16x32_bf16 v[0:3], v[178:181], v[210:213], v[0:3]
	v_mfma_f32_16x16x32_bf16 v[48:51], v[174:177], v[190:193], v[48:51]
	v_mfma_f32_16x16x32_bf16 v[40:43], v[182:185], v[190:193], v[40:43]
	v_mfma_f32_16x16x32_bf16 v[32:35], v[174:177], v[198:201], v[32:35]
	v_mfma_f32_16x16x32_bf16 v[24:27], v[182:185], v[198:201], v[24:27]
	v_mfma_f32_16x16x32_bf16 v[16:19], v[174:177], v[206:209], v[16:19]
	v_mfma_f32_16x16x32_bf16 v[8:11], v[182:185], v[206:209], v[8:11]
	v_mfma_f32_16x16x32_bf16 v[4:7], v[174:177], v[214:217], v[4:7]
	v_mfma_f32_16x16x32_bf16 v[0:3], v[182:185], v[214:217], v[0:3]
	s_barrier
	s_setprio 1
	s_movk_i32 s50, 0x100
	s_andn2_b64 vcc, exec, s[46:47]
	s_mov_b64 s[48:49], -1
	s_mov_b64 s[46:47], 0
	s_cbranch_vccz .LBB0_1262
	s_and_b64 vcc, exec, s[10:11]
	s_cbranch_vccz .LBB0_1265
	s_barrier

; #define PG8_STAGE(bufoff, gbase, voff) do { _Pragma("unroll") for (int _i = 0; _i < 2; ++_i) \
;         __builtin_amdgcn_global_load_lds((const unsigned*)((const char*)(gbase) + (voff)[_i]), (PG8_LAS unsigned*)(lds + (bufoff) + ldsw + _i * 8192), 16, 0, 0); } while (0)
; #define PG8_LDA(dst, b, h) do { _Pragma("unroll") for (int m = 0; m < 4; ++m) _Pragma("unroll") for (int k = 0; k < 2; ++k) dst[m][k] = *(const PG8_LAS bf16x8*)(lds + PG8_SA(b, h) + aoff + m * 2048 + k * 1024); } while (0)
; #define PG8_LDB(dst, b, h) do { _Pragma("unroll") for (int n = 0; n < 2; ++n) _Pragma("unroll") for (int k = 0; k < 2; ++k) dst[n][k] = *(const PG8_LAS bf16x8*)(lds + PG8_SB(b, h) + boff + n * 2048 + k * 1024); } while (0)
; #define PG8_WAIT_V(n) asm volatile("s_waitcnt vmcnt(" #n ")" ::: "memory")
; #define PG8_WAIT_L(n) asm volatile("s_waitcnt lgkmcnt(" #n ")" ::: "memory")
; #define PG8_BAR __builtin_amdgcn_s_barrier()
; template <class Epi, class Sched, bool ALIGN_EPI = false, bool SP2 = false>
; __device__ __forceinline__ void gemm_phase(PG8_LAS unsigned char* lds, const Gemm g, const Sched& S, const Epi& E) {
;     ...
;         const bool has_next = S.next(ui + 1, nxt);
;         const char* nA = has_next ? (const char*)g.A + (size_t)nxt.pm * tstepA + (size_t)nxt.kz * kzb : cA; const char* nB = has_next ? (const char*)g.Bt + (size_t)nxt.pn * tstepB + (size_t)nxt.kz * kzb : cB;
;         for (int t = 0; t < nt; t += 2) {
;             const bool last = (t == nt - 2);
;             const char* a1 = cA + (size_t)(t + 1) * kstep;
;             const char* a2 = last ? nA : cA + (size_t)(t + 2) * kstep; const char* b2 = last ? nB : cB + (size_t)(t + 2) * kstep;
;             const char* a3 = a2 + kstep; const char* b3 = b2 + kstep;
;             if (last && has_next) S.a_ready(nxt);
;             if constexpr (SP2) {
;             PG8_LDB(B0, 0, 0); PG8_LDB(B1, 0, 1); PG8_SCHED; PG8_LDA(At, 0, 0); PG8_STAGE(PG8_SA(1, 1), a1 + hstepA, voffA);
;             PG8_WAIT_V(8); PG8_WAIT_L(0); PG8_BAR; PG8_MMA(0, 0, At, B0); PG8_MMA(0, 1, At, B1); PG8_BAR; PG8_SCHED;
;     ...
;         for (int a = 0; a < 2; ++a)
; #pragma unroll
;             for (int b = 0; b < 2; ++b)
; #pragma unroll
;                 for (int m = 0; m < 4; ++m)
; #pragma unroll
;                     for (int n = 0; n < 2; ++n) acc[a][b][m][n] = (f32x4){0.f, 0.f, 0.f, 0.f};
.LBB0_1332:
	s_ashr_i32 s37, s36, 31
	s_lshl_b64 s[38:39], s[36:37], 20
	v_readlane_b32 s40, v240, 26
	v_readlane_b32 s41, v240, 27
	s_add_u32 s38, s40, s38
	s_addc_u32 s39, s41, s39
	s_and_b64 s[40:41], s[4:5], exec
	s_cselect_b32 s37, s39, s45
	s_cselect_b32 s58, s38, s44
	s_ashr_i32 s23, s22, 31
	s_lshl_b64 s[40:41], s[22:23], 20
	v_readlane_b32 s48, v240, 24
	v_readlane_b32 s49, v240, 25
	s_add_u32 s40, s48, s40
	s_addc_u32 s41, s49, s41
	s_and_b64 s[48:49], s[4:5], exec
	s_cselect_b32 s23, s41, s47
	s_cselect_b32 s59, s40, s46
	s_add_u32 s44, s44, 0x80080
	s_addc_u32 s45, s45, 0
	s_add_u32 s60, s46, 0x100
	v_mov_b64_e32 v[0:1], 0
	s_addc_u32 s61, s47, 0
	s_mov_b32 s62, -2
	v_mov_b64_e32 v[2:3], 0
	v_mov_b64_e32 v[4:5], 0
	v_mov_b64_e32 v[6:7], 0
	v_mov_b64_e32 v[16:17], 0
	v_mov_b64_e32 v[18:19], 0
	v_mov_b64_e32 v[20:21], 0
	v_mov_b64_e32 v[22:23], 0
	v_mov_b64_e32 v[32:33], 0
	v_mov_b64_e32 v[34:35], 0
	v_mov_b64_e32 v[36:37], 0
	v_mov_b64_e32 v[38:39], 0
	v_mov_b64_e32 v[48:49], 0
	v_mov_b64_e32 v[50:51], 0
	v_mov_b64_e32 v[52:53], 0
	v_mov_b64_e32 v[54:55], 0
	v_mov_b64_e32 v[8:9], 0
	v_mov_b64_e32 v[10:11], 0
	v_mov_b64_e32 v[12:13], 0
	v_mov_b64_e32 v[14:15], 0
	v_mov_b64_e32 v[24:25], 0
	v_mov_b64_e32 v[26:27], 0
	v_mov_b64_e32 v[28:29], 0
	v_mov_b64_e32 v[30:31], 0
	v_mov_b64_e32 v[40:41], 0
	v_mov_b64_e32 v[42:43], 0
	v_mov_b64_e32 v[44:45], 0
	v_mov_b64_e32 v[46:47], 0
	v_mov_b64_e32 v[56:57], 0
	v_mov_b64_e32 v[58:59], 0
	v_mov_b64_e32 v[60:61], 0
	v_mov_b64_e32 v[62:63], 0
	v_mov_b64_e32 v[64:65], 0
	v_mov_b64_e32 v[66:67], 0
	v_mov_b64_e32 v[68:69], 0
	v_mov_b64_e32 v[70:71], 0
	v_mov_b64_e32 v[80:81], 0
	v_mov_b64_e32 v[82:83], 0
	v_mov_b64_e32 v[84:85], 0
	v_mov_b64_e32 v[86:87], 0
	v_mov_b64_e32 v[96:97], 0
	v_mov_b64_e32 v[98:99], 0
	v_mov_b64_e32 v[100:101], 0
	v_mov_b64_e32 v[102:103], 0
	v_mov_b64_e32 v[112:113], 0
	v_mov_b64_e32 v[114:115], 0
	v_mov_b64_e32 v[116:117], 0
	v_mov_b64_e32 v[118:119], 0
	v_mov_b64_e32 v[72:73], 0
	v_mov_b64_e32 v[74:75], 0
	v_mov_b64_e32 v[76:77], 0
	v_mov_b64_e32 v[78:79], 0
	v_mov_b64_e32 v[88:89], 0
	v_mov_b64_e32 v[90:91], 0
	v_mov_b64_e32 v[92:93], 0
	v_mov_b64_e32 v[94:95], 0
	v_mov_b64_e32 v[104:105], 0
	v_mov_b64_e32 v[106:107], 0
	v_mov_b64_e32 v[108:109], 0
	v_mov_b64_e32 v[110:111], 0
	v_mov_b64_e32 v[120:121], 0
	v_mov_b64_e32 v[122:123], 0
	v_mov_b64_e32 v[124:125], 0
	v_mov_b64_e32 v[126:127], 0
	v_add_u32_e32 v241, 0x18000, v151
	v_add_u32_e32 v242, 0x1c000, v151
.LBB0_1333:
	ds_read_b128 v[144:147], v153
	ds_read_b128 v[156:159], v153 offset:1024
	ds_read_b128 v[166:169], v153 offset:2048
	ds_read_b128 v[170:173], v153 offset:3072
	ds_read_b128 v[174:177], v154
	ds_read_b128 v[178:181], v154 offset:1024
	ds_read_b128 v[182:185], v154 offset:2048
	ds_read_b128 v[186:189], v154 offset:3072
	s_add_u32 s46, s44, 0xfff80080
	s_addc_u32 s47, s45, -1
	s_cmp_eq_u32 s62, 28
	s_cselect_b32 s49, s37, s47
	s_cselect_b32 s48, s58, s46
	s_cselect_b32 s47, s23, s61
	s_cselect_b32 s46, s59, s60
	s_add_i32 m0, s30, 0xc000
	ds_read_b128 v[190:193], v155
	ds_read_b128 v[194:197], v155 offset:1024
	ds_read_b128 v[198:201], v155 offset:2048
	ds_read_b128 v[202:205], v155 offset:3072
	ds_read_b128 v[206:209], v155 offset:4096
	ds_read_b128 v[210:213], v155 offset:5120
	ds_read_b128 v[214:217], v155 offset:6144
	ds_read_b128 v[218:221], v155 offset:7168
	global_load_lds_dwordx4 v136, s[44:45]
	s_add_i32 m0, s30, 0xe000
	s_nop 0
	global_load_lds_dwordx4 v138, s[44:45]
	s_waitcnt vmcnt(8)
	s_waitcnt lgkmcnt(0)
	s_setprio 0
	s_barrier
	v_mfma_f32_16x16x32_bf16 v[124:127], v[144:147], v[190:193], v[124:127]
	v_mfma_f32_16x16x32_bf16 v[120:123], v[166:169], v[190:193], v[120:123]
	v_mfma_f32_16x16x32_bf16 v[108:111], v[144:147], v[198:201], v[108:111]
	v_mfma_f32_16x16x32_bf16 v[104:107], v[166:169], v[198:201], v[104:107]
	v_mfma_f32_16x16x32_bf16 v[92:95], v[144:147], v[206:209], v[92:95]
	v_mfma_f32_16x16x32_bf16 v[88:91], v[166:169], v[206:209], v[88:91]
	v_mfma_f32_16x16x32_bf16 v[76:79], v[144:147], v[214:217], v[76:79]
	v_mfma_f32_16x16x32_bf16 v[72:75], v[166:169], v[214:217], v[72:75]
	v_mfma_f32_16x16x32_bf16 v[124:127], v[156:159], v[194:197], v[124:127]
	v_mfma_f32_16x16x32_bf16 v[120:123], v[170:173], v[194:197], v[120:123]
	v_mfma_f32_16x16x32_bf16 v[108:111], v[156:159], v[202:205], v[108:111]
	v_mfma_f32_16x16x32_bf16 v[104:107], v[170:173], v[202:205], v[104:107]
	v_mfma_f32_16x16x32_bf16 v[92:95], v[156:159], v[210:213], v[92:95]
	v_mfma_f32_16x16x32_bf16 v[88:91], v[170:173], v[210:213], v[88:91]
	v_mfma_f32_16x16x32_bf16 v[76:79], v[156:159], v[218:221], v[76:79]
	v_mfma_f32_16x16x32_bf16 v[72:75], v[170:173], v[218:221], v[72:75]
	v_mfma_f32_16x16x32_bf16 v[116:119], v[174:177], v[190:193], v[116:119]
	v_mfma_f32_16x16x32_bf16 v[112:115], v[182:185], v[190:193], v[112:115]
	v_mfma_f32_16x16x32_bf16 v[100:103], v[174:177], v[198:201], v[100:103]
	v_mfma_f32_16x16x32_bf16 v[96:99], v[182:185], v[198:201], v[96:99]
	v_mfma_f32_16x16x32_bf16 v[84:87], v[174:177], v[206:209], v[84:87]
	v_mfma_f32_16x16x32_bf16 v[80:83], v[182:185], v[206:209], v[80:83]
	v_mfma_f32_16x16x32_bf16 v[68:71], v[174:177], v[214:217], v[68:71]
	v_mfma_f32_16x16x32_bf16 v[64:67], v[182:185], v[214:217], v[64:67]
	v_mfma_f32_16x16x32_bf16 v[116:119], v[178:181], v[194:197], v[116:119]
	v_mfma_f32_16x16x32_bf16 v[112:115], v[186:189], v[194:197], v[112:115]
	v_mfma_f32_16x16x32_bf16 v[100:103], v[178:181], v[202:205], v[100:103]
	v_mfma_f32_16x16x32_bf16 v[96:99], v[186:189], v[202:205], v[96:99]
	v_mfma_f32_16x16x32_bf16 v[84:87], v[178:181], v[210:213], v[84:87]
	v_mfma_f32_16x16x32_bf16 v[80:83], v[186:189], v[210:213], v[80:83]
	v_mfma_f32_16x16x32_bf16 v[68:71], v[178:181], v[218:221], v[68:71]
	v_mfma_f32_16x16x32_bf16 v[64:67], v[186:189], v[218:221], v[64:67]
	s_barrier
; #define PG8_STAGE(bufoff, gbase, voff) do { _Pragma("unroll") for (int _i = 0; _i < 2; ++_i) \
;         __builtin_amdgcn_global_load_lds((const unsigned*)((const char*)(gbase) + (voff)[_i]), (PG8_LAS unsigned*)(lds + (bufoff) + ldsw + _i * 8192), 16, 0, 0); } while (0)
; #define PG8_LDA(dst, b, h) do { _Pragma("unroll") for (int m = 0; m < 4; ++m) _Pragma("unroll") for (int k = 0; k < 2; ++k) dst[m][k] = *(const PG8_LAS bf16x8*)(lds + PG8_SA(b, h) + aoff + m * 2048 + k * 1024); } while (0)
; #define PG8_LDB(dst, b, h) do { _Pragma("unroll") for (int n = 0; n < 2; ++n) _Pragma("unroll") for (int k = 0; k < 2; ++k) dst[n][k] = *(const PG8_LAS bf16x8*)(lds + PG8_SB(b, h) + boff + n * 2048 + k * 1024); } while (0)
; #define PG8_MMA(ai, bj, At, Bt) do { __builtin_amdgcn_s_setprio(1); _Pragma("unroll") for (int m = 0; m < 4; ++m) _Pragma("unroll") for (int n = 0; n < 2; ++n) _Pragma("unroll") for (int k = 0; k < 2; ++k) \
;         acc[ai][bj][m][n] = __builtin_amdgcn_mfma_f32_16x16x32_bf16(Bt[n][k], At[m][k], acc[ai][bj][m][n], 0, 0, 0); __builtin_amdgcn_s_setprio(0); } while (0)
; #define PG8_WAIT_V(n) asm volatile("s_waitcnt vmcnt(" #n ")" ::: "memory")
; #define PG8_WAIT_L(n) asm volatile("s_waitcnt lgkmcnt(" #n ")" ::: "memory")
; #define PG8_BAR __builtin_amdgcn_s_barrier()
; #define PG8_SCHED __builtin_amdgcn_sched_barrier(0)
; template <class Epi, class Sched, bool ALIGN_EPI = false, bool SP2 = false>
; __device__ __forceinline__ void gemm_phase(PG8_LAS unsigned char* lds, const Gemm g, const Sched& S, const Epi& E) {
;     ...
;             PG8_LDA(At, 0, 1); PG8_STAGE(PG8_SB(0, 0), b2, voffB); PG8_STAGE(PG8_SB(0, 1), b2 + hstepB, voffB); PG8_STAGE(PG8_SA(0, 0), a2, voffA);
;             PG8_WAIT_V(8); PG8_WAIT_L(0); PG8_BAR; PG8_MMA(1, 0, At, B0); PG8_MMA(1, 1, At, B1); PG8_BAR; PG8_SCHED;
;             PG8_LDB(B0, 1, 0); PG8_LDB(B1, 1, 1); PG8_SCHED; PG8_LDA(At, 1, 0); PG8_STAGE(PG8_SA(0, 1), a2 + hstepA, voffA);
	s_setprio 1
	s_add_u32 s98, s46, s10
	s_addc_u32 s99, s47, s11
	s_add_u32 s100, s48, s10
	s_addc_u32 s101, s49, s11
	s_add_i32 s63, s51, s28
	s_mov_b32 m0, s63
	ds_read_b128 v[190:193], v155 offset:16384
	ds_read_b128 v[194:197], v155 offset:17408
	ds_read_b128 v[198:201], v155 offset:18432
	ds_read_b128 v[202:205], v155 offset:19456
	ds_read_b128 v[206:209], v155 offset:20480
	ds_read_b128 v[210:213], v155 offset:21504
	ds_read_b128 v[214:217], v155 offset:22528
	ds_read_b128 v[218:221], v155 offset:23552
	global_load_lds_dwordx4 v132, s[46:47]
	s_add_i32 m0, s63, 0x2000
	s_add_u32 s64, s46, 0x80000
	s_addc_u32 s65, s47, 0
	s_add_i32 s63, s52, s28
	global_load_lds_dwordx4 v128, s[46:47]
	s_mov_b32 m0, s63
	s_nop 0
	global_load_lds_dwordx4 v132, s[64:65]
	s_add_i32 m0, s63, 0x2000
	s_nop 0
	global_load_lds_dwordx4 v128, s[64:65]
	s_mov_b32 m0, s30
	s_nop 0
	global_load_lds_dwordx4 v134, s[48:49]
	s_mov_b32 m0, s31
	s_nop 0
	global_load_lds_dwordx4 v130, s[48:49]
	s_waitcnt vmcnt(8)
	s_waitcnt lgkmcnt(0)
	s_setprio 0
	s_barrier
	v_mfma_f32_16x16x32_bf16 v[60:63], v[144:147], v[190:193], v[60:63]
	v_mfma_f32_16x16x32_bf16 v[56:59], v[166:169], v[190:193], v[56:59]
	v_mfma_f32_16x16x32_bf16 v[44:47], v[144:147], v[198:201], v[44:47]
	v_mfma_f32_16x16x32_bf16 v[40:43], v[166:169], v[198:201], v[40:43]
	v_mfma_f32_16x16x32_bf16 v[28:31], v[144:147], v[206:209], v[28:31]
	v_mfma_f32_16x16x32_bf16 v[24:27], v[166:169], v[206:209], v[24:27]
	v_mfma_f32_16x16x32_bf16 v[12:15], v[144:147], v[214:217], v[12:15]
	v_mfma_f32_16x16x32_bf16 v[8:11], v[166:169], v[214:217], v[8:11]
	v_mfma_f32_16x16x32_bf16 v[60:63], v[156:159], v[194:197], v[60:63]
	v_mfma_f32_16x16x32_bf16 v[56:59], v[170:173], v[194:197], v[56:59]
	v_mfma_f32_16x16x32_bf16 v[44:47], v[156:159], v[202:205], v[44:47]
	v_mfma_f32_16x16x32_bf16 v[40:43], v[170:173], v[202:205], v[40:43]
	v_mfma_f32_16x16x32_bf16 v[28:31], v[156:159], v[210:213], v[28:31]
	v_mfma_f32_16x16x32_bf16 v[24:27], v[170:173], v[210:213], v[24:27]
	v_mfma_f32_16x16x32_bf16 v[12:15], v[156:159], v[218:221], v[12:15]
	v_mfma_f32_16x16x32_bf16 v[8:11], v[170:173], v[218:221], v[8:11]
	v_mfma_f32_16x16x32_bf16 v[52:55], v[174:177], v[190:193], v[52:55]
	v_mfma_f32_16x16x32_bf16 v[48:51], v[182:185], v[190:193], v[48:51]
	v_mfma_f32_16x16x32_bf16 v[36:39], v[174:177], v[198:201], v[36:39]
	v_mfma_f32_16x16x32_bf16 v[32:35], v[182:185], v[198:201], v[32:35]
	v_mfma_f32_16x16x32_bf16 v[20:23], v[174:177], v[206:209], v[20:23]
	v_mfma_f32_16x16x32_bf16 v[16:19], v[182:185], v[206:209], v[16:19]
	v_mfma_f32_16x16x32_bf16 v[4:7], v[174:177], v[214:217], v[4:7]
	v_mfma_f32_16x16x32_bf16 v[0:3], v[182:185], v[214:217], v[0:3]
	v_mfma_f32_16x16x32_bf16 v[52:55], v[178:181], v[194:197], v[52:55]
	v_mfma_f32_16x16x32_bf16 v[48:51], v[186:189], v[194:197], v[48:51]
	v_mfma_f32_16x16x32_bf16 v[36:39], v[178:181], v[202:205], v[36:39]
	v_mfma_f32_16x16x32_bf16 v[32:35], v[186:189], v[202:205], v[32:35]
	v_mfma_f32_16x16x32_bf16 v[20:23], v[178:181], v[210:213], v[20:23]
	v_mfma_f32_16x16x32_bf16 v[16:19], v[186:189], v[210:213], v[16:19]
	v_mfma_f32_16x16x32_bf16 v[4:7], v[178:181], v[218:221], v[4:7]
	v_mfma_f32_16x16x32_bf16 v[0:3], v[186:189], v[218:221], v[0:3]
	s_barrier
	s_setprio 1
	s_add_i32 s63, 0, 0x18000
	s_add_i32 s64, 0, 0x1c000
	ds_read_b128 v[144:147], v241
	ds_read_b128 v[156:159], v241 offset:1024
	ds_read_b128 v[166:169], v241 offset:2048
	ds_read_b128 v[170:173], v241 offset:3072
	ds_read_b128 v[174:177], v242
	ds_read_b128 v[178:181], v242 offset:1024
	ds_read_b128 v[182:185], v242 offset:2048
	ds_read_b128 v[186:189], v242 offset:3072
	s_add_u32 s48, s48, 0x80000
	s_addc_u32 s49, s49, 0
	s_mov_b32 m0, s33
	ds_read_b128 v[190:193], v155 offset:32768
	ds_read_b128 v[194:197], v155 offset:33792
	ds_read_b128 v[198:201], v155 offset:34816
	ds_read_b128 v[202:205], v155 offset:35840
	ds_read_b128 v[206:209], v155 offset:36864
	ds_read_b128 v[210:213], v155 offset:37888
	ds_read_b128 v[214:217], v155 offset:38912
	ds_read_b128 v[218:221], v155 offset:39936
	global_load_lds_dwordx4 v134, s[48:49]
	s_mov_b32 m0, s34
	s_nop 0
	global_load_lds_dwordx4 v130, s[48:49]
	s_waitcnt vmcnt(8)
	s_waitcnt lgkmcnt(0)
	s_setprio 0
	s_barrier
; #define PG8_STAGE(bufoff, gbase, voff) do { _Pragma("unroll") for (int _i = 0; _i < 2; ++_i) \
;         __builtin_amdgcn_global_load_lds((const unsigned*)((const char*)(gbase) + (voff)[_i]), (PG8_LAS unsigned*)(lds + (bufoff) + ldsw + _i * 8192), 16, 0, 0); } while (0)
; #define PG8_LDA(dst, b, h) do { _Pragma("unroll") for (int m = 0; m < 4; ++m) _Pragma("unroll") for (int k = 0; k < 2; ++k) dst[m][k] = *(const PG8_LAS bf16x8*)(lds + PG8_SA(b, h) + aoff + m * 2048 + k * 1024); } while (0)
; #define PG8_MMA(ai, bj, At, Bt) do { __builtin_amdgcn_s_setprio(1); _Pragma("unroll") for (int m = 0; m < 4; ++m) _Pragma("unroll") for (int n = 0; n < 2; ++n) _Pragma("unroll") for (int k = 0; k < 2; ++k) \
;         acc[ai][bj][m][n] = __builtin_amdgcn_mfma_f32_16x16x32_bf16(Bt[n][k], At[m][k], acc[ai][bj][m][n], 0, 0, 0); __builtin_amdgcn_s_setprio(0); } while (0)
; #define PG8_WAIT_V(n) asm volatile("s_waitcnt vmcnt(" #n ")" ::: "memory")
; #define PG8_WAIT_L(n) asm volatile("s_waitcnt lgkmcnt(" #n ")" ::: "memory")
; #define PG8_BAR __builtin_amdgcn_s_barrier()
; #define PG8_SCHED __builtin_amdgcn_sched_barrier(0)
; template <class Epi, class Sched, bool ALIGN_EPI = false, bool SP2 = false>
; __device__ __forceinline__ void gemm_phase(PG8_LAS unsigned char* lds, const Gemm g, const Sched& S, const Epi& E) {
;     ...
;             PG8_WAIT_V(8); PG8_WAIT_L(0); PG8_BAR; PG8_MMA(0, 0, At, B0); PG8_MMA(0, 1, At, B1); PG8_BAR; PG8_SCHED;
;             PG8_LDA(At, 1, 1); PG8_STAGE(PG8_SB(1, 0), b3, voffB); PG8_STAGE(PG8_SB(1, 1), b3 + hstepB, voffB); PG8_STAGE(PG8_SA(1, 0), a3, voffA);
;             PG8_WAIT_V(8); PG8_WAIT_L(0); PG8_BAR; PG8_MMA(1, 0, At, B0); PG8_MMA(1, 1, At, B1); PG8_BAR; PG8_SCHED;
;     ...
;         if constexpr (ALIGN_EPI) { if (wr == 0) PG8_BAR; }
	v_mfma_f32_16x16x32_bf16 v[124:127], v[144:147], v[190:193], v[124:127]
	v_mfma_f32_16x16x32_bf16 v[120:123], v[166:169], v[190:193], v[120:123]
	v_mfma_f32_16x16x32_bf16 v[108:111], v[144:147], v[198:201], v[108:111]
	v_mfma_f32_16x16x32_bf16 v[104:107], v[166:169], v[198:201], v[104:107]
	v_mfma_f32_16x16x32_bf16 v[92:95], v[144:147], v[206:209], v[92:95]
	v_mfma_f32_16x16x32_bf16 v[88:91], v[166:169], v[206:209], v[88:91]
	v_mfma_f32_16x16x32_bf16 v[76:79], v[144:147], v[214:217], v[76:79]
	v_mfma_f32_16x16x32_bf16 v[72:75], v[166:169], v[214:217], v[72:75]
	v_mfma_f32_16x16x32_bf16 v[124:127], v[156:159], v[194:197], v[124:127]
	v_mfma_f32_16x16x32_bf16 v[120:123], v[170:173], v[194:197], v[120:123]
	v_mfma_f32_16x16x32_bf16 v[108:111], v[156:159], v[202:205], v[108:111]
	v_mfma_f32_16x16x32_bf16 v[104:107], v[170:173], v[202:205], v[104:107]
	v_mfma_f32_16x16x32_bf16 v[92:95], v[156:159], v[210:213], v[92:95]
	v_mfma_f32_16x16x32_bf16 v[88:91], v[170:173], v[210:213], v[88:91]
	v_mfma_f32_16x16x32_bf16 v[76:79], v[156:159], v[218:221], v[76:79]
	v_mfma_f32_16x16x32_bf16 v[72:75], v[170:173], v[218:221], v[72:75]
	v_mfma_f32_16x16x32_bf16 v[116:119], v[174:177], v[190:193], v[116:119]
	v_mfma_f32_16x16x32_bf16 v[112:115], v[182:185], v[190:193], v[112:115]
	v_mfma_f32_16x16x32_bf16 v[100:103], v[174:177], v[198:201], v[100:103]
	v_mfma_f32_16x16x32_bf16 v[96:99], v[182:185], v[198:201], v[96:99]
	v_mfma_f32_16x16x32_bf16 v[84:87], v[174:177], v[206:209], v[84:87]
	v_mfma_f32_16x16x32_bf16 v[80:83], v[182:185], v[206:209], v[80:83]
	v_mfma_f32_16x16x32_bf16 v[68:71], v[174:177], v[214:217], v[68:71]
	v_mfma_f32_16x16x32_bf16 v[64:67], v[182:185], v[214:217], v[64:67]
	v_mfma_f32_16x16x32_bf16 v[116:119], v[178:181], v[194:197], v[116:119]
	v_mfma_f32_16x16x32_bf16 v[112:115], v[186:189], v[194:197], v[112:115]
	v_mfma_f32_16x16x32_bf16 v[100:103], v[178:181], v[202:205], v[100:103]
	v_mfma_f32_16x16x32_bf16 v[96:99], v[186:189], v[202:205], v[96:99]
	v_mfma_f32_16x16x32_bf16 v[84:87], v[178:181], v[210:213], v[84:87]
	v_mfma_f32_16x16x32_bf16 v[80:83], v[186:189], v[210:213], v[80:83]
	v_mfma_f32_16x16x32_bf16 v[68:71], v[178:181], v[218:221], v[68:71]
	v_mfma_f32_16x16x32_bf16 v[64:67], v[186:189], v[218:221], v[64:67]
	s_barrier
	s_setprio 1
	s_add_i32 s48, s63, s28
	s_mov_b32 m0, s48
	ds_read_b128 v[190:193], v155 offset:49152
	ds_read_b128 v[194:197], v155 offset:50176
	ds_read_b128 v[198:201], v155 offset:51200
	ds_read_b128 v[202:205], v155 offset:52224
	ds_read_b128 v[206:209], v155 offset:53248
	ds_read_b128 v[210:213], v155 offset:54272
	ds_read_b128 v[214:217], v155 offset:55296
	ds_read_b128 v[218:221], v155 offset:56320
	global_load_lds_dwordx4 v132, s[98:99]
	s_add_i32 m0, s48, 0x2000
	s_add_u32 s46, s46, 0x80080
	s_addc_u32 s47, s47, 0
	s_add_i32 s48, s64, s28
	global_load_lds_dwordx4 v128, s[98:99]
	s_mov_b32 m0, s48
	s_nop 0
	global_load_lds_dwordx4 v132, s[46:47]
	s_add_i32 m0, s48, 0x2000
	s_nop 0
	global_load_lds_dwordx4 v128, s[46:47]
	s_mov_b32 m0, s43
	s_nop 0
	global_load_lds_dwordx4 v134, s[100:101]
	s_mov_b32 m0, s50
	s_nop 0
	global_load_lds_dwordx4 v130, s[100:101]
	s_waitcnt vmcnt(8)
	s_waitcnt lgkmcnt(0)
	s_setprio 0
	s_barrier
	v_mfma_f32_16x16x32_bf16 v[60:63], v[144:147], v[190:193], v[60:63]
	v_mfma_f32_16x16x32_bf16 v[56:59], v[166:169], v[190:193], v[56:59]
	v_mfma_f32_16x16x32_bf16 v[44:47], v[144:147], v[198:201], v[44:47]
	v_mfma_f32_16x16x32_bf16 v[40:43], v[166:169], v[198:201], v[40:43]
	v_mfma_f32_16x16x32_bf16 v[28:31], v[144:147], v[206:209], v[28:31]
	v_mfma_f32_16x16x32_bf16 v[24:27], v[166:169], v[206:209], v[24:27]
	v_mfma_f32_16x16x32_bf16 v[12:15], v[144:147], v[214:217], v[12:15]
	v_mfma_f32_16x16x32_bf16 v[8:11], v[166:169], v[214:217], v[8:11]
	v_mfma_f32_16x16x32_bf16 v[60:63], v[156:159], v[194:197], v[60:63]
	v_mfma_f32_16x16x32_bf16 v[56:59], v[170:173], v[194:197], v[56:59]
	v_mfma_f32_16x16x32_bf16 v[44:47], v[156:159], v[202:205], v[44:47]
	v_mfma_f32_16x16x32_bf16 v[40:43], v[170:173], v[202:205], v[40:43]
	v_mfma_f32_16x16x32_bf16 v[28:31], v[156:159], v[210:213], v[28:31]
	v_mfma_f32_16x16x32_bf16 v[24:27], v[170:173], v[210:213], v[24:27]
	v_mfma_f32_16x16x32_bf16 v[12:15], v[156:159], v[218:221], v[12:15]
	v_mfma_f32_16x16x32_bf16 v[8:11], v[170:173], v[218:221], v[8:11]
	v_mfma_f32_16x16x32_bf16 v[52:55], v[174:177], v[190:193], v[52:55]
	v_mfma_f32_16x16x32_bf16 v[48:51], v[182:185], v[190:193], v[48:51]
	v_mfma_f32_16x16x32_bf16 v[36:39], v[174:177], v[198:201], v[36:39]
	v_mfma_f32_16x16x32_bf16 v[32:35], v[182:185], v[198:201], v[32:35]
	v_mfma_f32_16x16x32_bf16 v[20:23], v[174:177], v[206:209], v[20:23]
	v_mfma_f32_16x16x32_bf16 v[16:19], v[182:185], v[206:209], v[16:19]
	v_mfma_f32_16x16x32_bf16 v[4:7], v[174:177], v[214:217], v[4:7]
	v_mfma_f32_16x16x32_bf16 v[0:3], v[182:185], v[214:217], v[0:3]
	v_mfma_f32_16x16x32_bf16 v[52:55], v[178:181], v[194:197], v[52:55]
	v_mfma_f32_16x16x32_bf16 v[48:51], v[186:189], v[194:197], v[48:51]
	v_mfma_f32_16x16x32_bf16 v[36:39], v[178:181], v[202:205], v[36:39]
	v_mfma_f32_16x16x32_bf16 v[32:35], v[186:189], v[202:205], v[32:35]
	v_mfma_f32_16x16x32_bf16 v[20:23], v[178:181], v[210:213], v[20:23]
	v_mfma_f32_16x16x32_bf16 v[16:19], v[186:189], v[210:213], v[16:19]
	v_mfma_f32_16x16x32_bf16 v[4:7], v[178:181], v[218:221], v[4:7]
	v_mfma_f32_16x16x32_bf16 v[0:3], v[186:189], v[218:221], v[0:3]
	s_barrier
	s_setprio 1
	s_add_i32 s62, s62, 2
	s_add_u32 s44, s44, 0x100
	s_addc_u32 s45, s45, 0
	s_add_u32 s60, s60, 0x100
	s_addc_u32 s61, s61, 0
	s_cmp_gt_u32 s62, 29
	s_cbranch_scc0 .LBB0_1333
	s_and_b64 vcc, exec, s[14:15]
	s_cbranch_vccz .LBB0_1336
	s_barrier

; __global__ void __launch_bounds__(NTHR, 2) fwd_megakernel(Args args) {
	.amdhsa_kernel _Z14fwd_megakernel4Args
		.amdhsa_group_segment_fixed_size 0
		.amdhsa_private_segment_fixed_size 0
		.amdhsa_kernarg_size 464
		.amdhsa_user_sgpr_count 2
		.amdhsa_user_sgpr_dispatch_ptr 0
		.amdhsa_user_sgpr_queue_ptr 0
		.amdhsa_user_sgpr_kernarg_segment_ptr 1
		.amdhsa_user_sgpr_dispatch_id 0
		.amdhsa_user_sgpr_kernarg_preload_length 0
		.amdhsa_user_sgpr_kernarg_preload_offset 0
		.amdhsa_user_sgpr_private_segment_size 0
		.amdhsa_uses_dynamic_stack 0
		.amdhsa_enable_private_segment 0
		.amdhsa_system_sgpr_workgroup_id_x 1
		.amdhsa_system_sgpr_workgroup_id_y 0
		.amdhsa_system_sgpr_workgroup_id_z 0
		.amdhsa_system_sgpr_workgroup_info 0
		.amdhsa_system_vgpr_workitem_id 2
		.amdhsa_next_free_vgpr 244
		.amdhsa_next_free_sgpr 102
		.amdhsa_accum_offset 244
		.amdhsa_reserve_vcc 1
		.amdhsa_float_round_mode_32 0
		.amdhsa_float_round_mode_16_64 0
		.amdhsa_float_denorm_mode_32 3
		.amdhsa_float_denorm_mode_16_64 3
		.amdhsa_dx10_clamp 1
		.amdhsa_ieee_mode 1
		.amdhsa_fp16_overflow 0
		.amdhsa_tg_split 0
		.amdhsa_exception_fp_ieee_invalid_op 0
		.amdhsa_exception_fp_denorm_src 0
		.amdhsa_exception_fp_ieee_div_zero 0
		.amdhsa_exception_fp_ieee_overflow 0
		.amdhsa_exception_fp_ieee_underflow 0
		.amdhsa_exception_fp_ieee_inexact 0
		.amdhsa_exception_int_div_zero 0
	.end_amdhsa_kernel

; __global__ void __launch_bounds__(NTHR, 2) fwd_megakernel(Args args) {
amdhsa.kernels:
  - .agpr_count:     0
    .args:
      - .offset:         0
        .size:           208
        .value_kind:     by_value
      - .offset:         208
        .size:           4
        .value_kind:     hidden_block_count_x
      - .offset:         212
        .size:           4
        .value_kind:     hidden_block_count_y
      - .offset:         216
        .size:           4
        .value_kind:     hidden_block_count_z
      - .offset:         220
        .size:           2
        .value_kind:     hidden_group_size_x
      - .offset:         222
        .size:           2
        .value_kind:     hidden_group_size_y
      - .offset:         224
        .size:           2
        .value_kind:     hidden_group_size_z
      - .offset:         226
        .size:           2
        .value_kind:     hidden_remainder_x
      - .offset:         228
        .size:           2
        .value_kind:     hidden_remainder_y
      - .offset:         230
        .size:           2
        .value_kind:     hidden_remainder_z
      - .offset:         248
        .size:           8
        .value_kind:     hidden_global_offset_x
      - .offset:         256
        .size:           8
        .value_kind:     hidden_global_offset_y
      - .offset:         264
        .size:           8
        .value_kind:     hidden_global_offset_z
      - .offset:         272
        .size:           2
        .value_kind:     hidden_grid_dims
      - .offset:         296
        .size:           8
        .value_kind:     hidden_multigrid_sync_arg
      - .offset:         328
        .size:           4
        .value_kind:     hidden_dynamic_lds_size
    .group_segment_fixed_size: 0
    .kernarg_segment_align: 8
    .kernarg_segment_size: 464
    .language:       OpenCL C
    .language_version:
      - 2
      - 0
    .max_flat_workgroup_size: 512
    .name:           _Z14fwd_megakernel4Args
    .private_segment_fixed_size: 0
    .sgpr_count:     108
    .sgpr_spill_count: 42
    .symbol:         _Z14fwd_megakernel4Args.kd
    .uniform_work_group_size: 1
    .uses_dynamic_stack: false
    .vgpr_count:     244
    .vgpr_spill_count: 0
    .wavefront_size: 64
